# baseline (speedup 1.0000x reference)
; #define P8_STAGE(P,BASE,br,kt) do{const bfr* _ub=(BASE)+((long)(br)*K+(long)(kt)*BK); \
;     __builtin_amdgcn_global_load_lds((const unsigned*)(_ub+so0),(unsigned*)((char*)(P)+wid*1024),16,0,0); \
;     __builtin_amdgcn_global_load_lds((const unsigned*)(_ub+so1),(unsigned*)((char*)(P)+wid*1024+8192),16,0,0);}while(0)
; #define P8_LDA(dst,b,h) _Pragma("unroll") for(int m=0;m<4;++m) _Pragma("unroll") for(int k=0;k<2;++k) \
;     dst[m][k]=*reinterpret_cast<const bf16x8*>((char*)P8_SA(b,h)+lds_byte(wr*64+m*16+fr,k*32+fq*8))
; #define P8_LDB(dst,b,h) _Pragma("unroll") for(int n=0;n<2;++n) _Pragma("unroll") for(int k=0;k<2;++k) \
;     dst[n][k]=*reinterpret_cast<const bf16x8*>((char*)P8_SB(b,h)+lds_byte(wc*32+n*16+fr,k*32+fq*8))
; #define P8_MMA(ai,bj,At,Bt) do{__builtin_amdgcn_s_setprio(1); \
;     _Pragma("unroll") for(int m=0;m<4;++m) _Pragma("unroll") for(int n=0;n<2;++n) _Pragma("unroll") for(int k=0;k<2;++k) \
;       acc[ai][bj][m][n]=__builtin_amdgcn_mfma_f32_16x16x32_bf16(At[m][k],Bt[n][k],acc[ai][bj][m][n],0,0,0); \
;     __builtin_amdgcn_s_setprio(0);}while(0)
; #define P8_WAIT_V(n) asm volatile("s_waitcnt vmcnt(" #n ")":::"memory")
; #define P8_WAIT_L(n) asm volatile("s_waitcnt lgkmcnt(" #n ")":::"memory")
; #define P8_BAR __builtin_amdgcn_s_barrier()
; #define P8_SCHED __builtin_amdgcn_sched_barrier(0)
; template <class EPI>
; DEVI void gemm8_tile(const bfr* __restrict__ A, const bfr* __restrict__ Bt, int K, int brow, int bcol, int nbrow, int nbcol, char* shmc, EPI epi) {
;     ...
;     P8_LDB(B0,0,0); P8_SCHED; P8_LDA(At,0,0); P8_STAGE(P8_SA(1,1),A,brow+128,t+1);
;     P8_WAIT_L(8); P8_BAR; P8_WAIT_L(0); P8_MMA(0,0,At,B0); P8_BAR; P8_SCHED;
;     P8_LDB(B1,0,1); P8_STAGE(P8_SB(0,0),Bt,bcol,t+2);
;     P8_BAR; P8_WAIT_L(0); P8_MMA(0,1,At,B1); P8_BAR;
;     P8_LDA(At,0,1); P8_STAGE(P8_SA(0,0),A,brow,t+2);
;     P8_BAR; P8_WAIT_L(0); P8_MMA(1,0,At,B0); P8_BAR; P8_SCHED;
;     P8_STAGE(P8_SB(0,1),Bt,bcol+128,t+2);
;     P8_WAIT_V(6); P8_BAR; P8_MMA(1,1,At,B1); P8_BAR;
.LBB0_85:
	ds_read_b128 v[174:177], v157
	ds_read_b128 v[178:181], v157 offset:1024
	ds_read_b128 v[182:185], v157 offset:2048
	ds_read_b128 v[186:189], v157 offset:3072
	v_add_u32_e32 v171, s54, v140
	s_add_i32 m0, s100, 0xc000
	ds_read_b128 v[160:163], v147
	ds_read_b128 v[190:193], v147 offset:1024
	ds_read_b128 v[196:199], v146
	ds_read_b128 v[200:203], v146 offset:1024
	ds_read_b128 v[204:207], v145
	ds_read_b128 v[208:211], v145 offset:1024
	ds_read_b128 v[212:215], v144
	ds_read_b128 v[216:219], v144 offset:1024
	global_load_lds_dwordx4 v171, s[86:87]
	v_add_u32_e32 v172, s54, v138
	s_add_i32 m0, s100, 0xe000
	s_nop 0
	global_load_lds_dwordx4 v172, s[86:87]
	s_waitcnt lgkmcnt(8)
	s_barrier
	s_waitcnt lgkmcnt(0)
	v_mfma_f32_16x16x32_bf16 v[124:127], v[160:163], v[174:177], v[124:127]
	v_mfma_f32_16x16x32_bf16 v[120:123], v[160:163], v[182:185], v[120:123]
	v_mfma_f32_16x16x32_bf16 v[116:119], v[196:199], v[174:177], v[116:119]
	v_mfma_f32_16x16x32_bf16 v[112:115], v[196:199], v[182:185], v[112:115]
	v_mfma_f32_16x16x32_bf16 v[108:111], v[204:207], v[174:177], v[108:111]
	v_mfma_f32_16x16x32_bf16 v[104:107], v[204:207], v[182:185], v[104:107]
	v_mfma_f32_16x16x32_bf16 v[100:103], v[212:215], v[174:177], v[100:103]
	v_mfma_f32_16x16x32_bf16 v[96:99], v[212:215], v[182:185], v[96:99]
	v_mfma_f32_16x16x32_bf16 v[124:127], v[190:193], v[178:181], v[124:127]
	v_mfma_f32_16x16x32_bf16 v[120:123], v[190:193], v[186:189], v[120:123]
	v_mfma_f32_16x16x32_bf16 v[116:119], v[200:203], v[178:181], v[116:119]
	v_mfma_f32_16x16x32_bf16 v[112:115], v[200:203], v[186:189], v[112:115]
	v_mfma_f32_16x16x32_bf16 v[108:111], v[208:211], v[178:181], v[108:111]
	v_mfma_f32_16x16x32_bf16 v[104:107], v[208:211], v[186:189], v[104:107]
	v_mfma_f32_16x16x32_bf16 v[100:103], v[216:219], v[178:181], v[100:103]
	v_mfma_f32_16x16x32_bf16 v[96:99], v[216:219], v[186:189], v[96:99]
	s_barrier
	v_add_u32_e32 v158, s66, v136
	s_add_i32 m0, s100, 0x10000
	ds_read_b128 v[220:223], v155
	ds_read_b128 v[224:227], v155 offset:1024
	ds_read_b128 v[228:231], v155 offset:2048
	ds_read_b128 v[232:235], v155 offset:3072
	global_load_lds_dwordx4 v158, s[86:87]
	v_add_u32_e32 v159, s66, v134
	s_add_i32 m0, s100, 0x12000
	s_nop 0
	global_load_lds_dwordx4 v159, s[86:87]
	s_barrier
	s_waitcnt lgkmcnt(0)
	v_mfma_f32_16x16x32_bf16 v[92:95], v[160:163], v[220:223], v[92:95]
	v_mfma_f32_16x16x32_bf16 v[88:91], v[160:163], v[228:231], v[88:91]
	v_mfma_f32_16x16x32_bf16 v[84:87], v[196:199], v[220:223], v[84:87]
	v_mfma_f32_16x16x32_bf16 v[80:83], v[196:199], v[228:231], v[80:83]
	v_mfma_f32_16x16x32_bf16 v[76:79], v[204:207], v[220:223], v[76:79]
	v_mfma_f32_16x16x32_bf16 v[72:75], v[204:207], v[228:231], v[72:75]
	v_mfma_f32_16x16x32_bf16 v[68:71], v[212:215], v[220:223], v[68:71]
	v_mfma_f32_16x16x32_bf16 v[64:67], v[212:215], v[228:231], v[64:67]
	v_mfma_f32_16x16x32_bf16 v[92:95], v[190:193], v[224:227], v[92:95]
	v_mfma_f32_16x16x32_bf16 v[88:91], v[190:193], v[232:235], v[88:91]
	v_mfma_f32_16x16x32_bf16 v[84:87], v[200:203], v[224:227], v[84:87]
	v_mfma_f32_16x16x32_bf16 v[80:83], v[200:203], v[232:235], v[80:83]
	v_mfma_f32_16x16x32_bf16 v[76:79], v[208:211], v[224:227], v[76:79]
	v_mfma_f32_16x16x32_bf16 v[72:75], v[208:211], v[232:235], v[72:75]
	v_mfma_f32_16x16x32_bf16 v[68:71], v[216:219], v[224:227], v[68:71]
	v_mfma_f32_16x16x32_bf16 v[64:67], v[216:219], v[232:235], v[64:67]
	v_add_u32_e32 v170, s60, v140
	s_mov_b32 m0, s100
	s_barrier
	ds_read_b128 v[190:193], v147 offset:16384
	ds_read_b128 v[196:199], v147 offset:17408
	ds_read_b128 v[200:203], v146 offset:16384
	ds_read_b128 v[204:207], v146 offset:17408
	ds_read_b128 v[208:211], v145 offset:16384
	ds_read_b128 v[212:215], v145 offset:17408
	ds_read_b128 v[216:219], v144 offset:16384
	ds_read_b128 v[236:239], v144 offset:17408
	global_load_lds_dwordx4 v170, s[86:87]
	v_add_u32_e32 v248, s60, v138
	s_add_i32 m0, s100, 0x2000
	s_nop 0
	global_load_lds_dwordx4 v248, s[86:87]
	s_barrier
	s_waitcnt lgkmcnt(0)
	v_mfma_f32_16x16x32_bf16 v[60:63], v[190:193], v[174:177], v[60:63]
	v_mfma_f32_16x16x32_bf16 v[56:59], v[190:193], v[182:185], v[56:59]
	v_mfma_f32_16x16x32_bf16 v[52:55], v[200:203], v[174:177], v[52:55]
	v_mfma_f32_16x16x32_bf16 v[48:51], v[200:203], v[182:185], v[48:51]
	v_mfma_f32_16x16x32_bf16 v[44:47], v[208:211], v[174:177], v[44:47]
	v_mfma_f32_16x16x32_bf16 v[40:43], v[208:211], v[182:185], v[40:43]
	v_mfma_f32_16x16x32_bf16 v[36:39], v[216:219], v[174:177], v[36:39]
	v_mfma_f32_16x16x32_bf16 v[32:35], v[216:219], v[182:185], v[32:35]
	v_mfma_f32_16x16x32_bf16 v[60:63], v[196:199], v[178:181], v[60:63]
	v_mfma_f32_16x16x32_bf16 v[56:59], v[196:199], v[186:189], v[56:59]
	v_mfma_f32_16x16x32_bf16 v[52:55], v[204:207], v[178:181], v[52:55]
	v_mfma_f32_16x16x32_bf16 v[48:51], v[204:207], v[186:189], v[48:51]
	v_mfma_f32_16x16x32_bf16 v[44:47], v[212:215], v[178:181], v[44:47]
	v_mfma_f32_16x16x32_bf16 v[40:43], v[212:215], v[186:189], v[40:43]
	v_mfma_f32_16x16x32_bf16 v[36:39], v[236:239], v[178:181], v[36:39]
	v_mfma_f32_16x16x32_bf16 v[32:35], v[236:239], v[186:189], v[32:35]
	s_barrier
	v_add_u32_e32 v240, s70, v136
	s_add_i32 m0, s100, 0x14000
	v_add_u32_e32 v174, s70, v134
	global_load_lds_dwordx4 v240, s[86:87]
	s_nop 0
	s_add_i32 m0, s100, 0x16000
	s_nop 0
	global_load_lds_dwordx4 v174, s[86:87]
	s_waitcnt vmcnt(6)
	s_barrier
; #define P8_STAGE(P,BASE,br,kt) do{const bfr* _ub=(BASE)+((long)(br)*K+(long)(kt)*BK); \
;     __builtin_amdgcn_global_load_lds((const unsigned*)(_ub+so0),(unsigned*)((char*)(P)+wid*1024),16,0,0); \
;     __builtin_amdgcn_global_load_lds((const unsigned*)(_ub+so1),(unsigned*)((char*)(P)+wid*1024+8192),16,0,0);}while(0)
; #define P8_LDA(dst,b,h) _Pragma("unroll") for(int m=0;m<4;++m) _Pragma("unroll") for(int k=0;k<2;++k) \
;     dst[m][k]=*reinterpret_cast<const bf16x8*>((char*)P8_SA(b,h)+lds_byte(wr*64+m*16+fr,k*32+fq*8))
; #define P8_LDB(dst,b,h) _Pragma("unroll") for(int n=0;n<2;++n) _Pragma("unroll") for(int k=0;k<2;++k) \
;     dst[n][k]=*reinterpret_cast<const bf16x8*>((char*)P8_SB(b,h)+lds_byte(wc*32+n*16+fr,k*32+fq*8))
; #define P8_MMA(ai,bj,At,Bt) do{__builtin_amdgcn_s_setprio(1); \
;     _Pragma("unroll") for(int m=0;m<4;++m) _Pragma("unroll") for(int n=0;n<2;++n) _Pragma("unroll") for(int k=0;k<2;++k) \
;       acc[ai][bj][m][n]=__builtin_amdgcn_mfma_f32_16x16x32_bf16(At[m][k],Bt[n][k],acc[ai][bj][m][n],0,0,0); \
;     __builtin_amdgcn_s_setprio(0);}while(0)
; #define P8_WAIT_V(n) asm volatile("s_waitcnt vmcnt(" #n ")":::"memory")
; #define P8_WAIT_L(n) asm volatile("s_waitcnt lgkmcnt(" #n ")":::"memory")
; #define P8_BAR __builtin_amdgcn_s_barrier()
; #define P8_SCHED __builtin_amdgcn_sched_barrier(0)
; template <class EPI>
; DEVI void gemm8_tile(const bfr* __restrict__ A, const bfr* __restrict__ Bt, int K, int brow, int bcol, int nbrow, int nbcol, char* shmc, EPI epi) {
;     ...
;     P8_WAIT_V(6); P8_BAR; P8_MMA(1,1,At,B1); P8_BAR;
;     P8_LDB(B0,1,0); P8_SCHED; P8_LDA(At,1,0); P8_STAGE(P8_SA(0,1),A,brow+128,t+2);
;     P8_WAIT_L(8); P8_BAR; P8_WAIT_L(0); P8_MMA(0,0,At,B0); P8_BAR; P8_SCHED;
;     P8_LDB(B1,1,1); P8_STAGE(P8_SB(1,0),Bt,bcol,t+3);
;     P8_BAR; P8_WAIT_L(0); P8_MMA(0,1,At,B1); P8_BAR;
;     P8_LDA(At,1,1); P8_STAGE(P8_SA(1,0),A,brow,t+3);
;     P8_BAR; P8_WAIT_L(0); P8_MMA(1,0,At,B0); P8_BAR; P8_SCHED;
	v_mfma_f32_16x16x32_bf16 v[28:31], v[190:193], v[220:223], v[28:31]
	v_mfma_f32_16x16x32_bf16 v[24:27], v[190:193], v[228:231], v[24:27]
	v_mfma_f32_16x16x32_bf16 v[20:23], v[200:203], v[220:223], v[20:23]
	v_mfma_f32_16x16x32_bf16 v[16:19], v[200:203], v[228:231], v[16:19]
	v_mfma_f32_16x16x32_bf16 v[12:15], v[208:211], v[220:223], v[12:15]
	v_mfma_f32_16x16x32_bf16 v[8:11], v[208:211], v[228:231], v[8:11]
	v_mfma_f32_16x16x32_bf16 v[4:7], v[216:219], v[220:223], v[4:7]
	v_mfma_f32_16x16x32_bf16 v[0:3], v[216:219], v[228:231], v[0:3]
	v_mfma_f32_16x16x32_bf16 v[28:31], v[196:199], v[224:227], v[28:31]
	v_mfma_f32_16x16x32_bf16 v[24:27], v[196:199], v[232:235], v[24:27]
	v_mfma_f32_16x16x32_bf16 v[20:23], v[204:207], v[224:227], v[20:23]
	v_mfma_f32_16x16x32_bf16 v[16:19], v[204:207], v[232:235], v[16:19]
	v_mfma_f32_16x16x32_bf16 v[12:15], v[212:215], v[224:227], v[12:15]
	v_mfma_f32_16x16x32_bf16 v[8:11], v[212:215], v[232:235], v[8:11]
	v_mfma_f32_16x16x32_bf16 v[4:7], v[236:239], v[224:227], v[4:7]
	v_mfma_f32_16x16x32_bf16 v[0:3], v[236:239], v[232:235], v[0:3]
	s_barrier
	ds_read_b128 v[174:177], v149
	ds_read_b128 v[178:181], v149 offset:1024
	ds_read_b128 v[182:185], v149 offset:2048
	ds_read_b128 v[186:189], v149 offset:3072
	s_add_i32 m0, s100, 0x3f80
	ds_read_b128 v[190:193], v147 offset:32768
	ds_read_b128 v[196:199], v147 offset:33792
	ds_read_b128 v[200:203], v146 offset:32768
	ds_read_b128 v[204:207], v146 offset:33792
	ds_read_b128 v[208:211], v145 offset:32768
	ds_read_b128 v[212:215], v145 offset:33792
	ds_read_b128 v[216:219], v144 offset:32768
	ds_read_b128 v[220:223], v144 offset:33792
	global_load_lds_dwordx4 v171, s[86:87] offset:128
	s_add_i32 m0, s100, 0x5f80
	s_nop 0
	global_load_lds_dwordx4 v172, s[86:87] offset:128
	s_waitcnt lgkmcnt(8)
	s_barrier
	s_waitcnt lgkmcnt(0)
	v_mfma_f32_16x16x32_bf16 v[124:127], v[190:193], v[174:177], v[124:127]
	v_mfma_f32_16x16x32_bf16 v[120:123], v[190:193], v[182:185], v[120:123]
	v_mfma_f32_16x16x32_bf16 v[116:119], v[200:203], v[174:177], v[116:119]
	v_mfma_f32_16x16x32_bf16 v[112:115], v[200:203], v[182:185], v[112:115]
	v_mfma_f32_16x16x32_bf16 v[108:111], v[208:211], v[174:177], v[108:111]
	v_mfma_f32_16x16x32_bf16 v[104:107], v[208:211], v[182:185], v[104:107]
	v_mfma_f32_16x16x32_bf16 v[100:103], v[216:219], v[174:177], v[100:103]
	v_mfma_f32_16x16x32_bf16 v[96:99], v[216:219], v[182:185], v[96:99]
	v_mfma_f32_16x16x32_bf16 v[124:127], v[196:199], v[178:181], v[124:127]
	v_mfma_f32_16x16x32_bf16 v[120:123], v[196:199], v[186:189], v[120:123]
	v_mfma_f32_16x16x32_bf16 v[116:119], v[204:207], v[178:181], v[116:119]
	v_mfma_f32_16x16x32_bf16 v[112:115], v[204:207], v[186:189], v[112:115]
	v_mfma_f32_16x16x32_bf16 v[108:111], v[212:215], v[178:181], v[108:111]
	v_mfma_f32_16x16x32_bf16 v[104:107], v[212:215], v[186:189], v[104:107]
	v_mfma_f32_16x16x32_bf16 v[100:103], v[220:223], v[178:181], v[100:103]
	v_mfma_f32_16x16x32_bf16 v[96:99], v[220:223], v[186:189], v[96:99]
	s_barrier
	s_add_i32 m0, s100, 0x17f80
	ds_read_b128 v[224:227], v148
	ds_read_b128 v[228:231], v148 offset:1024
	ds_read_b128 v[232:235], v148 offset:2048
	ds_read_b128 v[236:239], v148 offset:3072
	global_load_lds_dwordx4 v158, s[86:87] offset:128
	s_add_i32 m0, s100, 0x19f80
	s_nop 0
	global_load_lds_dwordx4 v159, s[86:87] offset:128
	s_barrier
	s_waitcnt lgkmcnt(0)
	v_mfma_f32_16x16x32_bf16 v[92:95], v[190:193], v[224:227], v[92:95]
	v_mfma_f32_16x16x32_bf16 v[88:91], v[190:193], v[232:235], v[88:91]
	v_mfma_f32_16x16x32_bf16 v[84:87], v[200:203], v[224:227], v[84:87]
	v_mfma_f32_16x16x32_bf16 v[80:83], v[200:203], v[232:235], v[80:83]
	v_mfma_f32_16x16x32_bf16 v[76:79], v[208:211], v[224:227], v[76:79]
	v_mfma_f32_16x16x32_bf16 v[72:75], v[208:211], v[232:235], v[72:75]
	v_mfma_f32_16x16x32_bf16 v[68:71], v[216:219], v[224:227], v[68:71]
	v_mfma_f32_16x16x32_bf16 v[64:67], v[216:219], v[232:235], v[64:67]
	v_mfma_f32_16x16x32_bf16 v[92:95], v[196:199], v[228:231], v[92:95]
	v_mfma_f32_16x16x32_bf16 v[88:91], v[196:199], v[236:239], v[88:91]
	v_mfma_f32_16x16x32_bf16 v[84:87], v[204:207], v[228:231], v[84:87]
	v_mfma_f32_16x16x32_bf16 v[80:83], v[204:207], v[236:239], v[80:83]
	v_mfma_f32_16x16x32_bf16 v[76:79], v[212:215], v[228:231], v[76:79]
	v_mfma_f32_16x16x32_bf16 v[72:75], v[212:215], v[236:239], v[72:75]
	v_mfma_f32_16x16x32_bf16 v[68:71], v[220:223], v[228:231], v[68:71]
	v_mfma_f32_16x16x32_bf16 v[64:67], v[220:223], v[236:239], v[64:67]
	s_add_i32 m0, s100, 0x7f80
	s_barrier
	ds_read_b128 v[190:193], v147 offset:49152
	ds_read_b128 v[196:199], v147 offset:50176
	ds_read_b128 v[200:203], v146 offset:49152
	ds_read_b128 v[204:207], v146 offset:50176
	ds_read_b128 v[208:211], v145 offset:49152
	ds_read_b128 v[212:215], v145 offset:50176
	ds_read_b128 v[216:219], v144 offset:49152
	ds_read_b128 v[220:223], v144 offset:50176
	global_load_lds_dwordx4 v170, s[86:87] offset:128
	s_add_i32 m0, s100, 0x9f80
	s_nop 0
	global_load_lds_dwordx4 v248, s[86:87] offset:128
	s_barrier
	s_waitcnt lgkmcnt(0)
	v_mfma_f32_16x16x32_bf16 v[60:63], v[190:193], v[174:177], v[60:63]
	v_mfma_f32_16x16x32_bf16 v[56:59], v[190:193], v[182:185], v[56:59]
	v_mfma_f32_16x16x32_bf16 v[52:55], v[200:203], v[174:177], v[52:55]
	v_mfma_f32_16x16x32_bf16 v[48:51], v[200:203], v[182:185], v[48:51]
	v_mfma_f32_16x16x32_bf16 v[44:47], v[208:211], v[174:177], v[44:47]
	v_mfma_f32_16x16x32_bf16 v[40:43], v[208:211], v[182:185], v[40:43]
	v_mfma_f32_16x16x32_bf16 v[36:39], v[216:219], v[174:177], v[36:39]
	v_mfma_f32_16x16x32_bf16 v[32:35], v[216:219], v[182:185], v[32:35]
	v_mfma_f32_16x16x32_bf16 v[60:63], v[196:199], v[178:181], v[60:63]
	v_mfma_f32_16x16x32_bf16 v[56:59], v[196:199], v[186:189], v[56:59]
	v_mfma_f32_16x16x32_bf16 v[52:55], v[204:207], v[178:181], v[52:55]
	v_mfma_f32_16x16x32_bf16 v[48:51], v[204:207], v[186:189], v[48:51]
	v_mfma_f32_16x16x32_bf16 v[44:47], v[212:215], v[178:181], v[44:47]
	v_mfma_f32_16x16x32_bf16 v[40:43], v[212:215], v[186:189], v[40:43]
	v_mfma_f32_16x16x32_bf16 v[36:39], v[220:223], v[178:181], v[36:39]
	v_mfma_f32_16x16x32_bf16 v[32:35], v[220:223], v[186:189], v[32:35]
	s_barrier
; #define P8_STAGE(P,BASE,br,kt) do{const bfr* _ub=(BASE)+((long)(br)*K+(long)(kt)*BK); \
;     __builtin_amdgcn_global_load_lds((const unsigned*)(_ub+so0),(unsigned*)((char*)(P)+wid*1024),16,0,0); \
;     __builtin_amdgcn_global_load_lds((const unsigned*)(_ub+so1),(unsigned*)((char*)(P)+wid*1024+8192),16,0,0);}while(0)
; #define P8_LDA(dst,b,h) _Pragma("unroll") for(int m=0;m<4;++m) _Pragma("unroll") for(int k=0;k<2;++k) \
;     dst[m][k]=*reinterpret_cast<const bf16x8*>((char*)P8_SA(b,h)+lds_byte(wr*64+m*16+fr,k*32+fq*8))
; #define P8_LDB(dst,b,h) _Pragma("unroll") for(int n=0;n<2;++n) _Pragma("unroll") for(int k=0;k<2;++k) \
;     dst[n][k]=*reinterpret_cast<const bf16x8*>((char*)P8_SB(b,h)+lds_byte(wc*32+n*16+fr,k*32+fq*8))
; #define P8_MMA(ai,bj,At,Bt) do{__builtin_amdgcn_s_setprio(1); \
;     _Pragma("unroll") for(int m=0;m<4;++m) _Pragma("unroll") for(int n=0;n<2;++n) _Pragma("unroll") for(int k=0;k<2;++k) \
;       acc[ai][bj][m][n]=__builtin_amdgcn_mfma_f32_16x16x32_bf16(At[m][k],Bt[n][k],acc[ai][bj][m][n],0,0,0); \
;     __builtin_amdgcn_s_setprio(0);}while(0)
; #define P8_WAIT_V(n) asm volatile("s_waitcnt vmcnt(" #n ")":::"memory")
; #define P8_WAIT_L(n) asm volatile("s_waitcnt lgkmcnt(" #n ")":::"memory")
; #define P8_BAR __builtin_amdgcn_s_barrier()
; template <class EPI>
; DEVI void gemm8_tile(const bfr* __restrict__ A, const bfr* __restrict__ Bt, int K, int brow, int bcol, int nbrow, int nbcol, char* shmc, EPI epi) {
;     ...
;     P8_STAGE(P8_SB(1,1),Bt,bcol+128,t+3);
;     P8_WAIT_V(6); P8_BAR; P8_MMA(1,1,At,B1); P8_BAR;
;   }
;   { P8_LDB(B0,0,0); P8_LDA(At,0,0); P8_STAGE(P8_SA(1,1),A,brow+128,nt-1);
;     P8_BAR; P8_WAIT_L(0); P8_MMA(0,0,At,B0); P8_BAR;
;     P8_LDB(B1,0,1); P8_BAR; P8_WAIT_L(0); P8_MMA(0,1,At,B1); P8_BAR;
	s_add_i32 m0, s100, 0x1bf80
	s_nop 0
	global_load_lds_dwordx4 v240, s[86:87] offset:128
	v_add_u32_e32 v174, s78, v134
	s_add_i32 m0, s100, 0x1e000
	s_nop 0
	global_load_lds_dwordx4 v174, s[86:87]
	s_waitcnt vmcnt(6)
	s_barrier
	v_mfma_f32_16x16x32_bf16 v[28:31], v[190:193], v[224:227], v[28:31]
	v_mfma_f32_16x16x32_bf16 v[24:27], v[190:193], v[232:235], v[24:27]
	v_mfma_f32_16x16x32_bf16 v[20:23], v[200:203], v[224:227], v[20:23]
	v_mfma_f32_16x16x32_bf16 v[16:19], v[200:203], v[232:235], v[16:19]
	v_mfma_f32_16x16x32_bf16 v[12:15], v[208:211], v[224:227], v[12:15]
	v_mfma_f32_16x16x32_bf16 v[8:11], v[208:211], v[232:235], v[8:11]
	v_mfma_f32_16x16x32_bf16 v[4:7], v[216:219], v[224:227], v[4:7]
	v_mfma_f32_16x16x32_bf16 v[0:3], v[216:219], v[232:235], v[0:3]
	v_mfma_f32_16x16x32_bf16 v[28:31], v[196:199], v[228:231], v[28:31]
	v_mfma_f32_16x16x32_bf16 v[24:27], v[196:199], v[236:239], v[24:27]
	v_mfma_f32_16x16x32_bf16 v[20:23], v[204:207], v[228:231], v[20:23]
	v_mfma_f32_16x16x32_bf16 v[16:19], v[204:207], v[236:239], v[16:19]
	v_mfma_f32_16x16x32_bf16 v[12:15], v[212:215], v[228:231], v[12:15]
	v_mfma_f32_16x16x32_bf16 v[8:11], v[212:215], v[236:239], v[8:11]
	v_mfma_f32_16x16x32_bf16 v[4:7], v[220:223], v[228:231], v[4:7]
	v_mfma_f32_16x16x32_bf16 v[0:3], v[220:223], v[236:239], v[0:3]
	s_add_i32 s0, s0, 2
	v_lshl_add_u64 v[134:135], v[134:135], 0, s[80:81]
	v_lshl_add_u64 v[136:137], v[136:137], 0, s[80:81]
	v_lshl_add_u64 v[138:139], v[138:139], 0, s[80:81]
	s_cmp_lt_u32 s0, 28
	v_lshl_add_u64 v[140:141], v[140:141], 0, s[80:81]
	s_barrier
	s_cbranch_scc1 .LBB0_85
	v_add_u32_e32 v171, 0xc000, v143
	v_add_u32_e32 v172, 0xe000, v143
	v_add_u32_e32 v158, 0x10000, v143
	v_add_u32_e32 v159, 0x12000, v143
	v_add_u32_e32 v160, 0x2000, v143
	v_add_u32_e32 v161, 0x14000, v143
	v_add_u32_e32 v162, 0x16000, v143
	v_add_u32_e32 v163, 0x4000, v143
	v_add_u32_e32 v170, 0x6000, v143
	s_or_b32 s0, s8, 0x80
	s_ashr_i32 s1, s0, 31
	s_lshl_b64 s[0:1], s[0:1], 12
	s_add_u32 s0, s28, s0
	s_addc_u32 s1, s29, s1
	ds_read_b128 v[134:137], v157
	ds_read_b128 v[138:141], v157 offset:1024
	ds_read_b128 v[150:153], v157 offset:2048
	ds_read_b128 v[174:177], v157 offset:3072
	ds_read_b128 v[178:181], v147
	ds_read_b128 v[182:185], v147 offset:1024
	ds_read_b128 v[186:189], v146
	ds_read_b128 v[190:193], v146 offset:1024
	ds_read_b128 v[196:199], v145
	ds_read_b128 v[200:203], v145 offset:1024
	ds_read_b128 v[204:207], v144
	ds_read_b128 v[208:211], v144 offset:1024
	v_lshl_add_u64 v[156:157], v[166:167], 1, s[0:1]
	s_mov_b64 s[54:55], 0xf80
	v_lshl_add_u64 v[156:157], v[156:157], 0, s[54:55]
	s_add_i32 m0, s100, 0xc000
	v_lshl_add_u64 v[132:133], v[132:133], 1, s[0:1]
	global_load_lds_dwordx4 v[156:157], off
	v_lshl_add_u64 v[132:133], v[132:133], 0, s[54:55]
	s_add_i32 m0, s100, 0xe000
	s_nop 0
	global_load_lds_dwordx4 v[132:133], off
	s_barrier
	s_waitcnt lgkmcnt(0)
	s_setprio 1
	s_waitcnt lgkmcnt(0)
	v_mfma_f32_16x16x32_bf16 v[124:127], v[178:181], v[134:137], v[124:127]
	v_mfma_f32_16x16x32_bf16 v[116:119], v[186:189], v[134:137], v[116:119]
	v_mfma_f32_16x16x32_bf16 v[112:115], v[186:189], v[150:153], v[112:115]
	v_mfma_f32_16x16x32_bf16 v[96:99], v[204:207], v[150:153], v[96:99]
	v_mfma_f32_16x16x32_bf16 v[124:127], v[182:185], v[138:141], v[124:127]
	v_mfma_f32_16x16x32_bf16 v[120:123], v[178:181], v[150:153], v[120:123]
	v_mfma_f32_16x16x32_bf16 v[116:119], v[190:193], v[138:141], v[116:119]
	v_mfma_f32_16x16x32_bf16 v[112:115], v[190:193], v[174:177], v[112:115]
	v_mfma_f32_16x16x32_bf16 v[108:111], v[196:199], v[134:137], v[108:111]
	v_mfma_f32_16x16x32_bf16 v[104:107], v[196:199], v[150:153], v[104:107]
	v_mfma_f32_16x16x32_bf16 v[100:103], v[204:207], v[134:137], v[100:103]
	v_mfma_f32_16x16x32_bf16 v[96:99], v[208:211], v[174:177], v[96:99]
	v_mfma_f32_16x16x32_bf16 v[212:215], v[182:185], v[174:177], v[120:123]
	v_mfma_f32_16x16x32_bf16 v[216:219], v[200:203], v[138:141], v[108:111]
	v_mfma_f32_16x16x32_bf16 v[220:223], v[200:203], v[174:177], v[104:107]
	v_mfma_f32_16x16x32_bf16 v[224:227], v[208:211], v[138:141], v[100:103]
	s_setprio 0
	s_barrier
	s_nop 0
	ds_read_b128 v[100:103], v155
	ds_read_b128 v[104:107], v155 offset:1024
	ds_read_b128 v[108:111], v155 offset:2048
	ds_read_b128 v[120:123], v155 offset:3072
	s_barrier
	s_waitcnt lgkmcnt(0)
	s_setprio 1
	s_waitcnt lgkmcnt(0)
	v_mfma_f32_16x16x32_bf16 v[92:95], v[178:181], v[100:103], v[92:95]
	v_mfma_f32_16x16x32_bf16 v[84:87], v[186:189], v[100:103], v[84:87]
	v_mfma_f32_16x16x32_bf16 v[80:83], v[186:189], v[108:111], v[80:83]
	v_mfma_f32_16x16x32_bf16 v[64:67], v[204:207], v[108:111], v[64:67]
	v_mfma_f32_16x16x32_bf16 v[92:95], v[182:185], v[104:107], v[92:95]
	v_mfma_f32_16x16x32_bf16 v[88:91], v[178:181], v[108:111], v[88:91]
	v_mfma_f32_16x16x32_bf16 v[84:87], v[190:193], v[104:107], v[84:87]
	v_mfma_f32_16x16x32_bf16 v[80:83], v[190:193], v[120:123], v[80:83]
	v_mfma_f32_16x16x32_bf16 v[76:79], v[196:199], v[100:103], v[76:79]
	v_mfma_f32_16x16x32_bf16 v[72:75], v[196:199], v[108:111], v[72:75]
	v_mfma_f32_16x16x32_bf16 v[68:71], v[204:207], v[100:103], v[68:71]
	v_mfma_f32_16x16x32_bf16 v[64:67], v[208:211], v[120:123], v[64:67]
	v_mfma_f32_16x16x32_bf16 v[154:157], v[182:185], v[120:123], v[88:91]
	v_mfma_f32_16x16x32_bf16 v[178:181], v[200:203], v[104:107], v[76:79]
	v_mfma_f32_16x16x32_bf16 v[182:185], v[200:203], v[120:123], v[72:75]
	v_mfma_f32_16x16x32_bf16 v[186:189], v[208:211], v[104:107], v[68:71]
	s_setprio 0
	s_barrier
; #define P8_LDA(dst,b,h) _Pragma("unroll") for(int m=0;m<4;++m) _Pragma("unroll") for(int k=0;k<2;++k) \
;     dst[m][k]=*reinterpret_cast<const bf16x8*>((char*)P8_SA(b,h)+lds_byte(wr*64+m*16+fr,k*32+fq*8))
; #define P8_LDB(dst,b,h) _Pragma("unroll") for(int n=0;n<2;++n) _Pragma("unroll") for(int k=0;k<2;++k) \
;     dst[n][k]=*reinterpret_cast<const bf16x8*>((char*)P8_SB(b,h)+lds_byte(wc*32+n*16+fr,k*32+fq*8))
; #define P8_MMA(ai,bj,At,Bt) do{__builtin_amdgcn_s_setprio(1); \
;     _Pragma("unroll") for(int m=0;m<4;++m) _Pragma("unroll") for(int n=0;n<2;++n) _Pragma("unroll") for(int k=0;k<2;++k) \
;       acc[ai][bj][m][n]=__builtin_amdgcn_mfma_f32_16x16x32_bf16(At[m][k],Bt[n][k],acc[ai][bj][m][n],0,0,0); \
;     __builtin_amdgcn_s_setprio(0);}while(0)
; #define P8_WAIT_V(n) asm volatile("s_waitcnt vmcnt(" #n ")":::"memory")
; #define P8_WAIT_L(n) asm volatile("s_waitcnt lgkmcnt(" #n ")":::"memory")
; #define P8_BAR __builtin_amdgcn_s_barrier()
; template <class EPI>
; DEVI void gemm8_tile(const bfr* __restrict__ A, const bfr* __restrict__ Bt, int K, int brow, int bcol, int nbrow, int nbcol, char* shmc, EPI epi) {
;     ...
;     P8_LDB(B1,0,1); P8_BAR; P8_WAIT_L(0); P8_MMA(0,1,At,B1); P8_BAR;
;     P8_LDA(At,0,1); P8_WAIT_V(4); P8_BAR; P8_WAIT_L(0); P8_MMA(1,0,At,B0); P8_MMA(1,1,At,B1); P8_BAR; }
;   { P8_LDB(B0,1,0); P8_LDA(At,1,0); P8_WAIT_V(2); P8_BAR; P8_WAIT_L(0); P8_MMA(0,0,At,B0); P8_BAR;
	s_nop 0
	ds_read_b128 v[68:71], v147 offset:16384
	ds_read_b128 v[72:75], v147 offset:17408
	ds_read_b128 v[76:79], v146 offset:16384
	ds_read_b128 v[88:91], v146 offset:17408
	ds_read_b128 v[190:193], v145 offset:16384
	ds_read_b128 v[196:199], v145 offset:17408
	ds_read_b128 v[200:203], v144 offset:16384
	ds_read_b128 v[204:207], v144 offset:17408
	s_waitcnt vmcnt(4)
	s_barrier
	s_waitcnt lgkmcnt(0)
	s_setprio 1
	s_waitcnt lgkmcnt(0)
	v_mfma_f32_16x16x32_bf16 v[60:63], v[68:71], v[134:137], v[60:63]
	v_mfma_f32_16x16x32_bf16 v[52:55], v[76:79], v[134:137], v[52:55]
	v_mfma_f32_16x16x32_bf16 v[48:51], v[76:79], v[150:153], v[48:51]
	v_mfma_f32_16x16x32_bf16 v[32:35], v[200:203], v[150:153], v[32:35]
	v_mfma_f32_16x16x32_bf16 v[60:63], v[72:75], v[138:141], v[60:63]
	v_mfma_f32_16x16x32_bf16 v[56:59], v[68:71], v[150:153], v[56:59]
	v_mfma_f32_16x16x32_bf16 v[52:55], v[88:91], v[138:141], v[52:55]
	v_mfma_f32_16x16x32_bf16 v[48:51], v[88:91], v[174:177], v[48:51]
	v_mfma_f32_16x16x32_bf16 v[44:47], v[190:193], v[134:137], v[44:47]
	v_mfma_f32_16x16x32_bf16 v[40:43], v[190:193], v[150:153], v[40:43]
	v_mfma_f32_16x16x32_bf16 v[36:39], v[200:203], v[134:137], v[36:39]
	v_mfma_f32_16x16x32_bf16 v[32:35], v[204:207], v[174:177], v[32:35]
	v_mfma_f32_16x16x32_bf16 v[208:211], v[72:75], v[174:177], v[56:59]
	v_mfma_f32_16x16x32_bf16 v[228:231], v[196:199], v[138:141], v[44:47]
	v_mfma_f32_16x16x32_bf16 v[232:235], v[196:199], v[174:177], v[40:43]
	v_mfma_f32_16x16x32_bf16 v[132:135], v[204:207], v[138:141], v[36:39]
	s_setprio 0
	s_setprio 1
	v_mfma_f32_16x16x32_bf16 v[28:31], v[68:71], v[100:103], v[28:31]
	v_mfma_f32_16x16x32_bf16 v[20:23], v[76:79], v[100:103], v[20:23]
	v_mfma_f32_16x16x32_bf16 v[16:19], v[76:79], v[108:111], v[16:19]
	v_mfma_f32_16x16x32_bf16 v[0:3], v[200:203], v[108:111], v[0:3]
	v_mfma_f32_16x16x32_bf16 v[28:31], v[72:75], v[104:107], v[28:31]
	v_mfma_f32_16x16x32_bf16 v[24:27], v[68:71], v[108:111], v[24:27]
	v_mfma_f32_16x16x32_bf16 v[20:23], v[88:91], v[104:107], v[20:23]
	v_mfma_f32_16x16x32_bf16 v[16:19], v[88:91], v[120:123], v[16:19]
	v_mfma_f32_16x16x32_bf16 v[12:15], v[190:193], v[100:103], v[12:15]
	v_mfma_f32_16x16x32_bf16 v[8:11], v[190:193], v[108:111], v[8:11]
	v_mfma_f32_16x16x32_bf16 v[4:7], v[200:203], v[100:103], v[4:7]
	v_mfma_f32_16x16x32_bf16 v[0:3], v[204:207], v[120:123], v[0:3]
	v_mfma_f32_16x16x32_bf16 v[136:139], v[72:75], v[120:123], v[24:27]
	v_mfma_f32_16x16x32_bf16 v[150:153], v[196:199], v[104:107], v[12:15]
	v_mfma_f32_16x16x32_bf16 v[172:175], v[196:199], v[120:123], v[8:11]
	v_mfma_f32_16x16x32_bf16 v[190:193], v[204:207], v[104:107], v[4:7]
	s_setprio 0
	s_barrier
	s_nop 0
	ds_read_b128 v[4:7], v149
	ds_read_b128 v[8:11], v149 offset:1024
	ds_read_b128 v[12:15], v149 offset:2048
	ds_read_b128 v[24:27], v149 offset:3072
	ds_read_b128 v[36:39], v147 offset:32768
	ds_read_b128 v[40:43], v147 offset:33792
	ds_read_b128 v[44:47], v146 offset:32768
	ds_read_b128 v[56:59], v146 offset:33792
	ds_read_b128 v[68:71], v145 offset:32768
	ds_read_b128 v[196:199], v145 offset:33792
	ds_read_b128 v[200:203], v144 offset:32768
	ds_read_b128 v[204:207], v144 offset:33792
	s_waitcnt vmcnt(2)
	s_barrier
	s_waitcnt lgkmcnt(0)
	s_setprio 1
	s_waitcnt lgkmcnt(0)
	v_mfma_f32_16x16x32_bf16 v[72:75], v[36:39], v[4:7], v[124:127]
	v_mfma_f32_16x16x32_bf16 v[120:123], v[40:43], v[8:11], v[72:75]
	v_mfma_f32_16x16x32_bf16 v[72:75], v[36:39], v[12:15], v[212:215]
	v_mfma_f32_16x16x32_bf16 v[104:107], v[40:43], v[24:27], v[72:75]
	v_mfma_f32_16x16x32_bf16 v[72:75], v[44:47], v[4:7], v[116:119]
	v_mfma_f32_16x16x32_bf16 v[124:127], v[56:59], v[8:11], v[72:75]
	v_mfma_f32_16x16x32_bf16 v[72:75], v[44:47], v[12:15], v[112:115]
	v_mfma_f32_16x16x32_bf16 v[108:111], v[56:59], v[24:27], v[72:75]
	v_mfma_f32_16x16x32_bf16 v[72:75], v[68:71], v[4:7], v[216:219]
	v_mfma_f32_16x16x32_bf16 v[112:115], v[196:199], v[8:11], v[72:75]
	v_mfma_f32_16x16x32_bf16 v[72:75], v[68:71], v[12:15], v[220:223]
	v_mfma_f32_16x16x32_bf16 v[100:103], v[196:199], v[24:27], v[72:75]
	v_mfma_f32_16x16x32_bf16 v[72:75], v[200:203], v[4:7], v[224:227]
	v_mfma_f32_16x16x32_bf16 v[116:119], v[204:207], v[8:11], v[72:75]
	v_mfma_f32_16x16x32_bf16 v[72:75], v[200:203], v[12:15], v[96:99]
	v_mfma_f32_16x16x32_bf16 v[96:99], v[204:207], v[24:27], v[72:75]
	s_setprio 0
	s_barrier
; #define P8_LDA(dst,b,h) _Pragma("unroll") for(int m=0;m<4;++m) _Pragma("unroll") for(int k=0;k<2;++k) \
;     dst[m][k]=*reinterpret_cast<const bf16x8*>((char*)P8_SA(b,h)+lds_byte(wr*64+m*16+fr,k*32+fq*8))
; #define P8_LDB(dst,b,h) _Pragma("unroll") for(int n=0;n<2;++n) _Pragma("unroll") for(int k=0;k<2;++k) \
;     dst[n][k]=*reinterpret_cast<const bf16x8*>((char*)P8_SB(b,h)+lds_byte(wc*32+n*16+fr,k*32+fq*8))
; #define P8_MMA(ai,bj,At,Bt) do{__builtin_amdgcn_s_setprio(1); \
;     _Pragma("unroll") for(int m=0;m<4;++m) _Pragma("unroll") for(int n=0;n<2;++n) _Pragma("unroll") for(int k=0;k<2;++k) \
;       acc[ai][bj][m][n]=__builtin_amdgcn_mfma_f32_16x16x32_bf16(At[m][k],Bt[n][k],acc[ai][bj][m][n],0,0,0); \
;     __builtin_amdgcn_s_setprio(0);}while(0)
; #define P8_WAIT_V(n) asm volatile("s_waitcnt vmcnt(" #n ")":::"memory")
; #define P8_WAIT_L(n) asm volatile("s_waitcnt lgkmcnt(" #n ")":::"memory")
; #define P8_BAR __builtin_amdgcn_s_barrier()
; template <class EPI>
; DEVI void gemm8_tile(const bfr* __restrict__ A, const bfr* __restrict__ Bt, int K, int brow, int bcol, int nbrow, int nbcol, char* shmc, EPI epi) {
;     ...
;     P8_LDB(B1,1,1); P8_WAIT_V(0); P8_BAR; P8_WAIT_L(0); P8_MMA(0,1,At,B1); P8_BAR;
;     P8_LDA(At,1,1); P8_BAR; P8_WAIT_L(0); P8_MMA(1,0,At,B0); P8_MMA(1,1,At,B1); P8_BAR; }
;   if(wr==0)P8_BAR;
	ds_read_b128 v[212:215], v148
	ds_read_b128 v[216:219], v148 offset:1024
	ds_read_b128 v[220:223], v148 offset:2048
	ds_read_b128 v[224:227], v148 offset:3072
	s_waitcnt vmcnt(0)
	s_barrier
	s_waitcnt lgkmcnt(0)
	s_setprio 1
	s_waitcnt lgkmcnt(0)
	v_mfma_f32_16x16x32_bf16 v[72:75], v[36:39], v[212:215], v[92:95]
	v_mfma_f32_16x16x32_bf16 v[36:39], v[36:39], v[220:223], v[154:157]
	v_mfma_f32_16x16x32_bf16 v[88:91], v[40:43], v[216:219], v[72:75]
	v_mfma_f32_16x16x32_bf16 v[72:75], v[40:43], v[224:227], v[36:39]
	v_mfma_f32_16x16x32_bf16 v[36:39], v[44:47], v[212:215], v[84:87]
	v_mfma_f32_16x16x32_bf16 v[92:95], v[56:59], v[216:219], v[36:39]
	v_mfma_f32_16x16x32_bf16 v[36:39], v[44:47], v[220:223], v[80:83]
	v_mfma_f32_16x16x32_bf16 v[76:79], v[56:59], v[224:227], v[36:39]
	v_mfma_f32_16x16x32_bf16 v[36:39], v[68:71], v[212:215], v[178:181]
	v_mfma_f32_16x16x32_bf16 v[80:83], v[196:199], v[216:219], v[36:39]
	v_mfma_f32_16x16x32_bf16 v[36:39], v[68:71], v[220:223], v[182:185]
	v_mfma_f32_16x16x32_bf16 v[68:71], v[196:199], v[224:227], v[36:39]
	v_mfma_f32_16x16x32_bf16 v[36:39], v[200:203], v[212:215], v[186:189]
	v_mfma_f32_16x16x32_bf16 v[84:87], v[204:207], v[216:219], v[36:39]
	v_mfma_f32_16x16x32_bf16 v[36:39], v[200:203], v[220:223], v[64:67]
	v_mfma_f32_16x16x32_bf16 v[64:67], v[204:207], v[224:227], v[36:39]
	s_setprio 0
	s_barrier
	ds_read_b128 v[154:157], v147 offset:49152
	ds_read_b128 v[176:179], v147 offset:50176
	ds_read_b128 v[180:183], v146 offset:49152
	ds_read_b128 v[146:149], v146 offset:50176
	ds_read_b128 v[184:187], v145 offset:49152
	ds_read_b128 v[196:199], v145 offset:50176
	ds_read_b128 v[200:203], v144 offset:49152
	ds_read_b128 v[204:207], v144 offset:50176
	s_barrier
	s_waitcnt lgkmcnt(0)
	s_setprio 1
	s_waitcnt lgkmcnt(0)
	v_mfma_f32_16x16x32_bf16 v[36:39], v[154:157], v[4:7], v[60:63]
	v_mfma_f32_16x16x32_bf16 v[56:59], v[176:179], v[8:11], v[36:39]
	v_mfma_f32_16x16x32_bf16 v[36:39], v[154:157], v[12:15], v[208:211]
	v_mfma_f32_16x16x32_bf16 v[40:43], v[176:179], v[24:27], v[36:39]
	v_mfma_f32_16x16x32_bf16 v[36:39], v[180:183], v[4:7], v[52:55]
	v_mfma_f32_16x16x32_bf16 v[60:63], v[146:149], v[8:11], v[36:39]
	v_mfma_f32_16x16x32_bf16 v[36:39], v[180:183], v[12:15], v[48:51]
	v_mfma_f32_16x16x32_bf16 v[44:47], v[146:149], v[24:27], v[36:39]
	v_mfma_f32_16x16x32_bf16 v[36:39], v[184:187], v[4:7], v[228:231]
	v_mfma_f32_16x16x32_bf16 v[4:7], v[200:203], v[4:7], v[132:135]
	v_mfma_f32_16x16x32_bf16 v[48:51], v[196:199], v[8:11], v[36:39]
	v_mfma_f32_16x16x32_bf16 v[36:39], v[184:187], v[12:15], v[232:235]
	v_mfma_f32_16x16x32_bf16 v[52:55], v[204:207], v[8:11], v[4:7]
	v_mfma_f32_16x16x32_bf16 v[4:7], v[200:203], v[12:15], v[32:35]
	v_mfma_f32_16x16x32_bf16 v[36:39], v[196:199], v[24:27], v[36:39]
	v_mfma_f32_16x16x32_bf16 v[32:35], v[204:207], v[24:27], v[4:7]
	s_setprio 0
	s_setprio 1
	v_mfma_f32_16x16x32_bf16 v[4:7], v[154:157], v[212:215], v[28:31]
	v_mfma_f32_16x16x32_bf16 v[24:27], v[176:179], v[216:219], v[4:7]
	v_mfma_f32_16x16x32_bf16 v[4:7], v[154:157], v[220:223], v[136:139]
	v_mfma_f32_16x16x32_bf16 v[8:11], v[176:179], v[224:227], v[4:7]
	v_mfma_f32_16x16x32_bf16 v[4:7], v[180:183], v[212:215], v[20:23]
	v_mfma_f32_16x16x32_bf16 v[28:31], v[146:149], v[216:219], v[4:7]
	v_mfma_f32_16x16x32_bf16 v[4:7], v[180:183], v[220:223], v[16:19]
	v_mfma_f32_16x16x32_bf16 v[12:15], v[146:149], v[224:227], v[4:7]
	v_mfma_f32_16x16x32_bf16 v[4:7], v[184:187], v[212:215], v[150:153]
	v_mfma_f32_16x16x32_bf16 v[16:19], v[196:199], v[216:219], v[4:7]
	v_mfma_f32_16x16x32_bf16 v[4:7], v[184:187], v[220:223], v[172:175]
	v_mfma_f32_16x16x32_bf16 v[20:23], v[200:203], v[212:215], v[190:193]
	v_mfma_f32_16x16x32_bf16 v[0:3], v[200:203], v[220:223], v[0:3]
	v_mfma_f32_16x16x32_bf16 v[4:7], v[196:199], v[224:227], v[4:7]
	v_mfma_f32_16x16x32_bf16 v[20:23], v[204:207], v[216:219], v[20:23]
	v_mfma_f32_16x16x32_bf16 v[0:3], v[204:207], v[224:227], v[0:3]
	s_setprio 0
	v_cmp_gt_u32_e32 vcc, s57, v142
	s_barrier
	s_and_saveexec_b64 s[0:1], vcc
	s_cbranch_execz .LBB0_88
	s_barrier

; #define P8_STAGE(P,BASE,br,kt) do{const bfr* _ub=(BASE)+((long)(br)*K+(long)(kt)*BK); \
;     __builtin_amdgcn_global_load_lds((const unsigned*)(_ub+so0),(unsigned*)((char*)(P)+wid*1024),16,0,0); \
;     __builtin_amdgcn_global_load_lds((const unsigned*)(_ub+so1),(unsigned*)((char*)(P)+wid*1024+8192),16,0,0);}while(0)
; #define P8_LDA(dst,b,h) _Pragma("unroll") for(int m=0;m<4;++m) _Pragma("unroll") for(int k=0;k<2;++k) \
;     dst[m][k]=*reinterpret_cast<const bf16x8*>((char*)P8_SA(b,h)+lds_byte(wr*64+m*16+fr,k*32+fq*8))
; #define P8_LDB(dst,b,h) _Pragma("unroll") for(int n=0;n<2;++n) _Pragma("unroll") for(int k=0;k<2;++k) \
;     dst[n][k]=*reinterpret_cast<const bf16x8*>((char*)P8_SB(b,h)+lds_byte(wc*32+n*16+fr,k*32+fq*8))
; #define P8_MMA(ai,bj,At,Bt) do{__builtin_amdgcn_s_setprio(1); \
;     _Pragma("unroll") for(int m=0;m<4;++m) _Pragma("unroll") for(int n=0;n<2;++n) _Pragma("unroll") for(int k=0;k<2;++k) \
;       acc[ai][bj][m][n]=__builtin_amdgcn_mfma_f32_16x16x32_bf16(At[m][k],Bt[n][k],acc[ai][bj][m][n],0,0,0); \
;     __builtin_amdgcn_s_setprio(0);}while(0)
; #define P8_WAIT_V(n) asm volatile("s_waitcnt vmcnt(" #n ")":::"memory")
; #define P8_WAIT_L(n) asm volatile("s_waitcnt lgkmcnt(" #n ")":::"memory")
; #define P8_BAR __builtin_amdgcn_s_barrier()
; #define P8_SCHED __builtin_amdgcn_sched_barrier(0)
; template <class EPI>
; DEVI void gemm8_tile(const bfr* __restrict__ A, const bfr* __restrict__ Bt, int K, int brow, int bcol, int nbrow, int nbcol, char* shmc, EPI epi) {
;     ...
;     P8_LDB(B0,0,0); P8_SCHED; P8_LDA(At,0,0); P8_STAGE(P8_SA(1,1),A,brow+128,t+1);
;     P8_WAIT_L(8); P8_BAR; P8_WAIT_L(0); P8_MMA(0,0,At,B0); P8_BAR; P8_SCHED;
;     P8_LDB(B1,0,1); P8_STAGE(P8_SB(0,0),Bt,bcol,t+2);
;     P8_BAR; P8_WAIT_L(0); P8_MMA(0,1,At,B1); P8_BAR;
;     P8_LDA(At,0,1); P8_STAGE(P8_SA(0,0),A,brow,t+2);
;     P8_BAR; P8_WAIT_L(0); P8_MMA(1,0,At,B0); P8_BAR; P8_SCHED;
;     P8_STAGE(P8_SB(0,1),Bt,bcol+128,t+2);
;     P8_WAIT_V(6); P8_BAR; P8_MMA(1,1,At,B1); P8_BAR;
.LBB0_141:
	ds_read_b128 v[174:177], v157
	ds_read_b128 v[178:181], v157 offset:1024
	ds_read_b128 v[182:185], v157 offset:2048
	ds_read_b128 v[186:189], v157 offset:3072
	v_add_u32_e32 v171, s8, v136
	s_add_i32 m0, s100, 0xc000
	ds_read_b128 v[160:163], v147
	ds_read_b128 v[190:193], v147 offset:1024
	ds_read_b128 v[196:199], v146
	ds_read_b128 v[208:211], v146 offset:1024
	ds_read_b128 v[212:215], v145
	ds_read_b128 v[216:219], v145 offset:1024
	ds_read_b128 v[220:223], v144
	ds_read_b128 v[224:227], v144 offset:1024
	global_load_lds_dwordx4 v171, s[86:87]
	v_add_u32_e32 v172, s8, v134
	s_add_i32 m0, s100, 0xe000
	s_nop 0
	global_load_lds_dwordx4 v172, s[86:87]
	s_waitcnt lgkmcnt(8)
	s_barrier
	s_waitcnt lgkmcnt(0)
	v_mfma_f32_16x16x32_bf16 v[124:127], v[160:163], v[174:177], v[124:127]
	v_mfma_f32_16x16x32_bf16 v[120:123], v[160:163], v[182:185], v[120:123]
	v_mfma_f32_16x16x32_bf16 v[116:119], v[196:199], v[174:177], v[116:119]
	v_mfma_f32_16x16x32_bf16 v[112:115], v[196:199], v[182:185], v[112:115]
	v_mfma_f32_16x16x32_bf16 v[108:111], v[212:215], v[174:177], v[108:111]
	v_mfma_f32_16x16x32_bf16 v[104:107], v[212:215], v[182:185], v[104:107]
	v_mfma_f32_16x16x32_bf16 v[100:103], v[220:223], v[174:177], v[100:103]
	v_mfma_f32_16x16x32_bf16 v[96:99], v[220:223], v[182:185], v[96:99]
	v_mfma_f32_16x16x32_bf16 v[124:127], v[190:193], v[178:181], v[124:127]
	v_mfma_f32_16x16x32_bf16 v[120:123], v[190:193], v[186:189], v[120:123]
	v_mfma_f32_16x16x32_bf16 v[116:119], v[208:211], v[178:181], v[116:119]
	v_mfma_f32_16x16x32_bf16 v[112:115], v[208:211], v[186:189], v[112:115]
	v_mfma_f32_16x16x32_bf16 v[108:111], v[216:219], v[178:181], v[108:111]
	v_mfma_f32_16x16x32_bf16 v[104:107], v[216:219], v[186:189], v[104:107]
	v_mfma_f32_16x16x32_bf16 v[100:103], v[224:227], v[178:181], v[100:103]
	v_mfma_f32_16x16x32_bf16 v[96:99], v[224:227], v[186:189], v[96:99]
	s_barrier
	v_add_u32_e32 v158, s66, v140
	s_add_i32 m0, s100, 0x10000
	ds_read_b128 v[228:231], v154
	ds_read_b128 v[232:235], v154 offset:1024
	ds_read_b128 v[236:239], v154 offset:2048
	ds_read_b128 v[240:243], v154 offset:3072
	global_load_lds_dwordx4 v158, s[86:87]
	v_add_u32_e32 v159, s66, v138
	s_add_i32 m0, s100, 0x12000
	s_nop 0
	global_load_lds_dwordx4 v159, s[86:87]
	s_barrier
	s_waitcnt lgkmcnt(0)
	v_mfma_f32_16x16x32_bf16 v[92:95], v[160:163], v[228:231], v[92:95]
	v_mfma_f32_16x16x32_bf16 v[88:91], v[160:163], v[236:239], v[88:91]
	v_mfma_f32_16x16x32_bf16 v[84:87], v[196:199], v[228:231], v[84:87]
	v_mfma_f32_16x16x32_bf16 v[80:83], v[196:199], v[236:239], v[80:83]
	v_mfma_f32_16x16x32_bf16 v[76:79], v[212:215], v[228:231], v[76:79]
	v_mfma_f32_16x16x32_bf16 v[72:75], v[212:215], v[236:239], v[72:75]
	v_mfma_f32_16x16x32_bf16 v[68:71], v[220:223], v[228:231], v[68:71]
	v_mfma_f32_16x16x32_bf16 v[64:67], v[220:223], v[236:239], v[64:67]
	v_mfma_f32_16x16x32_bf16 v[92:95], v[190:193], v[232:235], v[92:95]
	v_mfma_f32_16x16x32_bf16 v[88:91], v[190:193], v[240:243], v[88:91]
	v_mfma_f32_16x16x32_bf16 v[84:87], v[208:211], v[232:235], v[84:87]
	v_mfma_f32_16x16x32_bf16 v[80:83], v[208:211], v[240:243], v[80:83]
	v_mfma_f32_16x16x32_bf16 v[76:79], v[216:219], v[232:235], v[76:79]
	v_mfma_f32_16x16x32_bf16 v[72:75], v[216:219], v[240:243], v[72:75]
	v_mfma_f32_16x16x32_bf16 v[68:71], v[224:227], v[232:235], v[68:71]
	v_mfma_f32_16x16x32_bf16 v[64:67], v[224:227], v[240:243], v[64:67]
	v_add_u32_e32 v170, s54, v136
	s_mov_b32 m0, s100
	s_barrier
	ds_read_b128 v[190:193], v147 offset:16384
	ds_read_b128 v[196:199], v147 offset:17408
	ds_read_b128 v[208:211], v146 offset:16384
	ds_read_b128 v[212:215], v146 offset:17408
	ds_read_b128 v[216:219], v145 offset:16384
	ds_read_b128 v[220:223], v145 offset:17408
	ds_read_b128 v[224:227], v144 offset:16384
	ds_read_b128 v[244:247], v144 offset:17408
	global_load_lds_dwordx4 v170, s[86:87]
	v_add_u32_e32 v206, s54, v134
	s_add_i32 m0, s100, 0x2000
	s_nop 0
	global_load_lds_dwordx4 v206, s[86:87]
	s_barrier
	s_waitcnt lgkmcnt(0)
	v_mfma_f32_16x16x32_bf16 v[60:63], v[190:193], v[174:177], v[60:63]
	v_mfma_f32_16x16x32_bf16 v[56:59], v[190:193], v[182:185], v[56:59]
	v_mfma_f32_16x16x32_bf16 v[52:55], v[208:211], v[174:177], v[52:55]
	v_mfma_f32_16x16x32_bf16 v[48:51], v[208:211], v[182:185], v[48:51]
	v_mfma_f32_16x16x32_bf16 v[44:47], v[216:219], v[174:177], v[44:47]
	v_mfma_f32_16x16x32_bf16 v[40:43], v[216:219], v[182:185], v[40:43]
	v_mfma_f32_16x16x32_bf16 v[36:39], v[224:227], v[174:177], v[36:39]
	v_mfma_f32_16x16x32_bf16 v[32:35], v[224:227], v[182:185], v[32:35]
	v_mfma_f32_16x16x32_bf16 v[60:63], v[196:199], v[178:181], v[60:63]
	v_mfma_f32_16x16x32_bf16 v[56:59], v[196:199], v[186:189], v[56:59]
	v_mfma_f32_16x16x32_bf16 v[52:55], v[212:215], v[178:181], v[52:55]
	v_mfma_f32_16x16x32_bf16 v[48:51], v[212:215], v[186:189], v[48:51]
	v_mfma_f32_16x16x32_bf16 v[44:47], v[220:223], v[178:181], v[44:47]
	v_mfma_f32_16x16x32_bf16 v[40:43], v[220:223], v[186:189], v[40:43]
	v_mfma_f32_16x16x32_bf16 v[36:39], v[244:247], v[178:181], v[36:39]
	v_mfma_f32_16x16x32_bf16 v[32:35], v[244:247], v[186:189], v[32:35]
	s_barrier
	v_add_u32_e32 v248, s60, v140
	s_add_i32 m0, s100, 0x14000
	v_add_u32_e32 v200, s60, v138
	global_load_lds_dwordx4 v248, s[86:87]
	s_nop 0
	s_add_i32 m0, s100, 0x16000
	s_nop 0
	global_load_lds_dwordx4 v200, s[86:87]
	s_waitcnt vmcnt(6)
	s_barrier
; #define P8_STAGE(P,BASE,br,kt) do{const bfr* _ub=(BASE)+((long)(br)*K+(long)(kt)*BK); \
;     __builtin_amdgcn_global_load_lds((const unsigned*)(_ub+so0),(unsigned*)((char*)(P)+wid*1024),16,0,0); \
;     __builtin_amdgcn_global_load_lds((const unsigned*)(_ub+so1),(unsigned*)((char*)(P)+wid*1024+8192),16,0,0);}while(0)
; #define P8_LDA(dst,b,h) _Pragma("unroll") for(int m=0;m<4;++m) _Pragma("unroll") for(int k=0;k<2;++k) \
;     dst[m][k]=*reinterpret_cast<const bf16x8*>((char*)P8_SA(b,h)+lds_byte(wr*64+m*16+fr,k*32+fq*8))
; #define P8_LDB(dst,b,h) _Pragma("unroll") for(int n=0;n<2;++n) _Pragma("unroll") for(int k=0;k<2;++k) \
;     dst[n][k]=*reinterpret_cast<const bf16x8*>((char*)P8_SB(b,h)+lds_byte(wc*32+n*16+fr,k*32+fq*8))
; #define P8_MMA(ai,bj,At,Bt) do{__builtin_amdgcn_s_setprio(1); \
;     _Pragma("unroll") for(int m=0;m<4;++m) _Pragma("unroll") for(int n=0;n<2;++n) _Pragma("unroll") for(int k=0;k<2;++k) \
;       acc[ai][bj][m][n]=__builtin_amdgcn_mfma_f32_16x16x32_bf16(At[m][k],Bt[n][k],acc[ai][bj][m][n],0,0,0); \
;     __builtin_amdgcn_s_setprio(0);}while(0)
; #define P8_WAIT_V(n) asm volatile("s_waitcnt vmcnt(" #n ")":::"memory")
; #define P8_WAIT_L(n) asm volatile("s_waitcnt lgkmcnt(" #n ")":::"memory")
; #define P8_BAR __builtin_amdgcn_s_barrier()
; #define P8_SCHED __builtin_amdgcn_sched_barrier(0)
; template <class EPI>
; DEVI void gemm8_tile(const bfr* __restrict__ A, const bfr* __restrict__ Bt, int K, int brow, int bcol, int nbrow, int nbcol, char* shmc, EPI epi) {
;     ...
;     P8_WAIT_V(6); P8_BAR; P8_MMA(1,1,At,B1); P8_BAR;
;     P8_LDB(B0,1,0); P8_SCHED; P8_LDA(At,1,0); P8_STAGE(P8_SA(0,1),A,brow+128,t+2);
;     P8_WAIT_L(8); P8_BAR; P8_WAIT_L(0); P8_MMA(0,0,At,B0); P8_BAR; P8_SCHED;
;     P8_LDB(B1,1,1); P8_STAGE(P8_SB(1,0),Bt,bcol,t+3);
;     P8_BAR; P8_WAIT_L(0); P8_MMA(0,1,At,B1); P8_BAR;
;     P8_LDA(At,1,1); P8_STAGE(P8_SA(1,0),A,brow,t+3);
;     P8_BAR; P8_WAIT_L(0); P8_MMA(1,0,At,B0); P8_BAR; P8_SCHED;
	v_mfma_f32_16x16x32_bf16 v[28:31], v[190:193], v[228:231], v[28:31]
	v_mfma_f32_16x16x32_bf16 v[24:27], v[190:193], v[236:239], v[24:27]
	v_mfma_f32_16x16x32_bf16 v[20:23], v[208:211], v[228:231], v[20:23]
	v_mfma_f32_16x16x32_bf16 v[16:19], v[208:211], v[236:239], v[16:19]
	v_mfma_f32_16x16x32_bf16 v[12:15], v[216:219], v[228:231], v[12:15]
	v_mfma_f32_16x16x32_bf16 v[8:11], v[216:219], v[236:239], v[8:11]
	v_mfma_f32_16x16x32_bf16 v[4:7], v[224:227], v[228:231], v[4:7]
	v_mfma_f32_16x16x32_bf16 v[0:3], v[224:227], v[236:239], v[0:3]
	v_mfma_f32_16x16x32_bf16 v[28:31], v[196:199], v[232:235], v[28:31]
	v_mfma_f32_16x16x32_bf16 v[24:27], v[196:199], v[240:243], v[24:27]
	v_mfma_f32_16x16x32_bf16 v[20:23], v[212:215], v[232:235], v[20:23]
	v_mfma_f32_16x16x32_bf16 v[16:19], v[212:215], v[240:243], v[16:19]
	v_mfma_f32_16x16x32_bf16 v[12:15], v[220:223], v[232:235], v[12:15]
	v_mfma_f32_16x16x32_bf16 v[8:11], v[220:223], v[240:243], v[8:11]
	v_mfma_f32_16x16x32_bf16 v[4:7], v[244:247], v[232:235], v[4:7]
	v_mfma_f32_16x16x32_bf16 v[0:3], v[244:247], v[240:243], v[0:3]
	s_barrier
	ds_read_b128 v[174:177], v149
	ds_read_b128 v[178:181], v149 offset:1024
	ds_read_b128 v[182:185], v149 offset:2048
	ds_read_b128 v[186:189], v149 offset:3072
	s_add_i32 m0, s100, 0x3f80
	ds_read_b128 v[190:193], v147 offset:32768
	ds_read_b128 v[196:199], v147 offset:33792
	ds_read_b128 v[208:211], v146 offset:32768
	ds_read_b128 v[212:215], v146 offset:33792
	ds_read_b128 v[216:219], v145 offset:32768
	ds_read_b128 v[220:223], v145 offset:33792
	ds_read_b128 v[224:227], v144 offset:32768
	ds_read_b128 v[228:231], v144 offset:33792
	global_load_lds_dwordx4 v171, s[86:87] offset:128
	s_add_i32 m0, s100, 0x5f80
	s_nop 0
	global_load_lds_dwordx4 v172, s[86:87] offset:128
	s_waitcnt lgkmcnt(8)
	s_barrier
	s_waitcnt lgkmcnt(0)
	v_mfma_f32_16x16x32_bf16 v[124:127], v[190:193], v[174:177], v[124:127]
	v_mfma_f32_16x16x32_bf16 v[120:123], v[190:193], v[182:185], v[120:123]
	v_mfma_f32_16x16x32_bf16 v[116:119], v[208:211], v[174:177], v[116:119]
	v_mfma_f32_16x16x32_bf16 v[112:115], v[208:211], v[182:185], v[112:115]
	v_mfma_f32_16x16x32_bf16 v[108:111], v[216:219], v[174:177], v[108:111]
	v_mfma_f32_16x16x32_bf16 v[104:107], v[216:219], v[182:185], v[104:107]
	v_mfma_f32_16x16x32_bf16 v[100:103], v[224:227], v[174:177], v[100:103]
	v_mfma_f32_16x16x32_bf16 v[96:99], v[224:227], v[182:185], v[96:99]
	v_mfma_f32_16x16x32_bf16 v[124:127], v[196:199], v[178:181], v[124:127]
	v_mfma_f32_16x16x32_bf16 v[120:123], v[196:199], v[186:189], v[120:123]
	v_mfma_f32_16x16x32_bf16 v[116:119], v[212:215], v[178:181], v[116:119]
	v_mfma_f32_16x16x32_bf16 v[112:115], v[212:215], v[186:189], v[112:115]
	v_mfma_f32_16x16x32_bf16 v[108:111], v[220:223], v[178:181], v[108:111]
	v_mfma_f32_16x16x32_bf16 v[104:107], v[220:223], v[186:189], v[104:107]
	v_mfma_f32_16x16x32_bf16 v[100:103], v[228:231], v[178:181], v[100:103]
	v_mfma_f32_16x16x32_bf16 v[96:99], v[228:231], v[186:189], v[96:99]
	s_barrier
	s_add_i32 m0, s100, 0x17f80
	ds_read_b128 v[232:235], v148
	ds_read_b128 v[236:239], v148 offset:1024
	ds_read_b128 v[240:243], v148 offset:2048
	ds_read_b128 v[244:247], v148 offset:3072
	global_load_lds_dwordx4 v158, s[86:87] offset:128
	s_add_i32 m0, s100, 0x19f80
	s_nop 0
	global_load_lds_dwordx4 v159, s[86:87] offset:128
	s_barrier
	s_waitcnt lgkmcnt(0)
	v_mfma_f32_16x16x32_bf16 v[92:95], v[190:193], v[232:235], v[92:95]
	v_mfma_f32_16x16x32_bf16 v[88:91], v[190:193], v[240:243], v[88:91]
	v_mfma_f32_16x16x32_bf16 v[84:87], v[208:211], v[232:235], v[84:87]
	v_mfma_f32_16x16x32_bf16 v[80:83], v[208:211], v[240:243], v[80:83]
	v_mfma_f32_16x16x32_bf16 v[76:79], v[216:219], v[232:235], v[76:79]
	v_mfma_f32_16x16x32_bf16 v[72:75], v[216:219], v[240:243], v[72:75]
	v_mfma_f32_16x16x32_bf16 v[68:71], v[224:227], v[232:235], v[68:71]
	v_mfma_f32_16x16x32_bf16 v[64:67], v[224:227], v[240:243], v[64:67]
	v_mfma_f32_16x16x32_bf16 v[92:95], v[196:199], v[236:239], v[92:95]
	v_mfma_f32_16x16x32_bf16 v[88:91], v[196:199], v[244:247], v[88:91]
	v_mfma_f32_16x16x32_bf16 v[84:87], v[212:215], v[236:239], v[84:87]
	v_mfma_f32_16x16x32_bf16 v[80:83], v[212:215], v[244:247], v[80:83]
	v_mfma_f32_16x16x32_bf16 v[76:79], v[220:223], v[236:239], v[76:79]
	v_mfma_f32_16x16x32_bf16 v[72:75], v[220:223], v[244:247], v[72:75]
	v_mfma_f32_16x16x32_bf16 v[68:71], v[228:231], v[236:239], v[68:71]
	v_mfma_f32_16x16x32_bf16 v[64:67], v[228:231], v[244:247], v[64:67]
	s_add_i32 m0, s100, 0x7f80
	s_barrier
	ds_read_b128 v[190:193], v147 offset:49152
	ds_read_b128 v[196:199], v147 offset:50176
	ds_read_b128 v[208:211], v146 offset:49152
	ds_read_b128 v[212:215], v146 offset:50176
	ds_read_b128 v[216:219], v145 offset:49152
	ds_read_b128 v[220:223], v145 offset:50176
	ds_read_b128 v[224:227], v144 offset:49152
	ds_read_b128 v[228:231], v144 offset:50176
	global_load_lds_dwordx4 v170, s[86:87] offset:128
	s_add_i32 m0, s100, 0x9f80
	s_nop 0
	global_load_lds_dwordx4 v206, s[86:87] offset:128
	s_barrier
	s_waitcnt lgkmcnt(0)
	v_mfma_f32_16x16x32_bf16 v[60:63], v[190:193], v[174:177], v[60:63]
	v_mfma_f32_16x16x32_bf16 v[56:59], v[190:193], v[182:185], v[56:59]
	v_mfma_f32_16x16x32_bf16 v[52:55], v[208:211], v[174:177], v[52:55]
	v_mfma_f32_16x16x32_bf16 v[48:51], v[208:211], v[182:185], v[48:51]
	v_mfma_f32_16x16x32_bf16 v[44:47], v[216:219], v[174:177], v[44:47]
	v_mfma_f32_16x16x32_bf16 v[40:43], v[216:219], v[182:185], v[40:43]
	v_mfma_f32_16x16x32_bf16 v[36:39], v[224:227], v[174:177], v[36:39]
	v_mfma_f32_16x16x32_bf16 v[32:35], v[224:227], v[182:185], v[32:35]
	v_mfma_f32_16x16x32_bf16 v[60:63], v[196:199], v[178:181], v[60:63]
	v_mfma_f32_16x16x32_bf16 v[56:59], v[196:199], v[186:189], v[56:59]
	v_mfma_f32_16x16x32_bf16 v[52:55], v[212:215], v[178:181], v[52:55]
	v_mfma_f32_16x16x32_bf16 v[48:51], v[212:215], v[186:189], v[48:51]
	v_mfma_f32_16x16x32_bf16 v[44:47], v[220:223], v[178:181], v[44:47]
	v_mfma_f32_16x16x32_bf16 v[40:43], v[220:223], v[186:189], v[40:43]
	v_mfma_f32_16x16x32_bf16 v[36:39], v[228:231], v[178:181], v[36:39]
	v_mfma_f32_16x16x32_bf16 v[32:35], v[228:231], v[186:189], v[32:35]
	s_barrier
; #define P8_STAGE(P,BASE,br,kt) do{const bfr* _ub=(BASE)+((long)(br)*K+(long)(kt)*BK); \
;     __builtin_amdgcn_global_load_lds((const unsigned*)(_ub+so0),(unsigned*)((char*)(P)+wid*1024),16,0,0); \
;     __builtin_amdgcn_global_load_lds((const unsigned*)(_ub+so1),(unsigned*)((char*)(P)+wid*1024+8192),16,0,0);}while(0)
; #define P8_LDA(dst,b,h) _Pragma("unroll") for(int m=0;m<4;++m) _Pragma("unroll") for(int k=0;k<2;++k) \
;     dst[m][k]=*reinterpret_cast<const bf16x8*>((char*)P8_SA(b,h)+lds_byte(wr*64+m*16+fr,k*32+fq*8))
; #define P8_LDB(dst,b,h) _Pragma("unroll") for(int n=0;n<2;++n) _Pragma("unroll") for(int k=0;k<2;++k) \
;     dst[n][k]=*reinterpret_cast<const bf16x8*>((char*)P8_SB(b,h)+lds_byte(wc*32+n*16+fr,k*32+fq*8))
; #define P8_MMA(ai,bj,At,Bt) do{__builtin_amdgcn_s_setprio(1); \
;     _Pragma("unroll") for(int m=0;m<4;++m) _Pragma("unroll") for(int n=0;n<2;++n) _Pragma("unroll") for(int k=0;k<2;++k) \
;       acc[ai][bj][m][n]=__builtin_amdgcn_mfma_f32_16x16x32_bf16(At[m][k],Bt[n][k],acc[ai][bj][m][n],0,0,0); \
;     __builtin_amdgcn_s_setprio(0);}while(0)
; #define P8_WAIT_V(n) asm volatile("s_waitcnt vmcnt(" #n ")":::"memory")
; #define P8_WAIT_L(n) asm volatile("s_waitcnt lgkmcnt(" #n ")":::"memory")
; #define P8_BAR __builtin_amdgcn_s_barrier()
; template <class EPI>
; DEVI void gemm8_tile(const bfr* __restrict__ A, const bfr* __restrict__ Bt, int K, int brow, int bcol, int nbrow, int nbcol, char* shmc, EPI epi) {
;     ...
;     P8_STAGE(P8_SB(1,1),Bt,bcol+128,t+3);
;     P8_WAIT_V(6); P8_BAR; P8_MMA(1,1,At,B1); P8_BAR;
;   }
;   { P8_LDB(B0,0,0); P8_LDA(At,0,0); P8_STAGE(P8_SA(1,1),A,brow+128,nt-1);
;     P8_BAR; P8_WAIT_L(0); P8_MMA(0,0,At,B0); P8_BAR;
;     P8_LDB(B1,0,1); P8_BAR; P8_WAIT_L(0); P8_MMA(0,1,At,B1); P8_BAR;
	s_add_i32 m0, s100, 0x1bf80
	s_nop 0
	global_load_lds_dwordx4 v248, s[86:87] offset:128
	s_add_i32 m0, s100, 0x1df80
	s_nop 0
	global_load_lds_dwordx4 v200, s[86:87] offset:128
	s_waitcnt vmcnt(6)
	s_barrier
	v_mfma_f32_16x16x32_bf16 v[28:31], v[190:193], v[232:235], v[28:31]
	v_mfma_f32_16x16x32_bf16 v[24:27], v[190:193], v[240:243], v[24:27]
	v_mfma_f32_16x16x32_bf16 v[20:23], v[208:211], v[232:235], v[20:23]
	v_mfma_f32_16x16x32_bf16 v[16:19], v[208:211], v[240:243], v[16:19]
	v_mfma_f32_16x16x32_bf16 v[12:15], v[216:219], v[232:235], v[12:15]
	v_mfma_f32_16x16x32_bf16 v[8:11], v[216:219], v[240:243], v[8:11]
	v_mfma_f32_16x16x32_bf16 v[4:7], v[224:227], v[232:235], v[4:7]
	v_mfma_f32_16x16x32_bf16 v[0:3], v[224:227], v[240:243], v[0:3]
	v_mfma_f32_16x16x32_bf16 v[28:31], v[196:199], v[236:239], v[28:31]
	v_mfma_f32_16x16x32_bf16 v[24:27], v[196:199], v[244:247], v[24:27]
	v_mfma_f32_16x16x32_bf16 v[20:23], v[212:215], v[236:239], v[20:23]
	v_mfma_f32_16x16x32_bf16 v[16:19], v[212:215], v[244:247], v[16:19]
	v_mfma_f32_16x16x32_bf16 v[12:15], v[220:223], v[236:239], v[12:15]
	v_mfma_f32_16x16x32_bf16 v[8:11], v[220:223], v[244:247], v[8:11]
	v_mfma_f32_16x16x32_bf16 v[4:7], v[228:231], v[236:239], v[4:7]
	v_mfma_f32_16x16x32_bf16 v[0:3], v[228:231], v[244:247], v[0:3]
	s_add_i32 s0, s0, 2
	v_lshl_add_u64 v[134:135], v[134:135], 0, s[80:81]
	v_lshl_add_u64 v[136:137], v[136:137], 0, s[80:81]
	v_lshl_add_u64 v[138:139], v[138:139], 0, s[80:81]
	s_cmp_lt_u32 s0, 4
	v_lshl_add_u64 v[140:141], v[140:141], 0, s[80:81]
	s_barrier
	s_cbranch_scc1 .LBB0_141
	v_add_u32_e32 v171, 0xc000, v143
	v_add_u32_e32 v172, 0xe000, v143
	v_add_u32_e32 v158, 0x10000, v143
	v_add_u32_e32 v159, 0x12000, v143
	v_add_u32_e32 v160, 0x2000, v143
	v_add_u32_e32 v161, 0x14000, v143
	v_add_u32_e32 v162, 0x16000, v143
	v_add_u32_e32 v163, 0x4000, v143
	v_add_u32_e32 v170, 0x6000, v143
	s_or_b32 s0, s6, 0x80
	s_ashr_i32 s1, s0, 31
	s_lshl_b64 s[0:1], s[0:1], 10
	s_add_u32 s0, s28, s0
	s_addc_u32 s1, s29, s1
	ds_read_b128 v[134:137], v157
	ds_read_b128 v[138:141], v157 offset:1024
	ds_read_b128 v[150:153], v157 offset:2048
	ds_read_b128 v[174:177], v157 offset:3072
	ds_read_b128 v[178:181], v147
	ds_read_b128 v[182:185], v147 offset:1024
	ds_read_b128 v[186:189], v146
	ds_read_b128 v[190:193], v146 offset:1024
	ds_read_b128 v[196:199], v145
	ds_read_b128 v[208:211], v145 offset:1024
	ds_read_b128 v[212:215], v144
	ds_read_b128 v[216:219], v144 offset:1024
	v_lshl_add_u64 v[156:157], v[166:167], 1, s[0:1]
	s_mov_b64 s[6:7], 0x380
	v_lshl_add_u64 v[156:157], v[156:157], 0, s[6:7]
	s_add_i32 m0, s100, 0xc000
	v_lshl_add_u64 v[132:133], v[132:133], 1, s[0:1]
	global_load_lds_dwordx4 v[156:157], off
	v_lshl_add_u64 v[132:133], v[132:133], 0, s[6:7]
	s_add_i32 m0, s100, 0xe000
	s_nop 0
	global_load_lds_dwordx4 v[132:133], off
	s_barrier
	s_waitcnt lgkmcnt(0)
	s_setprio 1
	s_waitcnt lgkmcnt(0)
	v_mfma_f32_16x16x32_bf16 v[124:127], v[178:181], v[134:137], v[124:127]
	v_mfma_f32_16x16x32_bf16 v[120:123], v[178:181], v[150:153], v[120:123]
	v_mfma_f32_16x16x32_bf16 v[116:119], v[186:189], v[134:137], v[116:119]
	v_mfma_f32_16x16x32_bf16 v[112:115], v[186:189], v[150:153], v[112:115]
	v_mfma_f32_16x16x32_bf16 v[108:111], v[196:199], v[134:137], v[108:111]
	v_mfma_f32_16x16x32_bf16 v[104:107], v[196:199], v[150:153], v[104:107]
	v_mfma_f32_16x16x32_bf16 v[100:103], v[212:215], v[134:137], v[100:103]
	v_mfma_f32_16x16x32_bf16 v[96:99], v[212:215], v[150:153], v[96:99]
	v_mfma_f32_16x16x32_bf16 v[124:127], v[182:185], v[138:141], v[124:127]
	v_mfma_f32_16x16x32_bf16 v[120:123], v[182:185], v[174:177], v[120:123]
	v_mfma_f32_16x16x32_bf16 v[116:119], v[190:193], v[138:141], v[116:119]
	v_mfma_f32_16x16x32_bf16 v[112:115], v[190:193], v[174:177], v[112:115]
	v_mfma_f32_16x16x32_bf16 v[108:111], v[208:211], v[138:141], v[108:111]
	v_mfma_f32_16x16x32_bf16 v[104:107], v[208:211], v[174:177], v[104:107]
	v_mfma_f32_16x16x32_bf16 v[100:103], v[216:219], v[138:141], v[100:103]
	v_mfma_f32_16x16x32_bf16 v[96:99], v[216:219], v[174:177], v[96:99]
	s_setprio 0
	s_barrier
	ds_read_b128 v[220:223], v154
	ds_read_b128 v[224:227], v154 offset:1024
	ds_read_b128 v[228:231], v154 offset:2048
	ds_read_b128 v[154:157], v154 offset:3072
	s_barrier
	s_waitcnt lgkmcnt(0)
	s_setprio 1
	s_waitcnt lgkmcnt(0)
	v_mfma_f32_16x16x32_bf16 v[88:91], v[178:181], v[228:231], v[88:91]
	v_mfma_f32_16x16x32_bf16 v[76:79], v[196:199], v[220:223], v[76:79]
	v_mfma_f32_16x16x32_bf16 v[72:75], v[196:199], v[228:231], v[72:75]
	v_mfma_f32_16x16x32_bf16 v[68:71], v[212:215], v[220:223], v[68:71]
	v_mfma_f32_16x16x32_bf16 v[64:67], v[212:215], v[228:231], v[64:67]
	v_mfma_f32_16x16x32_bf16 v[92:95], v[178:181], v[220:223], v[92:95]
	v_mfma_f32_16x16x32_bf16 v[178:181], v[182:185], v[154:157], v[88:91]
	v_mfma_f32_16x16x32_bf16 v[84:87], v[186:189], v[220:223], v[84:87]
	v_mfma_f32_16x16x32_bf16 v[80:83], v[186:189], v[228:231], v[80:83]
	v_mfma_f32_16x16x32_bf16 v[76:79], v[208:211], v[224:227], v[76:79]
	v_mfma_f32_16x16x32_bf16 v[72:75], v[208:211], v[154:157], v[72:75]
	v_mfma_f32_16x16x32_bf16 v[68:71], v[216:219], v[224:227], v[68:71]
	v_mfma_f32_16x16x32_bf16 v[64:67], v[216:219], v[154:157], v[64:67]
	v_mfma_f32_16x16x32_bf16 v[232:235], v[182:185], v[224:227], v[92:95]
	v_mfma_f32_16x16x32_bf16 v[182:185], v[190:193], v[224:227], v[84:87]
	v_mfma_f32_16x16x32_bf16 v[186:189], v[190:193], v[154:157], v[80:83]
	s_setprio 0
	s_barrier
; #define P8_LDA(dst,b,h) _Pragma("unroll") for(int m=0;m<4;++m) _Pragma("unroll") for(int k=0;k<2;++k) \
;     dst[m][k]=*reinterpret_cast<const bf16x8*>((char*)P8_SA(b,h)+lds_byte(wr*64+m*16+fr,k*32+fq*8))
; #define P8_LDB(dst,b,h) _Pragma("unroll") for(int n=0;n<2;++n) _Pragma("unroll") for(int k=0;k<2;++k) \
;     dst[n][k]=*reinterpret_cast<const bf16x8*>((char*)P8_SB(b,h)+lds_byte(wc*32+n*16+fr,k*32+fq*8))
; #define P8_MMA(ai,bj,At,Bt) do{__builtin_amdgcn_s_setprio(1); \
;     _Pragma("unroll") for(int m=0;m<4;++m) _Pragma("unroll") for(int n=0;n<2;++n) _Pragma("unroll") for(int k=0;k<2;++k) \
;       acc[ai][bj][m][n]=__builtin_amdgcn_mfma_f32_16x16x32_bf16(At[m][k],Bt[n][k],acc[ai][bj][m][n],0,0,0); \
;     __builtin_amdgcn_s_setprio(0);}while(0)
; #define P8_WAIT_V(n) asm volatile("s_waitcnt vmcnt(" #n ")":::"memory")
; #define P8_WAIT_L(n) asm volatile("s_waitcnt lgkmcnt(" #n ")":::"memory")
; #define P8_BAR __builtin_amdgcn_s_barrier()
; template <class EPI>
; DEVI void gemm8_tile(const bfr* __restrict__ A, const bfr* __restrict__ Bt, int K, int brow, int bcol, int nbrow, int nbcol, char* shmc, EPI epi) {
;     ...
;     P8_LDA(At,0,1); P8_WAIT_V(4); P8_BAR; P8_WAIT_L(0); P8_MMA(1,0,At,B0); P8_MMA(1,1,At,B1); P8_BAR; }
;   { P8_LDB(B0,1,0); P8_LDA(At,1,0); P8_WAIT_V(2); P8_BAR; P8_WAIT_L(0); P8_MMA(0,0,At,B0); P8_BAR;
	s_nop 0
	ds_read_b128 v[80:83], v147 offset:16384
	ds_read_b128 v[84:87], v147 offset:17408
	ds_read_b128 v[88:91], v146 offset:16384
	ds_read_b128 v[92:95], v146 offset:17408
	ds_read_b128 v[190:193], v145 offset:16384
	ds_read_b128 v[196:199], v145 offset:17408
	ds_read_b128 v[208:211], v144 offset:16384
	ds_read_b128 v[212:215], v144 offset:17408
	s_waitcnt vmcnt(4)
	s_barrier
	s_waitcnt lgkmcnt(0)
	s_setprio 1
	s_waitcnt lgkmcnt(0)
	v_mfma_f32_16x16x32_bf16 v[44:47], v[190:193], v[134:137], v[44:47]
	v_mfma_f32_16x16x32_bf16 v[40:43], v[190:193], v[150:153], v[40:43]
	v_mfma_f32_16x16x32_bf16 v[36:39], v[208:211], v[134:137], v[36:39]
	v_mfma_f32_16x16x32_bf16 v[32:35], v[208:211], v[150:153], v[32:35]
	v_mfma_f32_16x16x32_bf16 v[60:63], v[80:83], v[134:137], v[60:63]
	v_mfma_f32_16x16x32_bf16 v[56:59], v[80:83], v[150:153], v[56:59]
	v_mfma_f32_16x16x32_bf16 v[52:55], v[88:91], v[134:137], v[52:55]
	v_mfma_f32_16x16x32_bf16 v[48:51], v[88:91], v[150:153], v[48:51]
	v_mfma_f32_16x16x32_bf16 v[44:47], v[196:199], v[138:141], v[44:47]
	v_mfma_f32_16x16x32_bf16 v[40:43], v[196:199], v[174:177], v[40:43]
	v_mfma_f32_16x16x32_bf16 v[36:39], v[212:215], v[138:141], v[36:39]
	v_mfma_f32_16x16x32_bf16 v[32:35], v[212:215], v[174:177], v[32:35]
	v_mfma_f32_16x16x32_bf16 v[216:219], v[84:87], v[138:141], v[60:63]
	v_mfma_f32_16x16x32_bf16 v[236:239], v[84:87], v[174:177], v[56:59]
	v_mfma_f32_16x16x32_bf16 v[240:243], v[92:95], v[138:141], v[52:55]
	v_mfma_f32_16x16x32_bf16 v[244:247], v[92:95], v[174:177], v[48:51]
	s_setprio 0
	s_setprio 1
	v_mfma_f32_16x16x32_bf16 v[12:15], v[190:193], v[220:223], v[12:15]
	v_mfma_f32_16x16x32_bf16 v[4:7], v[208:211], v[220:223], v[4:7]
	v_mfma_f32_16x16x32_bf16 v[28:31], v[80:83], v[220:223], v[28:31]
	v_mfma_f32_16x16x32_bf16 v[24:27], v[80:83], v[228:231], v[24:27]
	v_mfma_f32_16x16x32_bf16 v[20:23], v[88:91], v[220:223], v[20:23]
	v_mfma_f32_16x16x32_bf16 v[16:19], v[88:91], v[228:231], v[16:19]
	v_mfma_f32_16x16x32_bf16 v[12:15], v[196:199], v[224:227], v[12:15]
	v_mfma_f32_16x16x32_bf16 v[8:11], v[190:193], v[228:231], v[8:11]
	v_mfma_f32_16x16x32_bf16 v[4:7], v[212:215], v[224:227], v[4:7]
	v_mfma_f32_16x16x32_bf16 v[0:3], v[208:211], v[228:231], v[0:3]
	v_mfma_f32_16x16x32_bf16 v[132:135], v[84:87], v[224:227], v[28:31]
	v_mfma_f32_16x16x32_bf16 v[136:139], v[84:87], v[154:157], v[24:27]
	v_mfma_f32_16x16x32_bf16 v[150:153], v[92:95], v[224:227], v[20:23]
	v_mfma_f32_16x16x32_bf16 v[172:175], v[92:95], v[154:157], v[16:19]
	v_mfma_f32_16x16x32_bf16 v[190:193], v[196:199], v[154:157], v[8:11]
	v_mfma_f32_16x16x32_bf16 v[154:157], v[212:215], v[154:157], v[0:3]
	s_setprio 0
	s_barrier
	s_nop 0
	ds_read_b128 v[0:3], v149
	ds_read_b128 v[8:11], v149 offset:1024
	ds_read_b128 v[196:199], v149 offset:2048
	ds_read_b128 v[208:211], v149 offset:3072
	ds_read_b128 v[16:19], v147 offset:32768
	ds_read_b128 v[20:23], v147 offset:33792
	ds_read_b128 v[24:27], v146 offset:32768
	ds_read_b128 v[48:51], v146 offset:33792
	ds_read_b128 v[212:215], v145 offset:32768
	ds_read_b128 v[220:223], v145 offset:33792
	ds_read_b128 v[224:227], v144 offset:32768
	ds_read_b128 v[228:231], v144 offset:33792
	s_waitcnt vmcnt(2)
	s_barrier
	s_waitcnt lgkmcnt(0)
	s_setprio 1
	s_waitcnt lgkmcnt(0)
	v_mfma_f32_16x16x32_bf16 v[28:31], v[16:19], v[0:3], v[124:127]
	v_mfma_f32_16x16x32_bf16 v[124:127], v[20:23], v[8:11], v[28:31]
	v_mfma_f32_16x16x32_bf16 v[28:31], v[16:19], v[196:199], v[120:123]
	v_mfma_f32_16x16x32_bf16 v[92:95], v[20:23], v[208:211], v[28:31]
	v_mfma_f32_16x16x32_bf16 v[28:31], v[24:27], v[0:3], v[116:119]
	v_mfma_f32_16x16x32_bf16 v[120:123], v[48:51], v[8:11], v[28:31]
	v_mfma_f32_16x16x32_bf16 v[28:31], v[24:27], v[196:199], v[112:115]
	v_mfma_f32_16x16x32_bf16 v[88:91], v[48:51], v[208:211], v[28:31]
	v_mfma_f32_16x16x32_bf16 v[28:31], v[212:215], v[0:3], v[108:111]
	v_mfma_f32_16x16x32_bf16 v[116:119], v[220:223], v[8:11], v[28:31]
	v_mfma_f32_16x16x32_bf16 v[28:31], v[212:215], v[196:199], v[104:107]
	v_mfma_f32_16x16x32_bf16 v[84:87], v[220:223], v[208:211], v[28:31]
	v_mfma_f32_16x16x32_bf16 v[28:31], v[224:227], v[0:3], v[100:103]
	v_mfma_f32_16x16x32_bf16 v[112:115], v[228:231], v[8:11], v[28:31]
	v_mfma_f32_16x16x32_bf16 v[28:31], v[224:227], v[196:199], v[96:99]
	v_mfma_f32_16x16x32_bf16 v[80:83], v[228:231], v[208:211], v[28:31]
	s_setprio 0
	s_barrier
; #define P8_LDA(dst,b,h) _Pragma("unroll") for(int m=0;m<4;++m) _Pragma("unroll") for(int k=0;k<2;++k) \
;     dst[m][k]=*reinterpret_cast<const bf16x8*>((char*)P8_SA(b,h)+lds_byte(wr*64+m*16+fr,k*32+fq*8))
; #define P8_LDB(dst,b,h) _Pragma("unroll") for(int n=0;n<2;++n) _Pragma("unroll") for(int k=0;k<2;++k) \
;     dst[n][k]=*reinterpret_cast<const bf16x8*>((char*)P8_SB(b,h)+lds_byte(wc*32+n*16+fr,k*32+fq*8))
; #define P8_MMA(ai,bj,At,Bt) do{__builtin_amdgcn_s_setprio(1); \
;     _Pragma("unroll") for(int m=0;m<4;++m) _Pragma("unroll") for(int n=0;n<2;++n) _Pragma("unroll") for(int k=0;k<2;++k) \
;       acc[ai][bj][m][n]=__builtin_amdgcn_mfma_f32_16x16x32_bf16(At[m][k],Bt[n][k],acc[ai][bj][m][n],0,0,0); \
;     __builtin_amdgcn_s_setprio(0);}while(0)
; #define P8_WAIT_V(n) asm volatile("s_waitcnt vmcnt(" #n ")":::"memory")
; #define P8_WAIT_L(n) asm volatile("s_waitcnt lgkmcnt(" #n ")":::"memory")
; #define P8_BAR __builtin_amdgcn_s_barrier()
; template <class EPI>
; DEVI void gemm8_tile(const bfr* __restrict__ A, const bfr* __restrict__ Bt, int K, int brow, int bcol, int nbrow, int nbcol, char* shmc, EPI epi) {
;     ...
;     P8_LDB(B1,1,1); P8_WAIT_V(0); P8_BAR; P8_WAIT_L(0); P8_MMA(0,1,At,B1); P8_BAR;
;     P8_LDA(At,1,1); P8_BAR; P8_WAIT_L(0); P8_MMA(1,0,At,B0); P8_MMA(1,1,At,B1); P8_BAR; }
;   if(wr==0)P8_BAR;
	ds_read_b128 v[248:251], v148
	ds_read_b128 v[200:203], v148 offset:1024
	ds_read_b128 v[204:207], v148 offset:2048
	s_nop 1
	ds_read_b128 v[28:31], v148 offset:3072
	s_waitcnt vmcnt(0)
	s_barrier
	s_waitcnt lgkmcnt(0)
	s_setprio 1
	s_waitcnt lgkmcnt(0)
	v_mfma_f32_16x16x32_bf16 v[52:55], v[16:19], v[248:251], v[232:235]
	v_mfma_f32_16x16x32_bf16 v[16:19], v[16:19], v[204:207], v[178:181]
	v_mfma_f32_16x16x32_bf16 v[176:179], v[20:23], v[28:31], v[16:19]
	v_mfma_f32_16x16x32_bf16 v[16:19], v[24:27], v[248:251], v[182:185]
	v_mfma_f32_16x16x32_bf16 v[56:59], v[48:51], v[200:203], v[16:19]
	v_mfma_f32_16x16x32_bf16 v[16:19], v[24:27], v[204:207], v[186:189]
	v_mfma_f32_16x16x32_bf16 v[24:27], v[48:51], v[28:31], v[16:19]
	v_mfma_f32_16x16x32_bf16 v[16:19], v[212:215], v[248:251], v[76:79]
	v_mfma_f32_16x16x32_bf16 v[60:63], v[20:23], v[200:203], v[52:55]
	v_mfma_f32_16x16x32_bf16 v[52:55], v[220:223], v[200:203], v[16:19]
	v_mfma_f32_16x16x32_bf16 v[16:19], v[212:215], v[204:207], v[72:75]
	v_mfma_f32_16x16x32_bf16 v[20:23], v[220:223], v[28:31], v[16:19]
	v_mfma_f32_16x16x32_bf16 v[16:19], v[224:227], v[248:251], v[68:71]
	v_mfma_f32_16x16x32_bf16 v[48:51], v[228:231], v[200:203], v[16:19]
	v_mfma_f32_16x16x32_bf16 v[16:19], v[224:227], v[204:207], v[64:67]
	v_mfma_f32_16x16x32_bf16 v[16:19], v[228:231], v[28:31], v[16:19]
	s_setprio 0
	s_barrier
	ds_read_b128 v[180:183], v147 offset:49152
	ds_read_b128 v[184:187], v147 offset:50176
	ds_read_b128 v[212:215], v146 offset:49152
	ds_read_b128 v[146:149], v146 offset:50176
	ds_read_b128 v[220:223], v145 offset:49152
	ds_read_b128 v[224:227], v145 offset:50176
	ds_read_b128 v[228:231], v144 offset:49152
	ds_read_b128 v[232:235], v144 offset:50176
	s_barrier
	s_waitcnt lgkmcnt(0)
	s_setprio 1
	s_waitcnt lgkmcnt(0)
	v_mfma_f32_16x16x32_bf16 v[64:67], v[180:183], v[0:3], v[216:219]
	v_mfma_f32_16x16x32_bf16 v[104:107], v[184:187], v[8:11], v[64:67]
	v_mfma_f32_16x16x32_bf16 v[64:67], v[180:183], v[196:199], v[236:239]
	v_mfma_f32_16x16x32_bf16 v[72:75], v[184:187], v[208:211], v[64:67]
	v_mfma_f32_16x16x32_bf16 v[64:67], v[212:215], v[0:3], v[240:243]
	v_mfma_f32_16x16x32_bf16 v[44:47], v[220:223], v[0:3], v[44:47]
	v_mfma_f32_16x16x32_bf16 v[0:3], v[228:231], v[0:3], v[36:39]
	v_mfma_f32_16x16x32_bf16 v[96:99], v[146:149], v[8:11], v[64:67]
	v_mfma_f32_16x16x32_bf16 v[64:67], v[212:215], v[196:199], v[244:247]
	v_mfma_f32_16x16x32_bf16 v[40:43], v[220:223], v[196:199], v[40:43]
	v_mfma_f32_16x16x32_bf16 v[100:103], v[232:235], v[8:11], v[0:3]
	v_mfma_f32_16x16x32_bf16 v[0:3], v[228:231], v[196:199], v[32:35]
	v_mfma_f32_16x16x32_bf16 v[64:67], v[146:149], v[208:211], v[64:67]
	v_mfma_f32_16x16x32_bf16 v[108:111], v[224:227], v[8:11], v[44:47]
	v_mfma_f32_16x16x32_bf16 v[76:79], v[224:227], v[208:211], v[40:43]
	v_mfma_f32_16x16x32_bf16 v[68:71], v[232:235], v[208:211], v[0:3]
	s_setprio 0
	s_setprio 1
	v_mfma_f32_16x16x32_bf16 v[0:3], v[180:183], v[248:251], v[132:135]
	v_mfma_f32_16x16x32_bf16 v[40:43], v[184:187], v[200:203], v[0:3]
	v_mfma_f32_16x16x32_bf16 v[0:3], v[180:183], v[204:207], v[136:139]
	v_mfma_f32_16x16x32_bf16 v[8:11], v[184:187], v[28:31], v[0:3]
	v_mfma_f32_16x16x32_bf16 v[0:3], v[212:215], v[248:251], v[150:153]
	v_mfma_f32_16x16x32_bf16 v[12:15], v[220:223], v[248:251], v[12:15]
	v_mfma_f32_16x16x32_bf16 v[4:7], v[228:231], v[248:251], v[4:7]
	v_mfma_f32_16x16x32_bf16 v[32:35], v[146:149], v[200:203], v[0:3]
	v_mfma_f32_16x16x32_bf16 v[0:3], v[212:215], v[204:207], v[172:175]
	v_mfma_f32_16x16x32_bf16 v[44:47], v[224:227], v[200:203], v[12:15]
	v_mfma_f32_16x16x32_bf16 v[12:15], v[220:223], v[204:207], v[190:193]
	v_mfma_f32_16x16x32_bf16 v[36:39], v[232:235], v[200:203], v[4:7]
	v_mfma_f32_16x16x32_bf16 v[4:7], v[228:231], v[204:207], v[154:157]
	v_mfma_f32_16x16x32_bf16 v[0:3], v[146:149], v[28:31], v[0:3]
	v_mfma_f32_16x16x32_bf16 v[12:15], v[224:227], v[28:31], v[12:15]
	v_mfma_f32_16x16x32_bf16 v[4:7], v[232:235], v[28:31], v[4:7]
	s_setprio 0
	v_cmp_gt_u32_e32 vcc, s57, v142
	s_barrier
	s_and_saveexec_b64 s[0:1], vcc
	s_cbranch_execz .LBB0_144
	s_barrier

; #define P8_STAGE(P,BASE,br,kt) do{const bfr* _ub=(BASE)+((long)(br)*K+(long)(kt)*BK); \
;     __builtin_amdgcn_global_load_lds((const unsigned*)(_ub+so0),(unsigned*)((char*)(P)+wid*1024),16,0,0); \
;     __builtin_amdgcn_global_load_lds((const unsigned*)(_ub+so1),(unsigned*)((char*)(P)+wid*1024+8192),16,0,0);}while(0)
; #define P8_LDA(dst,b,h) _Pragma("unroll") for(int m=0;m<4;++m) _Pragma("unroll") for(int k=0;k<2;++k) \
;     dst[m][k]=*reinterpret_cast<const bf16x8*>((char*)P8_SA(b,h)+lds_byte(wr*64+m*16+fr,k*32+fq*8))
; #define P8_LDB(dst,b,h) _Pragma("unroll") for(int n=0;n<2;++n) _Pragma("unroll") for(int k=0;k<2;++k) \
;     dst[n][k]=*reinterpret_cast<const bf16x8*>((char*)P8_SB(b,h)+lds_byte(wc*32+n*16+fr,k*32+fq*8))
; #define P8_MMA(ai,bj,At,Bt) do{__builtin_amdgcn_s_setprio(1); \
;     _Pragma("unroll") for(int m=0;m<4;++m) _Pragma("unroll") for(int n=0;n<2;++n) _Pragma("unroll") for(int k=0;k<2;++k) \
;       acc[ai][bj][m][n]=__builtin_amdgcn_mfma_f32_16x16x32_bf16(At[m][k],Bt[n][k],acc[ai][bj][m][n],0,0,0); \
;     __builtin_amdgcn_s_setprio(0);}while(0)
; #define P8_WAIT_V(n) asm volatile("s_waitcnt vmcnt(" #n ")":::"memory")
; #define P8_WAIT_L(n) asm volatile("s_waitcnt lgkmcnt(" #n ")":::"memory")
; #define P8_BAR __builtin_amdgcn_s_barrier()
; #define P8_SCHED __builtin_amdgcn_sched_barrier(0)
; template <class EPI>
; DEVI void gemm8_tile(const bfr* __restrict__ A, const bfr* __restrict__ Bt, int K, int brow, int bcol, int nbrow, int nbcol, char* shmc, EPI epi) {
;     ...
;     P8_LDB(B0,0,0); P8_SCHED; P8_LDA(At,0,0); P8_STAGE(P8_SA(1,1),A,brow+128,t+1);
;     P8_WAIT_L(8); P8_BAR; P8_WAIT_L(0); P8_MMA(0,0,At,B0); P8_BAR; P8_SCHED;
;     P8_LDB(B1,0,1); P8_STAGE(P8_SB(0,0),Bt,bcol,t+2);
;     P8_BAR; P8_WAIT_L(0); P8_MMA(0,1,At,B1); P8_BAR;
;     P8_LDA(At,0,1); P8_STAGE(P8_SA(0,0),A,brow,t+2);
;     P8_BAR; P8_WAIT_L(0); P8_MMA(1,0,At,B0); P8_BAR; P8_SCHED;
;     P8_STAGE(P8_SB(0,1),Bt,bcol+128,t+2);
;     P8_WAIT_V(6); P8_BAR; P8_MMA(1,1,At,B1); P8_BAR;
.LBB0_175:
	ds_read_b128 v[174:177], v157
	ds_read_b128 v[178:181], v157 offset:1024
	ds_read_b128 v[182:185], v157 offset:2048
	ds_read_b128 v[186:189], v157 offset:3072
	v_add_u32_e32 v171, s54, v136
	s_add_i32 m0, s100, 0xc000
	ds_read_b128 v[160:163], v147
	ds_read_b128 v[190:193], v147 offset:1024
	ds_read_b128 v[196:199], v146
	ds_read_b128 v[200:203], v146 offset:1024
	ds_read_b128 v[204:207], v145
	ds_read_b128 v[208:211], v145 offset:1024
	ds_read_b128 v[212:215], v144
	ds_read_b128 v[216:219], v144 offset:1024
	global_load_lds_dwordx4 v171, s[86:87]
	v_add_u32_e32 v172, s54, v134
	s_add_i32 m0, s100, 0xe000
	s_nop 0
	global_load_lds_dwordx4 v172, s[86:87]
	s_waitcnt lgkmcnt(8)
	s_barrier
	s_waitcnt lgkmcnt(0)
	v_mfma_f32_16x16x32_bf16 v[124:127], v[160:163], v[174:177], v[124:127]
	v_mfma_f32_16x16x32_bf16 v[120:123], v[160:163], v[182:185], v[120:123]
	v_mfma_f32_16x16x32_bf16 v[116:119], v[196:199], v[174:177], v[116:119]
	v_mfma_f32_16x16x32_bf16 v[112:115], v[196:199], v[182:185], v[112:115]
	v_mfma_f32_16x16x32_bf16 v[108:111], v[204:207], v[174:177], v[108:111]
	v_mfma_f32_16x16x32_bf16 v[104:107], v[204:207], v[182:185], v[104:107]
	v_mfma_f32_16x16x32_bf16 v[100:103], v[212:215], v[174:177], v[100:103]
	v_mfma_f32_16x16x32_bf16 v[96:99], v[212:215], v[182:185], v[96:99]
	v_mfma_f32_16x16x32_bf16 v[124:127], v[190:193], v[178:181], v[124:127]
	v_mfma_f32_16x16x32_bf16 v[120:123], v[190:193], v[186:189], v[120:123]
	v_mfma_f32_16x16x32_bf16 v[116:119], v[200:203], v[178:181], v[116:119]
	v_mfma_f32_16x16x32_bf16 v[112:115], v[200:203], v[186:189], v[112:115]
	v_mfma_f32_16x16x32_bf16 v[108:111], v[208:211], v[178:181], v[108:111]
	v_mfma_f32_16x16x32_bf16 v[104:107], v[208:211], v[186:189], v[104:107]
	v_mfma_f32_16x16x32_bf16 v[100:103], v[216:219], v[178:181], v[100:103]
	v_mfma_f32_16x16x32_bf16 v[96:99], v[216:219], v[186:189], v[96:99]
	s_barrier
	v_add_u32_e32 v158, s60, v140
	s_add_i32 m0, s100, 0x10000
	ds_read_b128 v[220:223], v154
	ds_read_b128 v[224:227], v154 offset:1024
	ds_read_b128 v[228:231], v154 offset:2048
	ds_read_b128 v[232:235], v154 offset:3072
	global_load_lds_dwordx4 v158, s[86:87]
	v_add_u32_e32 v159, s60, v138
	s_add_i32 m0, s100, 0x12000
	s_nop 0
	global_load_lds_dwordx4 v159, s[86:87]
	s_barrier
	s_waitcnt lgkmcnt(0)
	v_mfma_f32_16x16x32_bf16 v[92:95], v[160:163], v[220:223], v[92:95]
	v_mfma_f32_16x16x32_bf16 v[88:91], v[160:163], v[228:231], v[88:91]
	v_mfma_f32_16x16x32_bf16 v[84:87], v[196:199], v[220:223], v[84:87]
	v_mfma_f32_16x16x32_bf16 v[80:83], v[196:199], v[228:231], v[80:83]
	v_mfma_f32_16x16x32_bf16 v[76:79], v[204:207], v[220:223], v[76:79]
	v_mfma_f32_16x16x32_bf16 v[72:75], v[204:207], v[228:231], v[72:75]
	v_mfma_f32_16x16x32_bf16 v[68:71], v[212:215], v[220:223], v[68:71]
	v_mfma_f32_16x16x32_bf16 v[64:67], v[212:215], v[228:231], v[64:67]
	v_mfma_f32_16x16x32_bf16 v[92:95], v[190:193], v[224:227], v[92:95]
	v_mfma_f32_16x16x32_bf16 v[88:91], v[190:193], v[232:235], v[88:91]
	v_mfma_f32_16x16x32_bf16 v[84:87], v[200:203], v[224:227], v[84:87]
	v_mfma_f32_16x16x32_bf16 v[80:83], v[200:203], v[232:235], v[80:83]
	v_mfma_f32_16x16x32_bf16 v[76:79], v[208:211], v[224:227], v[76:79]
	v_mfma_f32_16x16x32_bf16 v[72:75], v[208:211], v[232:235], v[72:75]
	v_mfma_f32_16x16x32_bf16 v[68:71], v[216:219], v[224:227], v[68:71]
	v_mfma_f32_16x16x32_bf16 v[64:67], v[216:219], v[232:235], v[64:67]
	v_add_u32_e32 v170, s72, v136
	s_mov_b32 m0, s100
	s_barrier
	ds_read_b128 v[190:193], v147 offset:16384
	ds_read_b128 v[196:199], v147 offset:17408
	ds_read_b128 v[200:203], v146 offset:16384
	ds_read_b128 v[204:207], v146 offset:17408
	ds_read_b128 v[208:211], v145 offset:16384
	ds_read_b128 v[212:215], v145 offset:17408
	ds_read_b128 v[216:219], v144 offset:16384
	ds_read_b128 v[236:239], v144 offset:17408
	global_load_lds_dwordx4 v170, s[86:87]
	v_add_u32_e32 v248, s72, v134
	s_add_i32 m0, s100, 0x2000
	s_nop 0
	global_load_lds_dwordx4 v248, s[86:87]
	s_barrier
	s_waitcnt lgkmcnt(0)
	v_mfma_f32_16x16x32_bf16 v[60:63], v[190:193], v[174:177], v[60:63]
	v_mfma_f32_16x16x32_bf16 v[56:59], v[190:193], v[182:185], v[56:59]
	v_mfma_f32_16x16x32_bf16 v[52:55], v[200:203], v[174:177], v[52:55]
	v_mfma_f32_16x16x32_bf16 v[48:51], v[200:203], v[182:185], v[48:51]
	v_mfma_f32_16x16x32_bf16 v[44:47], v[208:211], v[174:177], v[44:47]
	v_mfma_f32_16x16x32_bf16 v[40:43], v[208:211], v[182:185], v[40:43]
	v_mfma_f32_16x16x32_bf16 v[36:39], v[216:219], v[174:177], v[36:39]
	v_mfma_f32_16x16x32_bf16 v[32:35], v[216:219], v[182:185], v[32:35]
	v_mfma_f32_16x16x32_bf16 v[60:63], v[196:199], v[178:181], v[60:63]
	v_mfma_f32_16x16x32_bf16 v[56:59], v[196:199], v[186:189], v[56:59]
	v_mfma_f32_16x16x32_bf16 v[52:55], v[204:207], v[178:181], v[52:55]
	v_mfma_f32_16x16x32_bf16 v[48:51], v[204:207], v[186:189], v[48:51]
	v_mfma_f32_16x16x32_bf16 v[44:47], v[212:215], v[178:181], v[44:47]
	v_mfma_f32_16x16x32_bf16 v[40:43], v[212:215], v[186:189], v[40:43]
	v_mfma_f32_16x16x32_bf16 v[36:39], v[236:239], v[178:181], v[36:39]
	v_mfma_f32_16x16x32_bf16 v[32:35], v[236:239], v[186:189], v[32:35]
	s_barrier
	v_add_u32_e32 v240, s82, v140
	s_add_i32 m0, s100, 0x14000
	v_add_u32_e32 v174, s82, v138
	global_load_lds_dwordx4 v240, s[86:87]
	s_nop 0
	s_add_i32 m0, s100, 0x16000
	s_nop 0
	global_load_lds_dwordx4 v174, s[86:87]
	s_waitcnt vmcnt(6)
	s_barrier
; #define P8_STAGE(P,BASE,br,kt) do{const bfr* _ub=(BASE)+((long)(br)*K+(long)(kt)*BK); \
;     __builtin_amdgcn_global_load_lds((const unsigned*)(_ub+so0),(unsigned*)((char*)(P)+wid*1024),16,0,0); \
;     __builtin_amdgcn_global_load_lds((const unsigned*)(_ub+so1),(unsigned*)((char*)(P)+wid*1024+8192),16,0,0);}while(0)
; #define P8_LDA(dst,b,h) _Pragma("unroll") for(int m=0;m<4;++m) _Pragma("unroll") for(int k=0;k<2;++k) \
;     dst[m][k]=*reinterpret_cast<const bf16x8*>((char*)P8_SA(b,h)+lds_byte(wr*64+m*16+fr,k*32+fq*8))
; #define P8_LDB(dst,b,h) _Pragma("unroll") for(int n=0;n<2;++n) _Pragma("unroll") for(int k=0;k<2;++k) \
;     dst[n][k]=*reinterpret_cast<const bf16x8*>((char*)P8_SB(b,h)+lds_byte(wc*32+n*16+fr,k*32+fq*8))
; #define P8_MMA(ai,bj,At,Bt) do{__builtin_amdgcn_s_setprio(1); \
;     _Pragma("unroll") for(int m=0;m<4;++m) _Pragma("unroll") for(int n=0;n<2;++n) _Pragma("unroll") for(int k=0;k<2;++k) \
;       acc[ai][bj][m][n]=__builtin_amdgcn_mfma_f32_16x16x32_bf16(At[m][k],Bt[n][k],acc[ai][bj][m][n],0,0,0); \
;     __builtin_amdgcn_s_setprio(0);}while(0)
; #define P8_WAIT_V(n) asm volatile("s_waitcnt vmcnt(" #n ")":::"memory")
; #define P8_WAIT_L(n) asm volatile("s_waitcnt lgkmcnt(" #n ")":::"memory")
; #define P8_BAR __builtin_amdgcn_s_barrier()
; #define P8_SCHED __builtin_amdgcn_sched_barrier(0)
; template <class EPI>
; DEVI void gemm8_tile(const bfr* __restrict__ A, const bfr* __restrict__ Bt, int K, int brow, int bcol, int nbrow, int nbcol, char* shmc, EPI epi) {
;     ...
;     P8_WAIT_V(6); P8_BAR; P8_MMA(1,1,At,B1); P8_BAR;
;     P8_LDB(B0,1,0); P8_SCHED; P8_LDA(At,1,0); P8_STAGE(P8_SA(0,1),A,brow+128,t+2);
;     P8_WAIT_L(8); P8_BAR; P8_WAIT_L(0); P8_MMA(0,0,At,B0); P8_BAR; P8_SCHED;
;     P8_LDB(B1,1,1); P8_STAGE(P8_SB(1,0),Bt,bcol,t+3);
;     P8_BAR; P8_WAIT_L(0); P8_MMA(0,1,At,B1); P8_BAR;
;     P8_LDA(At,1,1); P8_STAGE(P8_SA(1,0),A,brow,t+3);
;     P8_BAR; P8_WAIT_L(0); P8_MMA(1,0,At,B0); P8_BAR; P8_SCHED;
	v_mfma_f32_16x16x32_bf16 v[28:31], v[190:193], v[220:223], v[28:31]
	v_mfma_f32_16x16x32_bf16 v[24:27], v[190:193], v[228:231], v[24:27]
	v_mfma_f32_16x16x32_bf16 v[20:23], v[200:203], v[220:223], v[20:23]
	v_mfma_f32_16x16x32_bf16 v[16:19], v[200:203], v[228:231], v[16:19]
	v_mfma_f32_16x16x32_bf16 v[12:15], v[208:211], v[220:223], v[12:15]
	v_mfma_f32_16x16x32_bf16 v[8:11], v[208:211], v[228:231], v[8:11]
	v_mfma_f32_16x16x32_bf16 v[4:7], v[216:219], v[220:223], v[4:7]
	v_mfma_f32_16x16x32_bf16 v[0:3], v[216:219], v[228:231], v[0:3]
	v_mfma_f32_16x16x32_bf16 v[28:31], v[196:199], v[224:227], v[28:31]
	v_mfma_f32_16x16x32_bf16 v[24:27], v[196:199], v[232:235], v[24:27]
	v_mfma_f32_16x16x32_bf16 v[20:23], v[204:207], v[224:227], v[20:23]
	v_mfma_f32_16x16x32_bf16 v[16:19], v[204:207], v[232:235], v[16:19]
	v_mfma_f32_16x16x32_bf16 v[12:15], v[212:215], v[224:227], v[12:15]
	v_mfma_f32_16x16x32_bf16 v[8:11], v[212:215], v[232:235], v[8:11]
	v_mfma_f32_16x16x32_bf16 v[4:7], v[236:239], v[224:227], v[4:7]
	v_mfma_f32_16x16x32_bf16 v[0:3], v[236:239], v[232:235], v[0:3]
	s_barrier
	ds_read_b128 v[174:177], v149
	ds_read_b128 v[178:181], v149 offset:1024
	ds_read_b128 v[182:185], v149 offset:2048
	ds_read_b128 v[186:189], v149 offset:3072
	s_add_i32 m0, s100, 0x3f80
	ds_read_b128 v[190:193], v147 offset:32768
	ds_read_b128 v[196:199], v147 offset:33792
	ds_read_b128 v[200:203], v146 offset:32768
	ds_read_b128 v[204:207], v146 offset:33792
	ds_read_b128 v[208:211], v145 offset:32768
	ds_read_b128 v[212:215], v145 offset:33792
	ds_read_b128 v[216:219], v144 offset:32768
	ds_read_b128 v[220:223], v144 offset:33792
	global_load_lds_dwordx4 v171, s[86:87] offset:128
	s_add_i32 m0, s100, 0x5f80
	s_nop 0
	global_load_lds_dwordx4 v172, s[86:87] offset:128
	s_waitcnt lgkmcnt(8)
	s_barrier
	s_waitcnt lgkmcnt(0)
	v_mfma_f32_16x16x32_bf16 v[124:127], v[190:193], v[174:177], v[124:127]
	v_mfma_f32_16x16x32_bf16 v[120:123], v[190:193], v[182:185], v[120:123]
	v_mfma_f32_16x16x32_bf16 v[116:119], v[200:203], v[174:177], v[116:119]
	v_mfma_f32_16x16x32_bf16 v[112:115], v[200:203], v[182:185], v[112:115]
	v_mfma_f32_16x16x32_bf16 v[108:111], v[208:211], v[174:177], v[108:111]
	v_mfma_f32_16x16x32_bf16 v[104:107], v[208:211], v[182:185], v[104:107]
	v_mfma_f32_16x16x32_bf16 v[100:103], v[216:219], v[174:177], v[100:103]
	v_mfma_f32_16x16x32_bf16 v[96:99], v[216:219], v[182:185], v[96:99]
	v_mfma_f32_16x16x32_bf16 v[124:127], v[196:199], v[178:181], v[124:127]
	v_mfma_f32_16x16x32_bf16 v[120:123], v[196:199], v[186:189], v[120:123]
	v_mfma_f32_16x16x32_bf16 v[116:119], v[204:207], v[178:181], v[116:119]
	v_mfma_f32_16x16x32_bf16 v[112:115], v[204:207], v[186:189], v[112:115]
	v_mfma_f32_16x16x32_bf16 v[108:111], v[212:215], v[178:181], v[108:111]
	v_mfma_f32_16x16x32_bf16 v[104:107], v[212:215], v[186:189], v[104:107]
	v_mfma_f32_16x16x32_bf16 v[100:103], v[220:223], v[178:181], v[100:103]
	v_mfma_f32_16x16x32_bf16 v[96:99], v[220:223], v[186:189], v[96:99]
	s_barrier
	s_add_i32 m0, s100, 0x17f80
	ds_read_b128 v[224:227], v148
	ds_read_b128 v[228:231], v148 offset:1024
	ds_read_b128 v[232:235], v148 offset:2048
	ds_read_b128 v[236:239], v148 offset:3072
	global_load_lds_dwordx4 v158, s[86:87] offset:128
	s_add_i32 m0, s100, 0x19f80
	s_nop 0
	global_load_lds_dwordx4 v159, s[86:87] offset:128
	s_barrier
	s_waitcnt lgkmcnt(0)
	v_mfma_f32_16x16x32_bf16 v[92:95], v[190:193], v[224:227], v[92:95]
	v_mfma_f32_16x16x32_bf16 v[88:91], v[190:193], v[232:235], v[88:91]
	v_mfma_f32_16x16x32_bf16 v[84:87], v[200:203], v[224:227], v[84:87]
	v_mfma_f32_16x16x32_bf16 v[80:83], v[200:203], v[232:235], v[80:83]
	v_mfma_f32_16x16x32_bf16 v[76:79], v[208:211], v[224:227], v[76:79]
	v_mfma_f32_16x16x32_bf16 v[72:75], v[208:211], v[232:235], v[72:75]
	v_mfma_f32_16x16x32_bf16 v[68:71], v[216:219], v[224:227], v[68:71]
	v_mfma_f32_16x16x32_bf16 v[64:67], v[216:219], v[232:235], v[64:67]
	v_mfma_f32_16x16x32_bf16 v[92:95], v[196:199], v[228:231], v[92:95]
	v_mfma_f32_16x16x32_bf16 v[88:91], v[196:199], v[236:239], v[88:91]
	v_mfma_f32_16x16x32_bf16 v[84:87], v[204:207], v[228:231], v[84:87]
	v_mfma_f32_16x16x32_bf16 v[80:83], v[204:207], v[236:239], v[80:83]
	v_mfma_f32_16x16x32_bf16 v[76:79], v[212:215], v[228:231], v[76:79]
	v_mfma_f32_16x16x32_bf16 v[72:75], v[212:215], v[236:239], v[72:75]
	v_mfma_f32_16x16x32_bf16 v[68:71], v[220:223], v[228:231], v[68:71]
	v_mfma_f32_16x16x32_bf16 v[64:67], v[220:223], v[236:239], v[64:67]
	s_add_i32 m0, s100, 0x7f80
	s_barrier
	ds_read_b128 v[190:193], v147 offset:49152
	ds_read_b128 v[196:199], v147 offset:50176
	ds_read_b128 v[200:203], v146 offset:49152
	ds_read_b128 v[204:207], v146 offset:50176
	ds_read_b128 v[208:211], v145 offset:49152
	ds_read_b128 v[212:215], v145 offset:50176
	ds_read_b128 v[216:219], v144 offset:49152
	ds_read_b128 v[220:223], v144 offset:50176
	global_load_lds_dwordx4 v170, s[86:87] offset:128
	s_add_i32 m0, s100, 0x9f80
	s_nop 0
	global_load_lds_dwordx4 v248, s[86:87] offset:128
	s_barrier
	s_waitcnt lgkmcnt(0)
	v_mfma_f32_16x16x32_bf16 v[60:63], v[190:193], v[174:177], v[60:63]
	v_mfma_f32_16x16x32_bf16 v[56:59], v[190:193], v[182:185], v[56:59]
	v_mfma_f32_16x16x32_bf16 v[52:55], v[200:203], v[174:177], v[52:55]
	v_mfma_f32_16x16x32_bf16 v[48:51], v[200:203], v[182:185], v[48:51]
	v_mfma_f32_16x16x32_bf16 v[44:47], v[208:211], v[174:177], v[44:47]
	v_mfma_f32_16x16x32_bf16 v[40:43], v[208:211], v[182:185], v[40:43]
	v_mfma_f32_16x16x32_bf16 v[36:39], v[216:219], v[174:177], v[36:39]
	v_mfma_f32_16x16x32_bf16 v[32:35], v[216:219], v[182:185], v[32:35]
	v_mfma_f32_16x16x32_bf16 v[60:63], v[196:199], v[178:181], v[60:63]
	v_mfma_f32_16x16x32_bf16 v[56:59], v[196:199], v[186:189], v[56:59]
	v_mfma_f32_16x16x32_bf16 v[52:55], v[204:207], v[178:181], v[52:55]
	v_mfma_f32_16x16x32_bf16 v[48:51], v[204:207], v[186:189], v[48:51]
	v_mfma_f32_16x16x32_bf16 v[44:47], v[212:215], v[178:181], v[44:47]
	v_mfma_f32_16x16x32_bf16 v[40:43], v[212:215], v[186:189], v[40:43]
	v_mfma_f32_16x16x32_bf16 v[36:39], v[220:223], v[178:181], v[36:39]
	v_mfma_f32_16x16x32_bf16 v[32:35], v[220:223], v[186:189], v[32:35]
	s_barrier
; #define P8_STAGE(P,BASE,br,kt) do{const bfr* _ub=(BASE)+((long)(br)*K+(long)(kt)*BK); \
;     __builtin_amdgcn_global_load_lds((const unsigned*)(_ub+so0),(unsigned*)((char*)(P)+wid*1024),16,0,0); \
;     __builtin_amdgcn_global_load_lds((const unsigned*)(_ub+so1),(unsigned*)((char*)(P)+wid*1024+8192),16,0,0);}while(0)
; #define P8_LDA(dst,b,h) _Pragma("unroll") for(int m=0;m<4;++m) _Pragma("unroll") for(int k=0;k<2;++k) \
;     dst[m][k]=*reinterpret_cast<const bf16x8*>((char*)P8_SA(b,h)+lds_byte(wr*64+m*16+fr,k*32+fq*8))
; #define P8_LDB(dst,b,h) _Pragma("unroll") for(int n=0;n<2;++n) _Pragma("unroll") for(int k=0;k<2;++k) \
;     dst[n][k]=*reinterpret_cast<const bf16x8*>((char*)P8_SB(b,h)+lds_byte(wc*32+n*16+fr,k*32+fq*8))
; #define P8_MMA(ai,bj,At,Bt) do{__builtin_amdgcn_s_setprio(1); \
;     _Pragma("unroll") for(int m=0;m<4;++m) _Pragma("unroll") for(int n=0;n<2;++n) _Pragma("unroll") for(int k=0;k<2;++k) \
;       acc[ai][bj][m][n]=__builtin_amdgcn_mfma_f32_16x16x32_bf16(At[m][k],Bt[n][k],acc[ai][bj][m][n],0,0,0); \
;     __builtin_amdgcn_s_setprio(0);}while(0)
; #define P8_WAIT_V(n) asm volatile("s_waitcnt vmcnt(" #n ")":::"memory")
; #define P8_WAIT_L(n) asm volatile("s_waitcnt lgkmcnt(" #n ")":::"memory")
; #define P8_BAR __builtin_amdgcn_s_barrier()
; template <class EPI>
; DEVI void gemm8_tile(const bfr* __restrict__ A, const bfr* __restrict__ Bt, int K, int brow, int bcol, int nbrow, int nbcol, char* shmc, EPI epi) {
;     ...
;     P8_STAGE(P8_SB(1,1),Bt,bcol+128,t+3);
;     P8_WAIT_V(6); P8_BAR; P8_MMA(1,1,At,B1); P8_BAR;
;   }
;   { P8_LDB(B0,0,0); P8_LDA(At,0,0); P8_STAGE(P8_SA(1,1),A,brow+128,nt-1);
;     P8_BAR; P8_WAIT_L(0); P8_MMA(0,0,At,B0); P8_BAR;
;     P8_LDB(B1,0,1); P8_BAR; P8_WAIT_L(0); P8_MMA(0,1,At,B1); P8_BAR;
	s_add_i32 m0, s100, 0x1bf80
	s_nop 0
	global_load_lds_dwordx4 v240, s[86:87] offset:128
	v_add_u32_e32 v174, s96, v138
	s_add_i32 m0, s100, 0x1e000
	s_nop 0
	global_load_lds_dwordx4 v174, s[86:87]
	s_waitcnt vmcnt(6)
	s_barrier
	v_mfma_f32_16x16x32_bf16 v[28:31], v[190:193], v[224:227], v[28:31]
	v_mfma_f32_16x16x32_bf16 v[24:27], v[190:193], v[232:235], v[24:27]
	v_mfma_f32_16x16x32_bf16 v[20:23], v[200:203], v[224:227], v[20:23]
	v_mfma_f32_16x16x32_bf16 v[16:19], v[200:203], v[232:235], v[16:19]
	v_mfma_f32_16x16x32_bf16 v[12:15], v[208:211], v[224:227], v[12:15]
	v_mfma_f32_16x16x32_bf16 v[8:11], v[208:211], v[232:235], v[8:11]
	v_mfma_f32_16x16x32_bf16 v[4:7], v[216:219], v[224:227], v[4:7]
	v_mfma_f32_16x16x32_bf16 v[0:3], v[216:219], v[232:235], v[0:3]
	v_mfma_f32_16x16x32_bf16 v[28:31], v[196:199], v[228:231], v[28:31]
	v_mfma_f32_16x16x32_bf16 v[24:27], v[196:199], v[236:239], v[24:27]
	v_mfma_f32_16x16x32_bf16 v[20:23], v[204:207], v[228:231], v[20:23]
	v_mfma_f32_16x16x32_bf16 v[16:19], v[204:207], v[236:239], v[16:19]
	v_mfma_f32_16x16x32_bf16 v[12:15], v[212:215], v[228:231], v[12:15]
	v_mfma_f32_16x16x32_bf16 v[8:11], v[212:215], v[236:239], v[8:11]
	v_mfma_f32_16x16x32_bf16 v[4:7], v[220:223], v[228:231], v[4:7]
	v_mfma_f32_16x16x32_bf16 v[0:3], v[220:223], v[236:239], v[0:3]
	s_add_i32 s0, s0, 2
	v_lshl_add_u64 v[134:135], v[134:135], 0, s[80:81]
	v_lshl_add_u64 v[136:137], v[136:137], 0, s[80:81]
	v_lshl_add_u64 v[138:139], v[138:139], 0, s[80:81]
	s_cmp_lt_u32 s0, 4
	v_lshl_add_u64 v[140:141], v[140:141], 0, s[80:81]
	s_barrier
	s_cbranch_scc1 .LBB0_175
	v_add_u32_e32 v171, 0xc000, v143
	v_add_u32_e32 v172, 0xe000, v143
	v_add_u32_e32 v158, 0x10000, v143
	v_add_u32_e32 v159, 0x12000, v143
	v_add_u32_e32 v160, 0x2000, v143
	v_add_u32_e32 v161, 0x14000, v143
	v_add_u32_e32 v162, 0x16000, v143
	v_add_u32_e32 v163, 0x4000, v143
	v_add_u32_e32 v170, 0x6000, v143
	s_or_b32 s0, s34, 0x80
	s_ashr_i32 s1, s0, 31
	s_lshl_b64 s[0:1], s[0:1], 10
	s_add_u32 s0, s29, s0
	s_addc_u32 s1, s64, s1
	ds_read_b128 v[134:137], v157
	ds_read_b128 v[138:141], v157 offset:1024
	ds_read_b128 v[150:153], v157 offset:2048
	ds_read_b128 v[174:177], v157 offset:3072
	ds_read_b128 v[178:181], v147
	ds_read_b128 v[182:185], v147 offset:1024
	ds_read_b128 v[186:189], v146
	ds_read_b128 v[190:193], v146 offset:1024
	ds_read_b128 v[196:199], v145
	ds_read_b128 v[200:203], v145 offset:1024
	ds_read_b128 v[204:207], v144
	ds_read_b128 v[208:211], v144 offset:1024
	v_lshl_add_u64 v[156:157], v[166:167], 1, s[0:1]
	s_mov_b64 s[34:35], 0x380
	v_lshl_add_u64 v[156:157], v[156:157], 0, s[34:35]
	s_add_i32 m0, s100, 0xc000
	v_lshl_add_u64 v[132:133], v[132:133], 1, s[0:1]
	global_load_lds_dwordx4 v[156:157], off
	v_lshl_add_u64 v[132:133], v[132:133], 0, s[34:35]
	s_add_i32 m0, s100, 0xe000
	s_nop 0
	global_load_lds_dwordx4 v[132:133], off
	s_barrier
	s_waitcnt lgkmcnt(0)
	s_setprio 1
	s_waitcnt lgkmcnt(0)
	v_mfma_f32_16x16x32_bf16 v[124:127], v[178:181], v[134:137], v[124:127]
	v_mfma_f32_16x16x32_bf16 v[120:123], v[178:181], v[150:153], v[120:123]
	v_mfma_f32_16x16x32_bf16 v[116:119], v[186:189], v[134:137], v[116:119]
	v_mfma_f32_16x16x32_bf16 v[108:111], v[196:199], v[134:137], v[108:111]
	v_mfma_f32_16x16x32_bf16 v[124:127], v[182:185], v[138:141], v[124:127]
	v_mfma_f32_16x16x32_bf16 v[120:123], v[182:185], v[174:177], v[120:123]
	v_mfma_f32_16x16x32_bf16 v[116:119], v[190:193], v[138:141], v[116:119]
	v_mfma_f32_16x16x32_bf16 v[112:115], v[186:189], v[150:153], v[112:115]
	v_mfma_f32_16x16x32_bf16 v[108:111], v[200:203], v[138:141], v[108:111]
	v_mfma_f32_16x16x32_bf16 v[104:107], v[196:199], v[150:153], v[104:107]
	v_mfma_f32_16x16x32_bf16 v[100:103], v[204:207], v[134:137], v[100:103]
	v_mfma_f32_16x16x32_bf16 v[96:99], v[204:207], v[150:153], v[96:99]
	v_mfma_f32_16x16x32_bf16 v[212:215], v[190:193], v[174:177], v[112:115]
	v_mfma_f32_16x16x32_bf16 v[104:107], v[200:203], v[174:177], v[104:107]
	v_mfma_f32_16x16x32_bf16 v[216:219], v[208:211], v[138:141], v[100:103]
	v_mfma_f32_16x16x32_bf16 v[220:223], v[208:211], v[174:177], v[96:99]
	s_setprio 0
	s_barrier
	s_nop 1
	ds_read_b128 v[96:99], v154
	ds_read_b128 v[100:103], v154 offset:1024
	ds_read_b128 v[112:115], v154 offset:2048
	ds_read_b128 v[154:157], v154 offset:3072
	s_barrier
	s_waitcnt lgkmcnt(0)
	s_setprio 1
	s_waitcnt lgkmcnt(0)
	v_mfma_f32_16x16x32_bf16 v[88:91], v[178:181], v[112:115], v[88:91]
	v_mfma_f32_16x16x32_bf16 v[84:87], v[186:189], v[96:99], v[84:87]
	v_mfma_f32_16x16x32_bf16 v[76:79], v[196:199], v[96:99], v[76:79]
	v_mfma_f32_16x16x32_bf16 v[72:75], v[196:199], v[112:115], v[72:75]
	v_mfma_f32_16x16x32_bf16 v[92:95], v[178:181], v[96:99], v[92:95]
	v_mfma_f32_16x16x32_bf16 v[88:91], v[182:185], v[154:157], v[88:91]
	v_mfma_f32_16x16x32_bf16 v[84:87], v[190:193], v[100:103], v[84:87]
	v_mfma_f32_16x16x32_bf16 v[80:83], v[186:189], v[112:115], v[80:83]
	v_mfma_f32_16x16x32_bf16 v[76:79], v[200:203], v[100:103], v[76:79]
	v_mfma_f32_16x16x32_bf16 v[72:75], v[200:203], v[154:157], v[72:75]
	v_mfma_f32_16x16x32_bf16 v[68:71], v[204:207], v[96:99], v[68:71]
	v_mfma_f32_16x16x32_bf16 v[64:67], v[204:207], v[112:115], v[64:67]
	v_mfma_f32_16x16x32_bf16 v[224:227], v[182:185], v[100:103], v[92:95]
	v_mfma_f32_16x16x32_bf16 v[178:181], v[190:193], v[154:157], v[80:83]
	v_mfma_f32_16x16x32_bf16 v[182:185], v[208:211], v[100:103], v[68:71]
	v_mfma_f32_16x16x32_bf16 v[186:189], v[208:211], v[154:157], v[64:67]
	s_setprio 0
	s_barrier
; #define P8_LDA(dst,b,h) _Pragma("unroll") for(int m=0;m<4;++m) _Pragma("unroll") for(int k=0;k<2;++k) \
;     dst[m][k]=*reinterpret_cast<const bf16x8*>((char*)P8_SA(b,h)+lds_byte(wr*64+m*16+fr,k*32+fq*8))
; #define P8_LDB(dst,b,h) _Pragma("unroll") for(int n=0;n<2;++n) _Pragma("unroll") for(int k=0;k<2;++k) \
;     dst[n][k]=*reinterpret_cast<const bf16x8*>((char*)P8_SB(b,h)+lds_byte(wc*32+n*16+fr,k*32+fq*8))
; #define P8_MMA(ai,bj,At,Bt) do{__builtin_amdgcn_s_setprio(1); \
;     _Pragma("unroll") for(int m=0;m<4;++m) _Pragma("unroll") for(int n=0;n<2;++n) _Pragma("unroll") for(int k=0;k<2;++k) \
;       acc[ai][bj][m][n]=__builtin_amdgcn_mfma_f32_16x16x32_bf16(At[m][k],Bt[n][k],acc[ai][bj][m][n],0,0,0); \
;     __builtin_amdgcn_s_setprio(0);}while(0)
; #define P8_WAIT_V(n) asm volatile("s_waitcnt vmcnt(" #n ")":::"memory")
; #define P8_WAIT_L(n) asm volatile("s_waitcnt lgkmcnt(" #n ")":::"memory")
; #define P8_BAR __builtin_amdgcn_s_barrier()
; template <class EPI>
; DEVI void gemm8_tile(const bfr* __restrict__ A, const bfr* __restrict__ Bt, int K, int brow, int bcol, int nbrow, int nbcol, char* shmc, EPI epi) {
;     ...
;     P8_LDA(At,0,1); P8_WAIT_V(4); P8_BAR; P8_WAIT_L(0); P8_MMA(1,0,At,B0); P8_MMA(1,1,At,B1); P8_BAR; }
;   { P8_LDB(B0,1,0); P8_LDA(At,1,0); P8_WAIT_V(2); P8_BAR; P8_WAIT_L(0); P8_MMA(0,0,At,B0); P8_BAR;
	s_nop 1
	ds_read_b128 v[64:67], v147 offset:16384
	ds_read_b128 v[68:71], v147 offset:17408
	ds_read_b128 v[80:83], v146 offset:16384
	ds_read_b128 v[92:95], v146 offset:17408
	ds_read_b128 v[190:193], v145 offset:16384
	ds_read_b128 v[196:199], v145 offset:17408
	ds_read_b128 v[200:203], v144 offset:16384
	ds_read_b128 v[204:207], v144 offset:17408
	s_waitcnt vmcnt(4)
	s_barrier
	s_waitcnt lgkmcnt(0)
	s_setprio 1
	s_waitcnt lgkmcnt(0)
	v_mfma_f32_16x16x32_bf16 v[60:63], v[64:67], v[134:137], v[60:63]
	v_mfma_f32_16x16x32_bf16 v[56:59], v[64:67], v[150:153], v[56:59]
	v_mfma_f32_16x16x32_bf16 v[52:55], v[80:83], v[134:137], v[52:55]
	v_mfma_f32_16x16x32_bf16 v[40:43], v[190:193], v[150:153], v[40:43]
	v_mfma_f32_16x16x32_bf16 v[36:39], v[200:203], v[134:137], v[36:39]
	v_mfma_f32_16x16x32_bf16 v[208:211], v[68:71], v[138:141], v[60:63]
	v_mfma_f32_16x16x32_bf16 v[56:59], v[68:71], v[174:177], v[56:59]
	v_mfma_f32_16x16x32_bf16 v[52:55], v[92:95], v[138:141], v[52:55]
	v_mfma_f32_16x16x32_bf16 v[48:51], v[80:83], v[150:153], v[48:51]
	v_mfma_f32_16x16x32_bf16 v[44:47], v[190:193], v[134:137], v[44:47]
	v_mfma_f32_16x16x32_bf16 v[40:43], v[196:199], v[174:177], v[40:43]
	v_mfma_f32_16x16x32_bf16 v[36:39], v[204:207], v[138:141], v[36:39]
	v_mfma_f32_16x16x32_bf16 v[32:35], v[200:203], v[150:153], v[32:35]
	v_mfma_f32_16x16x32_bf16 v[228:231], v[92:95], v[174:177], v[48:51]
	v_mfma_f32_16x16x32_bf16 v[232:235], v[196:199], v[138:141], v[44:47]
	v_mfma_f32_16x16x32_bf16 v[132:135], v[204:207], v[174:177], v[32:35]
	s_setprio 0
	s_setprio 1
	v_mfma_f32_16x16x32_bf16 v[24:27], v[64:67], v[112:115], v[24:27]
	v_mfma_f32_16x16x32_bf16 v[20:23], v[80:83], v[96:99], v[20:23]
	v_mfma_f32_16x16x32_bf16 v[8:11], v[190:193], v[112:115], v[8:11]
	v_mfma_f32_16x16x32_bf16 v[28:31], v[64:67], v[96:99], v[28:31]
	v_mfma_f32_16x16x32_bf16 v[24:27], v[68:71], v[154:157], v[24:27]
	v_mfma_f32_16x16x32_bf16 v[20:23], v[92:95], v[100:103], v[20:23]
	v_mfma_f32_16x16x32_bf16 v[16:19], v[80:83], v[112:115], v[16:19]
	v_mfma_f32_16x16x32_bf16 v[12:15], v[190:193], v[96:99], v[12:15]
	v_mfma_f32_16x16x32_bf16 v[8:11], v[196:199], v[154:157], v[8:11]
	v_mfma_f32_16x16x32_bf16 v[4:7], v[200:203], v[96:99], v[4:7]
	v_mfma_f32_16x16x32_bf16 v[0:3], v[200:203], v[112:115], v[0:3]
	v_mfma_f32_16x16x32_bf16 v[136:139], v[68:71], v[100:103], v[28:31]
	v_mfma_f32_16x16x32_bf16 v[150:153], v[92:95], v[154:157], v[16:19]
	v_mfma_f32_16x16x32_bf16 v[172:175], v[196:199], v[100:103], v[12:15]
	v_mfma_f32_16x16x32_bf16 v[190:193], v[204:207], v[100:103], v[4:7]
	v_mfma_f32_16x16x32_bf16 v[154:157], v[204:207], v[154:157], v[0:3]
	s_setprio 0
	s_barrier
	ds_read_b128 v[4:7], v149
	ds_read_b128 v[196:199], v149 offset:1024
	ds_read_b128 v[200:203], v149 offset:2048
	ds_read_b128 v[204:207], v149 offset:3072
	ds_read_b128 v[0:3], v147 offset:32768
	ds_read_b128 v[12:15], v147 offset:33792
	ds_read_b128 v[16:19], v146 offset:32768
	ds_read_b128 v[32:35], v146 offset:33792
	ds_read_b128 v[236:239], v145 offset:32768
	ds_read_b128 v[240:243], v145 offset:33792
	ds_read_b128 v[244:247], v144 offset:32768
	ds_read_b128 v[248:251], v144 offset:33792
	s_waitcnt vmcnt(2)
	s_barrier
	s_waitcnt lgkmcnt(0)
	s_setprio 1
	s_waitcnt lgkmcnt(0)
	v_mfma_f32_16x16x32_bf16 v[28:31], v[0:3], v[4:7], v[124:127]
	v_mfma_f32_16x16x32_bf16 v[124:127], v[12:15], v[196:199], v[28:31]
	v_mfma_f32_16x16x32_bf16 v[28:31], v[0:3], v[200:203], v[120:123]
	v_mfma_f32_16x16x32_bf16 v[92:95], v[12:15], v[204:207], v[28:31]
	v_mfma_f32_16x16x32_bf16 v[28:31], v[16:19], v[4:7], v[116:119]
	v_mfma_f32_16x16x32_bf16 v[112:115], v[32:35], v[196:199], v[28:31]
	v_mfma_f32_16x16x32_bf16 v[28:31], v[16:19], v[200:203], v[212:215]
	v_mfma_f32_16x16x32_bf16 v[80:83], v[32:35], v[204:207], v[28:31]
	v_mfma_f32_16x16x32_bf16 v[28:31], v[236:239], v[4:7], v[108:111]
	v_mfma_f32_16x16x32_bf16 v[100:103], v[240:243], v[196:199], v[28:31]
	v_mfma_f32_16x16x32_bf16 v[28:31], v[236:239], v[200:203], v[104:107]
	v_mfma_f32_16x16x32_bf16 v[68:71], v[240:243], v[204:207], v[28:31]
	v_mfma_f32_16x16x32_bf16 v[28:31], v[244:247], v[4:7], v[216:219]
	v_mfma_f32_16x16x32_bf16 v[96:99], v[248:251], v[196:199], v[28:31]
	v_mfma_f32_16x16x32_bf16 v[28:31], v[244:247], v[200:203], v[220:223]
	v_mfma_f32_16x16x32_bf16 v[64:67], v[248:251], v[204:207], v[28:31]
	s_setprio 0
	s_barrier
; #define P8_LDA(dst,b,h) _Pragma("unroll") for(int m=0;m<4;++m) _Pragma("unroll") for(int k=0;k<2;++k) \
;     dst[m][k]=*reinterpret_cast<const bf16x8*>((char*)P8_SA(b,h)+lds_byte(wr*64+m*16+fr,k*32+fq*8))
; #define P8_LDB(dst,b,h) _Pragma("unroll") for(int n=0;n<2;++n) _Pragma("unroll") for(int k=0;k<2;++k) \
;     dst[n][k]=*reinterpret_cast<const bf16x8*>((char*)P8_SB(b,h)+lds_byte(wc*32+n*16+fr,k*32+fq*8))
; #define P8_MMA(ai,bj,At,Bt) do{__builtin_amdgcn_s_setprio(1); \
;     _Pragma("unroll") for(int m=0;m<4;++m) _Pragma("unroll") for(int n=0;n<2;++n) _Pragma("unroll") for(int k=0;k<2;++k) \
;       acc[ai][bj][m][n]=__builtin_amdgcn_mfma_f32_16x16x32_bf16(At[m][k],Bt[n][k],acc[ai][bj][m][n],0,0,0); \
;     __builtin_amdgcn_s_setprio(0);}while(0)
; #define P8_WAIT_V(n) asm volatile("s_waitcnt vmcnt(" #n ")":::"memory")
; #define P8_WAIT_L(n) asm volatile("s_waitcnt lgkmcnt(" #n ")":::"memory")
; #define P8_BAR __builtin_amdgcn_s_barrier()
; template <class EPI>
; DEVI void gemm8_tile(const bfr* __restrict__ A, const bfr* __restrict__ Bt, int K, int brow, int bcol, int nbrow, int nbcol, char* shmc, EPI epi) {
;     ...
;     P8_LDB(B1,1,1); P8_WAIT_V(0); P8_BAR; P8_WAIT_L(0); P8_MMA(0,1,At,B1); P8_BAR;
;     P8_LDA(At,1,1); P8_BAR; P8_WAIT_L(0); P8_MMA(1,0,At,B0); P8_MMA(1,1,At,B1); P8_BAR; }
;   if(wr==0)P8_BAR;
	ds_read_b128 v[212:215], v148
	ds_read_b128 v[216:219], v148 offset:1024
	ds_read_b128 v[220:223], v148 offset:2048
	ds_read_b128 v[104:107], v148 offset:3072
	s_waitcnt vmcnt(0)
	s_barrier
	s_waitcnt lgkmcnt(0)
	s_setprio 1
	s_waitcnt lgkmcnt(0)
	v_mfma_f32_16x16x32_bf16 v[28:31], v[0:3], v[212:215], v[224:227]
	v_mfma_f32_16x16x32_bf16 v[0:3], v[0:3], v[220:223], v[88:91]
	v_mfma_f32_16x16x32_bf16 v[60:63], v[12:15], v[216:219], v[28:31]
	v_mfma_f32_16x16x32_bf16 v[28:31], v[12:15], v[104:107], v[0:3]
	v_mfma_f32_16x16x32_bf16 v[0:3], v[16:19], v[212:215], v[84:87]
	v_mfma_f32_16x16x32_bf16 v[48:51], v[32:35], v[216:219], v[0:3]
	v_mfma_f32_16x16x32_bf16 v[0:3], v[16:19], v[220:223], v[178:181]
	v_mfma_f32_16x16x32_bf16 v[16:19], v[32:35], v[104:107], v[0:3]
	v_mfma_f32_16x16x32_bf16 v[0:3], v[236:239], v[212:215], v[76:79]
	v_mfma_f32_16x16x32_bf16 v[44:47], v[240:243], v[216:219], v[0:3]
	v_mfma_f32_16x16x32_bf16 v[0:3], v[236:239], v[220:223], v[72:75]
	v_mfma_f32_16x16x32_bf16 v[12:15], v[240:243], v[104:107], v[0:3]
	v_mfma_f32_16x16x32_bf16 v[0:3], v[244:247], v[212:215], v[182:185]
	v_mfma_f32_16x16x32_bf16 v[32:35], v[248:251], v[216:219], v[0:3]
	v_mfma_f32_16x16x32_bf16 v[0:3], v[244:247], v[220:223], v[186:189]
	v_mfma_f32_16x16x32_bf16 v[0:3], v[248:251], v[104:107], v[0:3]
	s_setprio 0
	s_barrier
	ds_read_b128 v[176:179], v147 offset:49152
	ds_read_b128 v[180:183], v147 offset:50176
	ds_read_b128 v[184:187], v146 offset:49152
	ds_read_b128 v[146:149], v146 offset:50176
	ds_read_b128 v[224:227], v145 offset:49152
	ds_read_b128 v[236:239], v145 offset:50176
	ds_read_b128 v[240:243], v144 offset:49152
	ds_read_b128 v[244:247], v144 offset:50176
	s_barrier
	s_waitcnt lgkmcnt(0)
	s_setprio 1
	s_waitcnt lgkmcnt(0)
	v_mfma_f32_16x16x32_bf16 v[52:55], v[184:187], v[4:7], v[52:55]
	v_mfma_f32_16x16x32_bf16 v[116:119], v[146:149], v[196:199], v[52:55]
	v_mfma_f32_16x16x32_bf16 v[52:55], v[184:187], v[200:203], v[228:231]
	v_mfma_f32_16x16x32_bf16 v[72:75], v[176:179], v[4:7], v[208:211]
	v_mfma_f32_16x16x32_bf16 v[84:87], v[146:149], v[204:207], v[52:55]
	v_mfma_f32_16x16x32_bf16 v[52:55], v[224:227], v[4:7], v[232:235]
	v_mfma_f32_16x16x32_bf16 v[4:7], v[240:243], v[4:7], v[36:39]
	v_mfma_f32_16x16x32_bf16 v[56:59], v[176:179], v[200:203], v[56:59]
	v_mfma_f32_16x16x32_bf16 v[40:43], v[224:227], v[200:203], v[40:43]
	v_mfma_f32_16x16x32_bf16 v[108:111], v[244:247], v[196:199], v[4:7]
	v_mfma_f32_16x16x32_bf16 v[4:7], v[240:243], v[200:203], v[132:135]
	v_mfma_f32_16x16x32_bf16 v[120:123], v[180:183], v[196:199], v[72:75]
	v_mfma_f32_16x16x32_bf16 v[88:91], v[180:183], v[204:207], v[56:59]
	v_mfma_f32_16x16x32_bf16 v[208:211], v[236:239], v[196:199], v[52:55]
	v_mfma_f32_16x16x32_bf16 v[72:75], v[236:239], v[204:207], v[40:43]
	v_mfma_f32_16x16x32_bf16 v[76:79], v[244:247], v[204:207], v[4:7]
	s_setprio 0
	s_setprio 1
	v_mfma_f32_16x16x32_bf16 v[4:7], v[176:179], v[212:215], v[136:139]
	v_mfma_f32_16x16x32_bf16 v[56:59], v[180:183], v[216:219], v[4:7]
	v_mfma_f32_16x16x32_bf16 v[4:7], v[176:179], v[220:223], v[24:27]
	v_mfma_f32_16x16x32_bf16 v[24:27], v[180:183], v[104:107], v[4:7]
	v_mfma_f32_16x16x32_bf16 v[4:7], v[184:187], v[212:215], v[20:23]
	v_mfma_f32_16x16x32_bf16 v[52:55], v[146:149], v[216:219], v[4:7]
	v_mfma_f32_16x16x32_bf16 v[4:7], v[184:187], v[220:223], v[150:153]
	v_mfma_f32_16x16x32_bf16 v[20:23], v[146:149], v[104:107], v[4:7]
	v_mfma_f32_16x16x32_bf16 v[4:7], v[224:227], v[212:215], v[172:175]
	v_mfma_f32_16x16x32_bf16 v[36:39], v[236:239], v[216:219], v[4:7]
	v_mfma_f32_16x16x32_bf16 v[4:7], v[224:227], v[220:223], v[8:11]
	v_mfma_f32_16x16x32_bf16 v[8:11], v[240:243], v[212:215], v[190:193]
	v_mfma_f32_16x16x32_bf16 v[40:43], v[244:247], v[216:219], v[8:11]
	v_mfma_f32_16x16x32_bf16 v[8:11], v[240:243], v[220:223], v[154:157]
	v_mfma_f32_16x16x32_bf16 v[4:7], v[236:239], v[104:107], v[4:7]
	v_mfma_f32_16x16x32_bf16 v[8:11], v[244:247], v[104:107], v[8:11]
	s_setprio 0
	v_cmp_gt_u32_e32 vcc, s57, v142
	s_barrier
	s_and_saveexec_b64 s[0:1], vcc
	s_cbranch_execz .LBB0_178
	s_barrier

; #define P8_STAGE(P,BASE,br,kt) do{const bfr* _ub=(BASE)+((long)(br)*K+(long)(kt)*BK); \
;     __builtin_amdgcn_global_load_lds((const unsigned*)(_ub+so0),(unsigned*)((char*)(P)+wid*1024),16,0,0); \
;     __builtin_amdgcn_global_load_lds((const unsigned*)(_ub+so1),(unsigned*)((char*)(P)+wid*1024+8192),16,0,0);}while(0)
; #define P8_LDA(dst,b,h) _Pragma("unroll") for(int m=0;m<4;++m) _Pragma("unroll") for(int k=0;k<2;++k) \
;     dst[m][k]=*reinterpret_cast<const bf16x8*>((char*)P8_SA(b,h)+lds_byte(wr*64+m*16+fr,k*32+fq*8))
; #define P8_LDB(dst,b,h) _Pragma("unroll") for(int n=0;n<2;++n) _Pragma("unroll") for(int k=0;k<2;++k) \
;     dst[n][k]=*reinterpret_cast<const bf16x8*>((char*)P8_SB(b,h)+lds_byte(wc*32+n*16+fr,k*32+fq*8))
; #define P8_MMA(ai,bj,At,Bt) do{__builtin_amdgcn_s_setprio(1); \
;     _Pragma("unroll") for(int m=0;m<4;++m) _Pragma("unroll") for(int n=0;n<2;++n) _Pragma("unroll") for(int k=0;k<2;++k) \
;       acc[ai][bj][m][n]=__builtin_amdgcn_mfma_f32_16x16x32_bf16(At[m][k],Bt[n][k],acc[ai][bj][m][n],0,0,0); \
;     __builtin_amdgcn_s_setprio(0);}while(0)
; #define P8_WAIT_V(n) asm volatile("s_waitcnt vmcnt(" #n ")":::"memory")
; #define P8_WAIT_L(n) asm volatile("s_waitcnt lgkmcnt(" #n ")":::"memory")
; #define P8_BAR __builtin_amdgcn_s_barrier()
; #define P8_SCHED __builtin_amdgcn_sched_barrier(0)
; template <class EPI>
; DEVI void gemm8_tile(const bfr* __restrict__ A, const bfr* __restrict__ Bt, int K, int brow, int bcol, int nbrow, int nbcol, char* shmc, EPI epi) {
;     ...
;     P8_LDB(B0,0,0); P8_SCHED; P8_LDA(At,0,0); P8_STAGE(P8_SA(1,1),A,brow+128,t+1);
;     P8_WAIT_L(8); P8_BAR; P8_WAIT_L(0); P8_MMA(0,0,At,B0); P8_BAR; P8_SCHED;
;     P8_LDB(B1,0,1); P8_STAGE(P8_SB(0,0),Bt,bcol,t+2);
;     P8_BAR; P8_WAIT_L(0); P8_MMA(0,1,At,B1); P8_BAR;
;     P8_LDA(At,0,1); P8_STAGE(P8_SA(0,0),A,brow,t+2);
;     P8_BAR; P8_WAIT_L(0); P8_MMA(1,0,At,B0); P8_BAR; P8_SCHED;
;     P8_STAGE(P8_SB(0,1),Bt,bcol+128,t+2);
;     P8_WAIT_V(6); P8_BAR; P8_MMA(1,1,At,B1); P8_BAR;
.LBB0_221:
	ds_read_b128 v[174:177], v157
	ds_read_b128 v[178:181], v157 offset:1024
	ds_read_b128 v[182:185], v157 offset:2048
	ds_read_b128 v[186:189], v157 offset:3072
	v_add_u32_e32 v171, s54, v136
	s_add_i32 m0, s100, 0xc000
	ds_read_b128 v[160:163], v147
	ds_read_b128 v[190:193], v147 offset:1024
	ds_read_b128 v[196:199], v146
	ds_read_b128 v[208:211], v146 offset:1024
	ds_read_b128 v[212:215], v145
	ds_read_b128 v[216:219], v145 offset:1024
	ds_read_b128 v[220:223], v144
	ds_read_b128 v[224:227], v144 offset:1024
	global_load_lds_dwordx4 v171, s[86:87]
	v_add_u32_e32 v172, s54, v134
	s_add_i32 m0, s100, 0xe000
	s_nop 0
	global_load_lds_dwordx4 v172, s[86:87]
	s_waitcnt lgkmcnt(8)
	s_barrier
	s_waitcnt lgkmcnt(0)
	v_mfma_f32_16x16x32_bf16 v[124:127], v[160:163], v[174:177], v[124:127]
	v_mfma_f32_16x16x32_bf16 v[120:123], v[160:163], v[182:185], v[120:123]
	v_mfma_f32_16x16x32_bf16 v[116:119], v[196:199], v[174:177], v[116:119]
	v_mfma_f32_16x16x32_bf16 v[112:115], v[196:199], v[182:185], v[112:115]
	v_mfma_f32_16x16x32_bf16 v[108:111], v[212:215], v[174:177], v[108:111]
	v_mfma_f32_16x16x32_bf16 v[104:107], v[212:215], v[182:185], v[104:107]
	v_mfma_f32_16x16x32_bf16 v[100:103], v[220:223], v[174:177], v[100:103]
	v_mfma_f32_16x16x32_bf16 v[96:99], v[220:223], v[182:185], v[96:99]
	v_mfma_f32_16x16x32_bf16 v[124:127], v[190:193], v[178:181], v[124:127]
	v_mfma_f32_16x16x32_bf16 v[120:123], v[190:193], v[186:189], v[120:123]
	v_mfma_f32_16x16x32_bf16 v[116:119], v[208:211], v[178:181], v[116:119]
	v_mfma_f32_16x16x32_bf16 v[112:115], v[208:211], v[186:189], v[112:115]
	v_mfma_f32_16x16x32_bf16 v[108:111], v[216:219], v[178:181], v[108:111]
	v_mfma_f32_16x16x32_bf16 v[104:107], v[216:219], v[186:189], v[104:107]
	v_mfma_f32_16x16x32_bf16 v[100:103], v[224:227], v[178:181], v[100:103]
	v_mfma_f32_16x16x32_bf16 v[96:99], v[224:227], v[186:189], v[96:99]
	s_barrier
	v_add_u32_e32 v158, s66, v140
	s_add_i32 m0, s100, 0x10000
	ds_read_b128 v[228:231], v155
	ds_read_b128 v[232:235], v155 offset:1024
	ds_read_b128 v[236:239], v155 offset:2048
	ds_read_b128 v[240:243], v155 offset:3072
	global_load_lds_dwordx4 v158, s[86:87]
	v_add_u32_e32 v159, s66, v138
	s_add_i32 m0, s100, 0x12000
	s_nop 0
	global_load_lds_dwordx4 v159, s[86:87]
	s_barrier
	s_waitcnt lgkmcnt(0)
	v_mfma_f32_16x16x32_bf16 v[92:95], v[160:163], v[228:231], v[92:95]
	v_mfma_f32_16x16x32_bf16 v[88:91], v[160:163], v[236:239], v[88:91]
	v_mfma_f32_16x16x32_bf16 v[84:87], v[196:199], v[228:231], v[84:87]
	v_mfma_f32_16x16x32_bf16 v[80:83], v[196:199], v[236:239], v[80:83]
	v_mfma_f32_16x16x32_bf16 v[76:79], v[212:215], v[228:231], v[76:79]
	v_mfma_f32_16x16x32_bf16 v[72:75], v[212:215], v[236:239], v[72:75]
	v_mfma_f32_16x16x32_bf16 v[68:71], v[220:223], v[228:231], v[68:71]
	v_mfma_f32_16x16x32_bf16 v[64:67], v[220:223], v[236:239], v[64:67]
	v_mfma_f32_16x16x32_bf16 v[92:95], v[190:193], v[232:235], v[92:95]
	v_mfma_f32_16x16x32_bf16 v[88:91], v[190:193], v[240:243], v[88:91]
	v_mfma_f32_16x16x32_bf16 v[84:87], v[208:211], v[232:235], v[84:87]
	v_mfma_f32_16x16x32_bf16 v[80:83], v[208:211], v[240:243], v[80:83]
	v_mfma_f32_16x16x32_bf16 v[76:79], v[216:219], v[232:235], v[76:79]
	v_mfma_f32_16x16x32_bf16 v[72:75], v[216:219], v[240:243], v[72:75]
	v_mfma_f32_16x16x32_bf16 v[68:71], v[224:227], v[232:235], v[68:71]
	v_mfma_f32_16x16x32_bf16 v[64:67], v[224:227], v[240:243], v[64:67]
	v_add_u32_e32 v170, s80, v136
	s_mov_b32 m0, s100
	s_barrier
	ds_read_b128 v[190:193], v147 offset:16384
	ds_read_b128 v[196:199], v147 offset:17408
	ds_read_b128 v[208:211], v146 offset:16384
	ds_read_b128 v[212:215], v146 offset:17408
	ds_read_b128 v[216:219], v145 offset:16384
	ds_read_b128 v[220:223], v145 offset:17408
	ds_read_b128 v[224:227], v144 offset:16384
	ds_read_b128 v[244:247], v144 offset:17408
	global_load_lds_dwordx4 v170, s[86:87]
	v_add_u32_e32 v206, s80, v134
	s_add_i32 m0, s100, 0x2000
	s_nop 0
	global_load_lds_dwordx4 v206, s[86:87]
	s_barrier
	s_waitcnt lgkmcnt(0)
	v_mfma_f32_16x16x32_bf16 v[60:63], v[190:193], v[174:177], v[60:63]
	v_mfma_f32_16x16x32_bf16 v[56:59], v[190:193], v[182:185], v[56:59]
	v_mfma_f32_16x16x32_bf16 v[52:55], v[208:211], v[174:177], v[52:55]
	v_mfma_f32_16x16x32_bf16 v[48:51], v[208:211], v[182:185], v[48:51]
	v_mfma_f32_16x16x32_bf16 v[44:47], v[216:219], v[174:177], v[44:47]
	v_mfma_f32_16x16x32_bf16 v[40:43], v[216:219], v[182:185], v[40:43]
	v_mfma_f32_16x16x32_bf16 v[36:39], v[224:227], v[174:177], v[36:39]
	v_mfma_f32_16x16x32_bf16 v[32:35], v[224:227], v[182:185], v[32:35]
	v_mfma_f32_16x16x32_bf16 v[60:63], v[196:199], v[178:181], v[60:63]
	v_mfma_f32_16x16x32_bf16 v[56:59], v[196:199], v[186:189], v[56:59]
	v_mfma_f32_16x16x32_bf16 v[52:55], v[212:215], v[178:181], v[52:55]
	v_mfma_f32_16x16x32_bf16 v[48:51], v[212:215], v[186:189], v[48:51]
	v_mfma_f32_16x16x32_bf16 v[44:47], v[220:223], v[178:181], v[44:47]
	v_mfma_f32_16x16x32_bf16 v[40:43], v[220:223], v[186:189], v[40:43]
	v_mfma_f32_16x16x32_bf16 v[36:39], v[244:247], v[178:181], v[36:39]
	v_mfma_f32_16x16x32_bf16 v[32:35], v[244:247], v[186:189], v[32:35]
	s_barrier
	v_add_u32_e32 v248, s70, v140
	s_add_i32 m0, s100, 0x14000
	v_add_u32_e32 v200, s70, v138
	global_load_lds_dwordx4 v248, s[86:87]
	s_nop 0
	s_add_i32 m0, s100, 0x16000
	s_nop 0
	global_load_lds_dwordx4 v200, s[86:87]
	s_waitcnt vmcnt(6)
	s_barrier
; #define P8_STAGE(P,BASE,br,kt) do{const bfr* _ub=(BASE)+((long)(br)*K+(long)(kt)*BK); \
;     __builtin_amdgcn_global_load_lds((const unsigned*)(_ub+so0),(unsigned*)((char*)(P)+wid*1024),16,0,0); \
;     __builtin_amdgcn_global_load_lds((const unsigned*)(_ub+so1),(unsigned*)((char*)(P)+wid*1024+8192),16,0,0);}while(0)
; #define P8_LDA(dst,b,h) _Pragma("unroll") for(int m=0;m<4;++m) _Pragma("unroll") for(int k=0;k<2;++k) \
;     dst[m][k]=*reinterpret_cast<const bf16x8*>((char*)P8_SA(b,h)+lds_byte(wr*64+m*16+fr,k*32+fq*8))
; #define P8_LDB(dst,b,h) _Pragma("unroll") for(int n=0;n<2;++n) _Pragma("unroll") for(int k=0;k<2;++k) \
;     dst[n][k]=*reinterpret_cast<const bf16x8*>((char*)P8_SB(b,h)+lds_byte(wc*32+n*16+fr,k*32+fq*8))
; #define P8_MMA(ai,bj,At,Bt) do{__builtin_amdgcn_s_setprio(1); \
;     _Pragma("unroll") for(int m=0;m<4;++m) _Pragma("unroll") for(int n=0;n<2;++n) _Pragma("unroll") for(int k=0;k<2;++k) \
;       acc[ai][bj][m][n]=__builtin_amdgcn_mfma_f32_16x16x32_bf16(At[m][k],Bt[n][k],acc[ai][bj][m][n],0,0,0); \
;     __builtin_amdgcn_s_setprio(0);}while(0)
; #define P8_WAIT_V(n) asm volatile("s_waitcnt vmcnt(" #n ")":::"memory")
; #define P8_WAIT_L(n) asm volatile("s_waitcnt lgkmcnt(" #n ")":::"memory")
; #define P8_BAR __builtin_amdgcn_s_barrier()
; #define P8_SCHED __builtin_amdgcn_sched_barrier(0)
; template <class EPI>
; DEVI void gemm8_tile(const bfr* __restrict__ A, const bfr* __restrict__ Bt, int K, int brow, int bcol, int nbrow, int nbcol, char* shmc, EPI epi) {
;     ...
;     P8_WAIT_V(6); P8_BAR; P8_MMA(1,1,At,B1); P8_BAR;
;     P8_LDB(B0,1,0); P8_SCHED; P8_LDA(At,1,0); P8_STAGE(P8_SA(0,1),A,brow+128,t+2);
;     P8_WAIT_L(8); P8_BAR; P8_WAIT_L(0); P8_MMA(0,0,At,B0); P8_BAR; P8_SCHED;
;     P8_LDB(B1,1,1); P8_STAGE(P8_SB(1,0),Bt,bcol,t+3);
;     P8_BAR; P8_WAIT_L(0); P8_MMA(0,1,At,B1); P8_BAR;
;     P8_LDA(At,1,1); P8_STAGE(P8_SA(1,0),A,brow,t+3);
;     P8_BAR; P8_WAIT_L(0); P8_MMA(1,0,At,B0); P8_BAR; P8_SCHED;
	v_mfma_f32_16x16x32_bf16 v[28:31], v[190:193], v[228:231], v[28:31]
	v_mfma_f32_16x16x32_bf16 v[24:27], v[190:193], v[236:239], v[24:27]
	v_mfma_f32_16x16x32_bf16 v[20:23], v[208:211], v[228:231], v[20:23]
	v_mfma_f32_16x16x32_bf16 v[16:19], v[208:211], v[236:239], v[16:19]
	v_mfma_f32_16x16x32_bf16 v[12:15], v[216:219], v[228:231], v[12:15]
	v_mfma_f32_16x16x32_bf16 v[8:11], v[216:219], v[236:239], v[8:11]
	v_mfma_f32_16x16x32_bf16 v[4:7], v[224:227], v[228:231], v[4:7]
	v_mfma_f32_16x16x32_bf16 v[0:3], v[224:227], v[236:239], v[0:3]
	v_mfma_f32_16x16x32_bf16 v[28:31], v[196:199], v[232:235], v[28:31]
	v_mfma_f32_16x16x32_bf16 v[24:27], v[196:199], v[240:243], v[24:27]
	v_mfma_f32_16x16x32_bf16 v[20:23], v[212:215], v[232:235], v[20:23]
	v_mfma_f32_16x16x32_bf16 v[16:19], v[212:215], v[240:243], v[16:19]
	v_mfma_f32_16x16x32_bf16 v[12:15], v[220:223], v[232:235], v[12:15]
	v_mfma_f32_16x16x32_bf16 v[8:11], v[220:223], v[240:243], v[8:11]
	v_mfma_f32_16x16x32_bf16 v[4:7], v[244:247], v[232:235], v[4:7]
	v_mfma_f32_16x16x32_bf16 v[0:3], v[244:247], v[240:243], v[0:3]
	s_barrier
	ds_read_b128 v[174:177], v149
	ds_read_b128 v[178:181], v149 offset:1024
	ds_read_b128 v[182:185], v149 offset:2048
	ds_read_b128 v[186:189], v149 offset:3072
	s_add_i32 m0, s100, 0x3f80
	ds_read_b128 v[190:193], v147 offset:32768
	ds_read_b128 v[196:199], v147 offset:33792
	ds_read_b128 v[208:211], v146 offset:32768
	ds_read_b128 v[212:215], v146 offset:33792
	ds_read_b128 v[216:219], v145 offset:32768
	ds_read_b128 v[220:223], v145 offset:33792
	ds_read_b128 v[224:227], v144 offset:32768
	ds_read_b128 v[228:231], v144 offset:33792
	global_load_lds_dwordx4 v171, s[86:87] offset:128
	s_add_i32 m0, s100, 0x5f80
	s_nop 0
	global_load_lds_dwordx4 v172, s[86:87] offset:128
	s_waitcnt lgkmcnt(8)
	s_barrier
	s_waitcnt lgkmcnt(0)
	v_mfma_f32_16x16x32_bf16 v[124:127], v[190:193], v[174:177], v[124:127]
	v_mfma_f32_16x16x32_bf16 v[120:123], v[190:193], v[182:185], v[120:123]
	v_mfma_f32_16x16x32_bf16 v[116:119], v[208:211], v[174:177], v[116:119]
	v_mfma_f32_16x16x32_bf16 v[112:115], v[208:211], v[182:185], v[112:115]
	v_mfma_f32_16x16x32_bf16 v[108:111], v[216:219], v[174:177], v[108:111]
	v_mfma_f32_16x16x32_bf16 v[104:107], v[216:219], v[182:185], v[104:107]
	v_mfma_f32_16x16x32_bf16 v[100:103], v[224:227], v[174:177], v[100:103]
	v_mfma_f32_16x16x32_bf16 v[96:99], v[224:227], v[182:185], v[96:99]
	v_mfma_f32_16x16x32_bf16 v[124:127], v[196:199], v[178:181], v[124:127]
	v_mfma_f32_16x16x32_bf16 v[120:123], v[196:199], v[186:189], v[120:123]
	v_mfma_f32_16x16x32_bf16 v[116:119], v[212:215], v[178:181], v[116:119]
	v_mfma_f32_16x16x32_bf16 v[112:115], v[212:215], v[186:189], v[112:115]
	v_mfma_f32_16x16x32_bf16 v[108:111], v[220:223], v[178:181], v[108:111]
	v_mfma_f32_16x16x32_bf16 v[104:107], v[220:223], v[186:189], v[104:107]
	v_mfma_f32_16x16x32_bf16 v[100:103], v[228:231], v[178:181], v[100:103]
	v_mfma_f32_16x16x32_bf16 v[96:99], v[228:231], v[186:189], v[96:99]
	s_barrier
	s_add_i32 m0, s100, 0x17f80
	ds_read_b128 v[232:235], v148
	ds_read_b128 v[236:239], v148 offset:1024
	ds_read_b128 v[240:243], v148 offset:2048
	ds_read_b128 v[244:247], v148 offset:3072
	global_load_lds_dwordx4 v158, s[86:87] offset:128
	s_add_i32 m0, s100, 0x19f80
	s_nop 0
	global_load_lds_dwordx4 v159, s[86:87] offset:128
	s_barrier
	s_waitcnt lgkmcnt(0)
	v_mfma_f32_16x16x32_bf16 v[92:95], v[190:193], v[232:235], v[92:95]
	v_mfma_f32_16x16x32_bf16 v[88:91], v[190:193], v[240:243], v[88:91]
	v_mfma_f32_16x16x32_bf16 v[84:87], v[208:211], v[232:235], v[84:87]
	v_mfma_f32_16x16x32_bf16 v[80:83], v[208:211], v[240:243], v[80:83]
	v_mfma_f32_16x16x32_bf16 v[76:79], v[216:219], v[232:235], v[76:79]
	v_mfma_f32_16x16x32_bf16 v[72:75], v[216:219], v[240:243], v[72:75]
	v_mfma_f32_16x16x32_bf16 v[68:71], v[224:227], v[232:235], v[68:71]
	v_mfma_f32_16x16x32_bf16 v[64:67], v[224:227], v[240:243], v[64:67]
	v_mfma_f32_16x16x32_bf16 v[92:95], v[196:199], v[236:239], v[92:95]
	v_mfma_f32_16x16x32_bf16 v[88:91], v[196:199], v[244:247], v[88:91]
	v_mfma_f32_16x16x32_bf16 v[84:87], v[212:215], v[236:239], v[84:87]
	v_mfma_f32_16x16x32_bf16 v[80:83], v[212:215], v[244:247], v[80:83]
	v_mfma_f32_16x16x32_bf16 v[76:79], v[220:223], v[236:239], v[76:79]
	v_mfma_f32_16x16x32_bf16 v[72:75], v[220:223], v[244:247], v[72:75]
	v_mfma_f32_16x16x32_bf16 v[68:71], v[228:231], v[236:239], v[68:71]
	v_mfma_f32_16x16x32_bf16 v[64:67], v[228:231], v[244:247], v[64:67]
	s_add_i32 m0, s100, 0x7f80
	s_barrier
	ds_read_b128 v[190:193], v147 offset:49152
	ds_read_b128 v[196:199], v147 offset:50176
	ds_read_b128 v[208:211], v146 offset:49152
	ds_read_b128 v[212:215], v146 offset:50176
	ds_read_b128 v[216:219], v145 offset:49152
	ds_read_b128 v[220:223], v145 offset:50176
	ds_read_b128 v[224:227], v144 offset:49152
	ds_read_b128 v[228:231], v144 offset:50176
	global_load_lds_dwordx4 v170, s[86:87] offset:128
	s_add_i32 m0, s100, 0x9f80
	s_nop 0
	global_load_lds_dwordx4 v206, s[86:87] offset:128
	s_barrier
	s_waitcnt lgkmcnt(0)
	v_mfma_f32_16x16x32_bf16 v[60:63], v[190:193], v[174:177], v[60:63]
	v_mfma_f32_16x16x32_bf16 v[56:59], v[190:193], v[182:185], v[56:59]
	v_mfma_f32_16x16x32_bf16 v[52:55], v[208:211], v[174:177], v[52:55]
	v_mfma_f32_16x16x32_bf16 v[48:51], v[208:211], v[182:185], v[48:51]
	v_mfma_f32_16x16x32_bf16 v[44:47], v[216:219], v[174:177], v[44:47]
	v_mfma_f32_16x16x32_bf16 v[40:43], v[216:219], v[182:185], v[40:43]
	v_mfma_f32_16x16x32_bf16 v[36:39], v[224:227], v[174:177], v[36:39]
	v_mfma_f32_16x16x32_bf16 v[32:35], v[224:227], v[182:185], v[32:35]
	v_mfma_f32_16x16x32_bf16 v[60:63], v[196:199], v[178:181], v[60:63]
	v_mfma_f32_16x16x32_bf16 v[56:59], v[196:199], v[186:189], v[56:59]
	v_mfma_f32_16x16x32_bf16 v[52:55], v[212:215], v[178:181], v[52:55]
	v_mfma_f32_16x16x32_bf16 v[48:51], v[212:215], v[186:189], v[48:51]
	v_mfma_f32_16x16x32_bf16 v[44:47], v[220:223], v[178:181], v[44:47]
	v_mfma_f32_16x16x32_bf16 v[40:43], v[220:223], v[186:189], v[40:43]
	v_mfma_f32_16x16x32_bf16 v[36:39], v[228:231], v[178:181], v[36:39]
	v_mfma_f32_16x16x32_bf16 v[32:35], v[228:231], v[186:189], v[32:35]
	s_barrier
; #define P8_STAGE(P,BASE,br,kt) do{const bfr* _ub=(BASE)+((long)(br)*K+(long)(kt)*BK); \
;     __builtin_amdgcn_global_load_lds((const unsigned*)(_ub+so0),(unsigned*)((char*)(P)+wid*1024),16,0,0); \
;     __builtin_amdgcn_global_load_lds((const unsigned*)(_ub+so1),(unsigned*)((char*)(P)+wid*1024+8192),16,0,0);}while(0)
; #define P8_LDA(dst,b,h) _Pragma("unroll") for(int m=0;m<4;++m) _Pragma("unroll") for(int k=0;k<2;++k) \
;     dst[m][k]=*reinterpret_cast<const bf16x8*>((char*)P8_SA(b,h)+lds_byte(wr*64+m*16+fr,k*32+fq*8))
; #define P8_LDB(dst,b,h) _Pragma("unroll") for(int n=0;n<2;++n) _Pragma("unroll") for(int k=0;k<2;++k) \
;     dst[n][k]=*reinterpret_cast<const bf16x8*>((char*)P8_SB(b,h)+lds_byte(wc*32+n*16+fr,k*32+fq*8))
; #define P8_MMA(ai,bj,At,Bt) do{__builtin_amdgcn_s_setprio(1); \
;     _Pragma("unroll") for(int m=0;m<4;++m) _Pragma("unroll") for(int n=0;n<2;++n) _Pragma("unroll") for(int k=0;k<2;++k) \
;       acc[ai][bj][m][n]=__builtin_amdgcn_mfma_f32_16x16x32_bf16(At[m][k],Bt[n][k],acc[ai][bj][m][n],0,0,0); \
;     __builtin_amdgcn_s_setprio(0);}while(0)
; #define P8_WAIT_V(n) asm volatile("s_waitcnt vmcnt(" #n ")":::"memory")
; #define P8_WAIT_L(n) asm volatile("s_waitcnt lgkmcnt(" #n ")":::"memory")
; #define P8_BAR __builtin_amdgcn_s_barrier()
; #define P8_SCHED __builtin_amdgcn_sched_barrier(0)
; template <class EPI>
; DEVI void gemm8_tile(const bfr* __restrict__ A, const bfr* __restrict__ Bt, int K, int brow, int bcol, int nbrow, int nbcol, char* shmc, EPI epi) {
;     ...
;     P8_BAR; P8_WAIT_L(0); P8_MMA(1,0,At,B0); P8_BAR; P8_SCHED;
;     P8_STAGE(P8_SB(1,1),Bt,bcol+128,t+3);
;     P8_WAIT_V(6); P8_BAR; P8_MMA(1,1,At,B1); P8_BAR;
;   }
;   { P8_LDB(B0,0,0); P8_LDA(At,0,0); P8_STAGE(P8_SA(1,1),A,brow+128,nt-1);
;     P8_BAR; P8_WAIT_L(0); P8_MMA(0,0,At,B0); P8_BAR;
;     P8_LDB(B1,0,1); P8_BAR; P8_WAIT_L(0); P8_MMA(0,1,At,B1); P8_BAR;
	s_add_i32 m0, s100, 0x1bf80
	s_nop 0
	global_load_lds_dwordx4 v248, s[86:87] offset:128
	s_add_i32 m0, s100, 0x1df80
	s_nop 0
	global_load_lds_dwordx4 v200, s[86:87] offset:128
	s_waitcnt vmcnt(6)
	s_barrier
	v_mfma_f32_16x16x32_bf16 v[28:31], v[190:193], v[232:235], v[28:31]
	v_mfma_f32_16x16x32_bf16 v[24:27], v[190:193], v[240:243], v[24:27]
	v_mfma_f32_16x16x32_bf16 v[20:23], v[208:211], v[232:235], v[20:23]
	v_mfma_f32_16x16x32_bf16 v[16:19], v[208:211], v[240:243], v[16:19]
	v_mfma_f32_16x16x32_bf16 v[12:15], v[216:219], v[232:235], v[12:15]
	v_mfma_f32_16x16x32_bf16 v[8:11], v[216:219], v[240:243], v[8:11]
	v_mfma_f32_16x16x32_bf16 v[4:7], v[224:227], v[232:235], v[4:7]
	v_mfma_f32_16x16x32_bf16 v[0:3], v[224:227], v[240:243], v[0:3]
	v_mfma_f32_16x16x32_bf16 v[28:31], v[196:199], v[236:239], v[28:31]
	v_mfma_f32_16x16x32_bf16 v[24:27], v[196:199], v[244:247], v[24:27]
	v_mfma_f32_16x16x32_bf16 v[20:23], v[212:215], v[236:239], v[20:23]
	v_mfma_f32_16x16x32_bf16 v[16:19], v[212:215], v[244:247], v[16:19]
	v_mfma_f32_16x16x32_bf16 v[12:15], v[220:223], v[236:239], v[12:15]
	v_mfma_f32_16x16x32_bf16 v[8:11], v[220:223], v[244:247], v[8:11]
	v_mfma_f32_16x16x32_bf16 v[4:7], v[228:231], v[236:239], v[4:7]
	v_mfma_f32_16x16x32_bf16 v[0:3], v[228:231], v[244:247], v[0:3]
	s_add_i32 s0, s0, 2
	v_lshl_add_u64 v[134:135], v[134:135], 0, s[80:81]
	v_lshl_add_u64 v[136:137], v[136:137], 0, s[80:81]
	v_lshl_add_u64 v[138:139], v[138:139], 0, s[80:81]
	s_cmp_lt_u32 s0, 28
	v_lshl_add_u64 v[140:141], v[140:141], 0, s[80:81]
	s_barrier
	s_cbranch_scc1 .LBB0_221
	v_add_u32_e32 v171, 0xc000, v143
	v_add_u32_e32 v172, 0xe000, v143
	v_add_u32_e32 v158, 0x10000, v143
	v_add_u32_e32 v159, 0x12000, v143
	v_add_u32_e32 v160, 0x2000, v143
	v_add_u32_e32 v161, 0x14000, v143
	v_add_u32_e32 v162, 0x16000, v143
	v_add_u32_e32 v163, 0x4000, v143
	v_add_u32_e32 v170, 0x6000, v143
	s_or_b32 s0, s8, 0x80
	s_ashr_i32 s1, s0, 31
	s_lshl_b64 s[0:1], s[0:1], 12
	s_add_u32 s0, s34, s0
	s_addc_u32 s1, s35, s1
	ds_read_b128 v[134:137], v157
	ds_read_b128 v[138:141], v157 offset:1024
	ds_read_b128 v[150:153], v157 offset:2048
	ds_read_b128 v[174:177], v157 offset:3072
	ds_read_b128 v[178:181], v147
	ds_read_b128 v[182:185], v147 offset:1024
	ds_read_b128 v[186:189], v146
	ds_read_b128 v[190:193], v146 offset:1024
	ds_read_b128 v[196:199], v145
	ds_read_b128 v[208:211], v145 offset:1024
	ds_read_b128 v[212:215], v144
	ds_read_b128 v[216:219], v144 offset:1024
	v_lshl_add_u64 v[156:157], v[166:167], 1, s[0:1]
	s_mov_b64 s[54:55], 0xf80
	v_lshl_add_u64 v[156:157], v[156:157], 0, s[54:55]
	s_add_i32 m0, s100, 0xc000
	v_lshl_add_u64 v[132:133], v[132:133], 1, s[0:1]
	global_load_lds_dwordx4 v[156:157], off
	v_lshl_add_u64 v[132:133], v[132:133], 0, s[54:55]
	s_add_i32 m0, s100, 0xe000
	s_nop 0
	global_load_lds_dwordx4 v[132:133], off
	s_barrier
	s_waitcnt lgkmcnt(0)
	s_setprio 1
	s_waitcnt lgkmcnt(0)
	v_mfma_f32_16x16x32_bf16 v[124:127], v[178:181], v[134:137], v[124:127]
	v_mfma_f32_16x16x32_bf16 v[120:123], v[178:181], v[150:153], v[120:123]
	v_mfma_f32_16x16x32_bf16 v[116:119], v[186:189], v[134:137], v[116:119]
	v_mfma_f32_16x16x32_bf16 v[112:115], v[186:189], v[150:153], v[112:115]
	v_mfma_f32_16x16x32_bf16 v[96:99], v[212:215], v[150:153], v[96:99]
	v_mfma_f32_16x16x32_bf16 v[124:127], v[182:185], v[138:141], v[124:127]
	v_mfma_f32_16x16x32_bf16 v[120:123], v[182:185], v[174:177], v[120:123]
	v_mfma_f32_16x16x32_bf16 v[116:119], v[190:193], v[138:141], v[116:119]
	v_mfma_f32_16x16x32_bf16 v[112:115], v[190:193], v[174:177], v[112:115]
	v_mfma_f32_16x16x32_bf16 v[108:111], v[196:199], v[134:137], v[108:111]
	v_mfma_f32_16x16x32_bf16 v[104:107], v[196:199], v[150:153], v[104:107]
	v_mfma_f32_16x16x32_bf16 v[100:103], v[212:215], v[134:137], v[100:103]
	v_mfma_f32_16x16x32_bf16 v[96:99], v[216:219], v[174:177], v[96:99]
	v_mfma_f32_16x16x32_bf16 v[220:223], v[208:211], v[138:141], v[108:111]
	v_mfma_f32_16x16x32_bf16 v[224:227], v[208:211], v[174:177], v[104:107]
	v_mfma_f32_16x16x32_bf16 v[228:231], v[216:219], v[138:141], v[100:103]
	s_setprio 0
	s_barrier
	s_nop 1
	ds_read_b128 v[100:103], v155
	ds_read_b128 v[104:107], v155 offset:1024
	ds_read_b128 v[108:111], v155 offset:2048
	ds_read_b128 v[154:157], v155 offset:3072
	s_barrier
	s_waitcnt lgkmcnt(0)
	s_setprio 1
	s_waitcnt lgkmcnt(0)
	v_mfma_f32_16x16x32_bf16 v[92:95], v[178:181], v[100:103], v[92:95]
	v_mfma_f32_16x16x32_bf16 v[88:91], v[178:181], v[108:111], v[88:91]
	v_mfma_f32_16x16x32_bf16 v[84:87], v[186:189], v[100:103], v[84:87]
	v_mfma_f32_16x16x32_bf16 v[80:83], v[186:189], v[108:111], v[80:83]
	v_mfma_f32_16x16x32_bf16 v[64:67], v[212:215], v[108:111], v[64:67]
	v_mfma_f32_16x16x32_bf16 v[92:95], v[182:185], v[104:107], v[92:95]
	v_mfma_f32_16x16x32_bf16 v[88:91], v[182:185], v[154:157], v[88:91]
	v_mfma_f32_16x16x32_bf16 v[84:87], v[190:193], v[104:107], v[84:87]
	v_mfma_f32_16x16x32_bf16 v[80:83], v[190:193], v[154:157], v[80:83]
	v_mfma_f32_16x16x32_bf16 v[76:79], v[196:199], v[100:103], v[76:79]
	v_mfma_f32_16x16x32_bf16 v[72:75], v[196:199], v[108:111], v[72:75]
	v_mfma_f32_16x16x32_bf16 v[68:71], v[212:215], v[100:103], v[68:71]
	v_mfma_f32_16x16x32_bf16 v[64:67], v[216:219], v[154:157], v[64:67]
	v_mfma_f32_16x16x32_bf16 v[178:181], v[208:211], v[104:107], v[76:79]
	v_mfma_f32_16x16x32_bf16 v[182:185], v[208:211], v[154:157], v[72:75]
	v_mfma_f32_16x16x32_bf16 v[186:189], v[216:219], v[104:107], v[68:71]
	s_setprio 0
	s_barrier
; #define P8_LDA(dst,b,h) _Pragma("unroll") for(int m=0;m<4;++m) _Pragma("unroll") for(int k=0;k<2;++k) \
;     dst[m][k]=*reinterpret_cast<const bf16x8*>((char*)P8_SA(b,h)+lds_byte(wr*64+m*16+fr,k*32+fq*8))
; #define P8_LDB(dst,b,h) _Pragma("unroll") for(int n=0;n<2;++n) _Pragma("unroll") for(int k=0;k<2;++k) \
;     dst[n][k]=*reinterpret_cast<const bf16x8*>((char*)P8_SB(b,h)+lds_byte(wc*32+n*16+fr,k*32+fq*8))
; #define P8_MMA(ai,bj,At,Bt) do{__builtin_amdgcn_s_setprio(1); \
;     _Pragma("unroll") for(int m=0;m<4;++m) _Pragma("unroll") for(int n=0;n<2;++n) _Pragma("unroll") for(int k=0;k<2;++k) \
;       acc[ai][bj][m][n]=__builtin_amdgcn_mfma_f32_16x16x32_bf16(At[m][k],Bt[n][k],acc[ai][bj][m][n],0,0,0); \
;     __builtin_amdgcn_s_setprio(0);}while(0)
; #define P8_WAIT_V(n) asm volatile("s_waitcnt vmcnt(" #n ")":::"memory")
; #define P8_WAIT_L(n) asm volatile("s_waitcnt lgkmcnt(" #n ")":::"memory")
; #define P8_BAR __builtin_amdgcn_s_barrier()
; template <class EPI>
; DEVI void gemm8_tile(const bfr* __restrict__ A, const bfr* __restrict__ Bt, int K, int brow, int bcol, int nbrow, int nbcol, char* shmc, EPI epi) {
;     ...
;     P8_LDA(At,0,1); P8_WAIT_V(4); P8_BAR; P8_WAIT_L(0); P8_MMA(1,0,At,B0); P8_MMA(1,1,At,B1); P8_BAR; }
;   { P8_LDB(B0,1,0); P8_LDA(At,1,0); P8_WAIT_V(2); P8_BAR; P8_WAIT_L(0); P8_MMA(0,0,At,B0); P8_BAR;
	s_nop 1
	ds_read_b128 v[68:71], v147 offset:16384
	ds_read_b128 v[72:75], v147 offset:17408
	ds_read_b128 v[76:79], v146 offset:16384
	ds_read_b128 v[190:193], v146 offset:17408
	ds_read_b128 v[196:199], v145 offset:16384
	ds_read_b128 v[208:211], v145 offset:17408
	ds_read_b128 v[212:215], v144 offset:16384
	ds_read_b128 v[216:219], v144 offset:17408
	s_waitcnt vmcnt(4)
	s_barrier
	s_waitcnt lgkmcnt(0)
	s_setprio 1
	s_waitcnt lgkmcnt(0)
	v_mfma_f32_16x16x32_bf16 v[60:63], v[68:71], v[134:137], v[60:63]
	v_mfma_f32_16x16x32_bf16 v[56:59], v[68:71], v[150:153], v[56:59]
	v_mfma_f32_16x16x32_bf16 v[52:55], v[76:79], v[134:137], v[52:55]
	v_mfma_f32_16x16x32_bf16 v[48:51], v[76:79], v[150:153], v[48:51]
	v_mfma_f32_16x16x32_bf16 v[32:35], v[212:215], v[150:153], v[32:35]
	v_mfma_f32_16x16x32_bf16 v[60:63], v[72:75], v[138:141], v[60:63]
	v_mfma_f32_16x16x32_bf16 v[56:59], v[72:75], v[174:177], v[56:59]
	v_mfma_f32_16x16x32_bf16 v[52:55], v[190:193], v[138:141], v[52:55]
	v_mfma_f32_16x16x32_bf16 v[48:51], v[190:193], v[174:177], v[48:51]
	v_mfma_f32_16x16x32_bf16 v[44:47], v[196:199], v[134:137], v[44:47]
	v_mfma_f32_16x16x32_bf16 v[40:43], v[196:199], v[150:153], v[40:43]
	v_mfma_f32_16x16x32_bf16 v[36:39], v[212:215], v[134:137], v[36:39]
	v_mfma_f32_16x16x32_bf16 v[32:35], v[216:219], v[174:177], v[32:35]
	v_mfma_f32_16x16x32_bf16 v[232:235], v[208:211], v[138:141], v[44:47]
	v_mfma_f32_16x16x32_bf16 v[236:239], v[208:211], v[174:177], v[40:43]
	v_mfma_f32_16x16x32_bf16 v[132:135], v[216:219], v[138:141], v[36:39]
	s_setprio 0
	s_setprio 1
	v_mfma_f32_16x16x32_bf16 v[28:31], v[68:71], v[100:103], v[28:31]
	v_mfma_f32_16x16x32_bf16 v[24:27], v[68:71], v[108:111], v[24:27]
	v_mfma_f32_16x16x32_bf16 v[20:23], v[76:79], v[100:103], v[20:23]
	v_mfma_f32_16x16x32_bf16 v[16:19], v[76:79], v[108:111], v[16:19]
	v_mfma_f32_16x16x32_bf16 v[0:3], v[212:215], v[108:111], v[0:3]
	v_mfma_f32_16x16x32_bf16 v[28:31], v[72:75], v[104:107], v[28:31]
	v_mfma_f32_16x16x32_bf16 v[24:27], v[72:75], v[154:157], v[24:27]
	v_mfma_f32_16x16x32_bf16 v[20:23], v[190:193], v[104:107], v[20:23]
	v_mfma_f32_16x16x32_bf16 v[16:19], v[190:193], v[154:157], v[16:19]
	v_mfma_f32_16x16x32_bf16 v[12:15], v[196:199], v[100:103], v[12:15]
	v_mfma_f32_16x16x32_bf16 v[8:11], v[196:199], v[108:111], v[8:11]
	v_mfma_f32_16x16x32_bf16 v[4:7], v[212:215], v[100:103], v[4:7]
	v_mfma_f32_16x16x32_bf16 v[0:3], v[216:219], v[154:157], v[0:3]
	v_mfma_f32_16x16x32_bf16 v[136:139], v[208:211], v[104:107], v[12:15]
	v_mfma_f32_16x16x32_bf16 v[150:153], v[208:211], v[154:157], v[8:11]
	v_mfma_f32_16x16x32_bf16 v[172:175], v[216:219], v[104:107], v[4:7]
	s_setprio 0
	s_barrier
	s_nop 1
	ds_read_b128 v[4:7], v149
	ds_read_b128 v[8:11], v149 offset:1024
	ds_read_b128 v[12:15], v149 offset:2048
	ds_read_b128 v[154:157], v149 offset:3072
	ds_read_b128 v[36:39], v147 offset:32768
	ds_read_b128 v[40:43], v147 offset:33792
	ds_read_b128 v[44:47], v146 offset:32768
	ds_read_b128 v[68:71], v146 offset:33792
	ds_read_b128 v[190:193], v145 offset:32768
	ds_read_b128 v[196:199], v145 offset:33792
	ds_read_b128 v[208:211], v144 offset:32768
	ds_read_b128 v[212:215], v144 offset:33792
	s_waitcnt vmcnt(2)
	s_barrier
	s_waitcnt lgkmcnt(0)
	s_setprio 1
	s_waitcnt lgkmcnt(0)
	v_mfma_f32_16x16x32_bf16 v[72:75], v[36:39], v[4:7], v[124:127]
	v_mfma_f32_16x16x32_bf16 v[124:127], v[40:43], v[8:11], v[72:75]
	v_mfma_f32_16x16x32_bf16 v[72:75], v[36:39], v[12:15], v[120:123]
	v_mfma_f32_16x16x32_bf16 v[108:111], v[40:43], v[154:157], v[72:75]
	v_mfma_f32_16x16x32_bf16 v[72:75], v[44:47], v[4:7], v[116:119]
	v_mfma_f32_16x16x32_bf16 v[120:123], v[68:71], v[8:11], v[72:75]
	v_mfma_f32_16x16x32_bf16 v[72:75], v[44:47], v[12:15], v[112:115]
	v_mfma_f32_16x16x32_bf16 v[104:107], v[68:71], v[154:157], v[72:75]
	v_mfma_f32_16x16x32_bf16 v[72:75], v[190:193], v[4:7], v[220:223]
	v_mfma_f32_16x16x32_bf16 v[116:119], v[196:199], v[8:11], v[72:75]
	v_mfma_f32_16x16x32_bf16 v[72:75], v[190:193], v[12:15], v[224:227]
	v_mfma_f32_16x16x32_bf16 v[100:103], v[196:199], v[154:157], v[72:75]
	v_mfma_f32_16x16x32_bf16 v[72:75], v[208:211], v[4:7], v[228:231]
	v_mfma_f32_16x16x32_bf16 v[112:115], v[212:215], v[8:11], v[72:75]
	v_mfma_f32_16x16x32_bf16 v[72:75], v[208:211], v[12:15], v[96:99]
	v_mfma_f32_16x16x32_bf16 v[96:99], v[212:215], v[154:157], v[72:75]
	s_setprio 0
	s_barrier
; #define P8_LDA(dst,b,h) _Pragma("unroll") for(int m=0;m<4;++m) _Pragma("unroll") for(int k=0;k<2;++k) \
;     dst[m][k]=*reinterpret_cast<const bf16x8*>((char*)P8_SA(b,h)+lds_byte(wr*64+m*16+fr,k*32+fq*8))
; #define P8_LDB(dst,b,h) _Pragma("unroll") for(int n=0;n<2;++n) _Pragma("unroll") for(int k=0;k<2;++k) \
;     dst[n][k]=*reinterpret_cast<const bf16x8*>((char*)P8_SB(b,h)+lds_byte(wc*32+n*16+fr,k*32+fq*8))
; #define P8_MMA(ai,bj,At,Bt) do{__builtin_amdgcn_s_setprio(1); \
;     _Pragma("unroll") for(int m=0;m<4;++m) _Pragma("unroll") for(int n=0;n<2;++n) _Pragma("unroll") for(int k=0;k<2;++k) \
;       acc[ai][bj][m][n]=__builtin_amdgcn_mfma_f32_16x16x32_bf16(At[m][k],Bt[n][k],acc[ai][bj][m][n],0,0,0); \
;     __builtin_amdgcn_s_setprio(0);}while(0)
; #define P8_WAIT_V(n) asm volatile("s_waitcnt vmcnt(" #n ")":::"memory")
; #define P8_WAIT_L(n) asm volatile("s_waitcnt lgkmcnt(" #n ")":::"memory")
; #define P8_BAR __builtin_amdgcn_s_barrier()
; template <class EPI>
; DEVI void gemm8_tile(const bfr* __restrict__ A, const bfr* __restrict__ Bt, int K, int brow, int bcol, int nbrow, int nbcol, char* shmc, EPI epi) {
;     ...
;     P8_LDB(B1,1,1); P8_WAIT_V(0); P8_BAR; P8_WAIT_L(0); P8_MMA(0,1,At,B1); P8_BAR;
;     P8_LDA(At,1,1); P8_BAR; P8_WAIT_L(0); P8_MMA(1,0,At,B0); P8_MMA(1,1,At,B1); P8_BAR; }
;   if(wr==0)P8_BAR;
	ds_read_b128 v[216:219], v148
	ds_read_b128 v[220:223], v148 offset:1024
	ds_read_b128 v[224:227], v148 offset:2048
	ds_read_b128 v[228:231], v148 offset:3072
	s_waitcnt vmcnt(0)
	s_barrier
	s_waitcnt lgkmcnt(0)
	s_setprio 1
	s_waitcnt lgkmcnt(0)
	v_mfma_f32_16x16x32_bf16 v[72:75], v[36:39], v[216:219], v[92:95]
	v_mfma_f32_16x16x32_bf16 v[36:39], v[36:39], v[224:227], v[88:91]
	v_mfma_f32_16x16x32_bf16 v[76:79], v[40:43], v[228:231], v[36:39]
	v_mfma_f32_16x16x32_bf16 v[36:39], v[44:47], v[216:219], v[84:87]
	v_mfma_f32_16x16x32_bf16 v[88:91], v[68:71], v[220:223], v[36:39]
	v_mfma_f32_16x16x32_bf16 v[36:39], v[44:47], v[224:227], v[80:83]
	v_mfma_f32_16x16x32_bf16 v[92:95], v[40:43], v[220:223], v[72:75]
	v_mfma_f32_16x16x32_bf16 v[72:75], v[68:71], v[228:231], v[36:39]
	v_mfma_f32_16x16x32_bf16 v[36:39], v[190:193], v[216:219], v[178:181]
	v_mfma_f32_16x16x32_bf16 v[84:87], v[196:199], v[220:223], v[36:39]
	v_mfma_f32_16x16x32_bf16 v[36:39], v[190:193], v[224:227], v[182:185]
	v_mfma_f32_16x16x32_bf16 v[68:71], v[196:199], v[228:231], v[36:39]
	v_mfma_f32_16x16x32_bf16 v[36:39], v[208:211], v[216:219], v[186:189]
	v_mfma_f32_16x16x32_bf16 v[80:83], v[212:215], v[220:223], v[36:39]
	v_mfma_f32_16x16x32_bf16 v[36:39], v[208:211], v[224:227], v[64:67]
	v_mfma_f32_16x16x32_bf16 v[64:67], v[212:215], v[228:231], v[36:39]
	s_setprio 0
	s_barrier
	ds_read_b128 v[176:179], v147 offset:49152
	ds_read_b128 v[180:183], v147 offset:50176
	ds_read_b128 v[184:187], v146 offset:49152
	ds_read_b128 v[146:149], v146 offset:50176
	ds_read_b128 v[188:191], v145 offset:49152
	ds_read_b128 v[196:199], v145 offset:50176
	ds_read_b128 v[208:211], v144 offset:49152
	ds_read_b128 v[212:215], v144 offset:50176
	s_barrier
	s_waitcnt lgkmcnt(0)
	s_setprio 1
	s_waitcnt lgkmcnt(0)
	v_mfma_f32_16x16x32_bf16 v[36:39], v[176:179], v[4:7], v[60:63]
	v_mfma_f32_16x16x32_bf16 v[60:63], v[180:183], v[8:11], v[36:39]
	v_mfma_f32_16x16x32_bf16 v[36:39], v[176:179], v[12:15], v[56:59]
	v_mfma_f32_16x16x32_bf16 v[44:47], v[180:183], v[154:157], v[36:39]
	v_mfma_f32_16x16x32_bf16 v[36:39], v[184:187], v[4:7], v[52:55]
	v_mfma_f32_16x16x32_bf16 v[56:59], v[146:149], v[8:11], v[36:39]
	v_mfma_f32_16x16x32_bf16 v[36:39], v[184:187], v[12:15], v[48:51]
	v_mfma_f32_16x16x32_bf16 v[40:43], v[146:149], v[154:157], v[36:39]
	v_mfma_f32_16x16x32_bf16 v[36:39], v[188:191], v[4:7], v[232:235]
	v_mfma_f32_16x16x32_bf16 v[4:7], v[208:211], v[4:7], v[132:135]
	v_mfma_f32_16x16x32_bf16 v[52:55], v[196:199], v[8:11], v[36:39]
	v_mfma_f32_16x16x32_bf16 v[36:39], v[188:191], v[12:15], v[236:239]
	v_mfma_f32_16x16x32_bf16 v[48:51], v[212:215], v[8:11], v[4:7]
	v_mfma_f32_16x16x32_bf16 v[4:7], v[208:211], v[12:15], v[32:35]
	v_mfma_f32_16x16x32_bf16 v[36:39], v[196:199], v[154:157], v[36:39]
	v_mfma_f32_16x16x32_bf16 v[32:35], v[212:215], v[154:157], v[4:7]
	s_setprio 0
	s_setprio 1
	v_mfma_f32_16x16x32_bf16 v[4:7], v[176:179], v[216:219], v[28:31]
	v_mfma_f32_16x16x32_bf16 v[28:31], v[180:183], v[220:223], v[4:7]
	v_mfma_f32_16x16x32_bf16 v[4:7], v[176:179], v[224:227], v[24:27]
	v_mfma_f32_16x16x32_bf16 v[12:15], v[180:183], v[228:231], v[4:7]
	v_mfma_f32_16x16x32_bf16 v[4:7], v[184:187], v[216:219], v[20:23]
	v_mfma_f32_16x16x32_bf16 v[24:27], v[146:149], v[220:223], v[4:7]
	v_mfma_f32_16x16x32_bf16 v[4:7], v[184:187], v[224:227], v[16:19]
	v_mfma_f32_16x16x32_bf16 v[8:11], v[146:149], v[228:231], v[4:7]
	v_mfma_f32_16x16x32_bf16 v[4:7], v[188:191], v[216:219], v[136:139]
	v_mfma_f32_16x16x32_bf16 v[20:23], v[196:199], v[220:223], v[4:7]
	v_mfma_f32_16x16x32_bf16 v[4:7], v[188:191], v[224:227], v[150:153]
	v_mfma_f32_16x16x32_bf16 v[16:19], v[208:211], v[216:219], v[172:175]
	v_mfma_f32_16x16x32_bf16 v[0:3], v[208:211], v[224:227], v[0:3]
	v_mfma_f32_16x16x32_bf16 v[4:7], v[196:199], v[228:231], v[4:7]
	v_mfma_f32_16x16x32_bf16 v[16:19], v[212:215], v[220:223], v[16:19]
	v_mfma_f32_16x16x32_bf16 v[0:3], v[212:215], v[228:231], v[0:3]
	s_setprio 0
	v_cmp_gt_u32_e32 vcc, s57, v142
	s_barrier
	s_and_saveexec_b64 s[0:1], vcc
	s_cbranch_execz .LBB0_224
	s_barrier

; #define P8_STAGE(P,BASE,br,kt) do{const bfr* _ub=(BASE)+((long)(br)*K+(long)(kt)*BK); \
;     __builtin_amdgcn_global_load_lds((const unsigned*)(_ub+so0),(unsigned*)((char*)(P)+wid*1024),16,0,0); \
;     __builtin_amdgcn_global_load_lds((const unsigned*)(_ub+so1),(unsigned*)((char*)(P)+wid*1024+8192),16,0,0);}while(0)
; #define P8_LDA(dst,b,h) _Pragma("unroll") for(int m=0;m<4;++m) _Pragma("unroll") for(int k=0;k<2;++k) \
;     dst[m][k]=*reinterpret_cast<const bf16x8*>((char*)P8_SA(b,h)+lds_byte(wr*64+m*16+fr,k*32+fq*8))
; #define P8_LDB(dst,b,h) _Pragma("unroll") for(int n=0;n<2;++n) _Pragma("unroll") for(int k=0;k<2;++k) \
;     dst[n][k]=*reinterpret_cast<const bf16x8*>((char*)P8_SB(b,h)+lds_byte(wc*32+n*16+fr,k*32+fq*8))
; #define P8_MMA(ai,bj,At,Bt) do{__builtin_amdgcn_s_setprio(1); \
;     _Pragma("unroll") for(int m=0;m<4;++m) _Pragma("unroll") for(int n=0;n<2;++n) _Pragma("unroll") for(int k=0;k<2;++k) \
;       acc[ai][bj][m][n]=__builtin_amdgcn_mfma_f32_16x16x32_bf16(At[m][k],Bt[n][k],acc[ai][bj][m][n],0,0,0); \
;     __builtin_amdgcn_s_setprio(0);}while(0)
; #define P8_WAIT_V(n) asm volatile("s_waitcnt vmcnt(" #n ")":::"memory")
; #define P8_WAIT_L(n) asm volatile("s_waitcnt lgkmcnt(" #n ")":::"memory")
; #define P8_BAR __builtin_amdgcn_s_barrier()
; #define P8_SCHED __builtin_amdgcn_sched_barrier(0)
; template <class EPI>
; DEVI void gemm8_tile(const bfr* __restrict__ A, const bfr* __restrict__ Bt, int K, int brow, int bcol, int nbrow, int nbcol, char* shmc, EPI epi) {
;     ...
;     P8_LDB(B0,0,0); P8_SCHED; P8_LDA(At,0,0); P8_STAGE(P8_SA(1,1),A,brow+128,t+1);
;     P8_WAIT_L(8); P8_BAR; P8_WAIT_L(0); P8_MMA(0,0,At,B0); P8_BAR; P8_SCHED;
;     P8_LDB(B1,0,1); P8_STAGE(P8_SB(0,0),Bt,bcol,t+2);
;     P8_BAR; P8_WAIT_L(0); P8_MMA(0,1,At,B1); P8_BAR;
;     P8_LDA(At,0,1); P8_STAGE(P8_SA(0,0),A,brow,t+2);
;     P8_BAR; P8_WAIT_L(0); P8_MMA(1,0,At,B0); P8_BAR; P8_SCHED;
;     P8_STAGE(P8_SB(0,1),Bt,bcol+128,t+2);
;     P8_WAIT_V(6); P8_BAR; P8_MMA(1,1,At,B1); P8_BAR;
.LBB0_286:
	ds_read_b128 v[174:177], v157
	ds_read_b128 v[178:181], v157 offset:1024
	ds_read_b128 v[182:185], v157 offset:2048
	ds_read_b128 v[186:189], v157 offset:3072
	v_add_u32_e32 v171, s54, v140
	s_add_i32 m0, s100, 0xc000
	ds_read_b128 v[160:163], v147
	ds_read_b128 v[190:193], v147 offset:1024
	ds_read_b128 v[196:199], v146
	ds_read_b128 v[200:203], v146 offset:1024
	ds_read_b128 v[204:207], v145
	ds_read_b128 v[208:211], v145 offset:1024
	ds_read_b128 v[212:215], v144
	ds_read_b128 v[216:219], v144 offset:1024
	global_load_lds_dwordx4 v171, s[86:87]
	v_add_u32_e32 v172, s54, v138
	s_add_i32 m0, s100, 0xe000
	s_nop 0
	global_load_lds_dwordx4 v172, s[86:87]
	s_waitcnt lgkmcnt(8)
	s_barrier
	s_waitcnt lgkmcnt(0)
	v_mfma_f32_16x16x32_bf16 v[124:127], v[160:163], v[174:177], v[124:127]
	v_mfma_f32_16x16x32_bf16 v[120:123], v[160:163], v[182:185], v[120:123]
	v_mfma_f32_16x16x32_bf16 v[116:119], v[196:199], v[174:177], v[116:119]
	v_mfma_f32_16x16x32_bf16 v[112:115], v[196:199], v[182:185], v[112:115]
	v_mfma_f32_16x16x32_bf16 v[108:111], v[204:207], v[174:177], v[108:111]
	v_mfma_f32_16x16x32_bf16 v[104:107], v[204:207], v[182:185], v[104:107]
	v_mfma_f32_16x16x32_bf16 v[100:103], v[212:215], v[174:177], v[100:103]
	v_mfma_f32_16x16x32_bf16 v[96:99], v[212:215], v[182:185], v[96:99]
	v_mfma_f32_16x16x32_bf16 v[124:127], v[190:193], v[178:181], v[124:127]
	v_mfma_f32_16x16x32_bf16 v[120:123], v[190:193], v[186:189], v[120:123]
	v_mfma_f32_16x16x32_bf16 v[116:119], v[200:203], v[178:181], v[116:119]
	v_mfma_f32_16x16x32_bf16 v[112:115], v[200:203], v[186:189], v[112:115]
	v_mfma_f32_16x16x32_bf16 v[108:111], v[208:211], v[178:181], v[108:111]
	v_mfma_f32_16x16x32_bf16 v[104:107], v[208:211], v[186:189], v[104:107]
	v_mfma_f32_16x16x32_bf16 v[100:103], v[216:219], v[178:181], v[100:103]
	v_mfma_f32_16x16x32_bf16 v[96:99], v[216:219], v[186:189], v[96:99]
	s_barrier
	v_add_u32_e32 v158, s66, v136
	s_add_i32 m0, s100, 0x10000
	ds_read_b128 v[220:223], v155
	ds_read_b128 v[224:227], v155 offset:1024
	ds_read_b128 v[228:231], v155 offset:2048
	ds_read_b128 v[232:235], v155 offset:3072
	global_load_lds_dwordx4 v158, s[86:87]
	v_add_u32_e32 v159, s66, v134
	s_add_i32 m0, s100, 0x12000
	s_nop 0
	global_load_lds_dwordx4 v159, s[86:87]
	s_barrier
	s_waitcnt lgkmcnt(0)
	v_mfma_f32_16x16x32_bf16 v[92:95], v[160:163], v[220:223], v[92:95]
	v_mfma_f32_16x16x32_bf16 v[88:91], v[160:163], v[228:231], v[88:91]
	v_mfma_f32_16x16x32_bf16 v[84:87], v[196:199], v[220:223], v[84:87]
	v_mfma_f32_16x16x32_bf16 v[80:83], v[196:199], v[228:231], v[80:83]
	v_mfma_f32_16x16x32_bf16 v[76:79], v[204:207], v[220:223], v[76:79]
	v_mfma_f32_16x16x32_bf16 v[72:75], v[204:207], v[228:231], v[72:75]
	v_mfma_f32_16x16x32_bf16 v[68:71], v[212:215], v[220:223], v[68:71]
	v_mfma_f32_16x16x32_bf16 v[64:67], v[212:215], v[228:231], v[64:67]
	v_mfma_f32_16x16x32_bf16 v[92:95], v[190:193], v[224:227], v[92:95]
	v_mfma_f32_16x16x32_bf16 v[88:91], v[190:193], v[232:235], v[88:91]
	v_mfma_f32_16x16x32_bf16 v[84:87], v[200:203], v[224:227], v[84:87]
	v_mfma_f32_16x16x32_bf16 v[80:83], v[200:203], v[232:235], v[80:83]
	v_mfma_f32_16x16x32_bf16 v[76:79], v[208:211], v[224:227], v[76:79]
	v_mfma_f32_16x16x32_bf16 v[72:75], v[208:211], v[232:235], v[72:75]
	v_mfma_f32_16x16x32_bf16 v[68:71], v[216:219], v[224:227], v[68:71]
	v_mfma_f32_16x16x32_bf16 v[64:67], v[216:219], v[232:235], v[64:67]
	v_add_u32_e32 v170, s60, v140
	s_mov_b32 m0, s100
	s_barrier
	ds_read_b128 v[190:193], v147 offset:16384
	ds_read_b128 v[196:199], v147 offset:17408
	ds_read_b128 v[200:203], v146 offset:16384
	ds_read_b128 v[204:207], v146 offset:17408
	ds_read_b128 v[208:211], v145 offset:16384
	ds_read_b128 v[212:215], v145 offset:17408
	ds_read_b128 v[216:219], v144 offset:16384
	ds_read_b128 v[236:239], v144 offset:17408
	global_load_lds_dwordx4 v170, s[86:87]
	v_add_u32_e32 v248, s60, v138
	s_add_i32 m0, s100, 0x2000
	s_nop 0
	global_load_lds_dwordx4 v248, s[86:87]
	s_barrier
	s_waitcnt lgkmcnt(0)
	v_mfma_f32_16x16x32_bf16 v[60:63], v[190:193], v[174:177], v[60:63]
	v_mfma_f32_16x16x32_bf16 v[56:59], v[190:193], v[182:185], v[56:59]
	v_mfma_f32_16x16x32_bf16 v[52:55], v[200:203], v[174:177], v[52:55]
	v_mfma_f32_16x16x32_bf16 v[48:51], v[200:203], v[182:185], v[48:51]
	v_mfma_f32_16x16x32_bf16 v[44:47], v[208:211], v[174:177], v[44:47]
	v_mfma_f32_16x16x32_bf16 v[40:43], v[208:211], v[182:185], v[40:43]
	v_mfma_f32_16x16x32_bf16 v[36:39], v[216:219], v[174:177], v[36:39]
	v_mfma_f32_16x16x32_bf16 v[32:35], v[216:219], v[182:185], v[32:35]
	v_mfma_f32_16x16x32_bf16 v[60:63], v[196:199], v[178:181], v[60:63]
	v_mfma_f32_16x16x32_bf16 v[56:59], v[196:199], v[186:189], v[56:59]
	v_mfma_f32_16x16x32_bf16 v[52:55], v[204:207], v[178:181], v[52:55]
	v_mfma_f32_16x16x32_bf16 v[48:51], v[204:207], v[186:189], v[48:51]
	v_mfma_f32_16x16x32_bf16 v[44:47], v[212:215], v[178:181], v[44:47]
	v_mfma_f32_16x16x32_bf16 v[40:43], v[212:215], v[186:189], v[40:43]
	v_mfma_f32_16x16x32_bf16 v[36:39], v[236:239], v[178:181], v[36:39]
	v_mfma_f32_16x16x32_bf16 v[32:35], v[236:239], v[186:189], v[32:35]
	s_barrier
	v_add_u32_e32 v240, s70, v136
	s_add_i32 m0, s100, 0x14000
	v_add_u32_e32 v174, s70, v134
	global_load_lds_dwordx4 v240, s[86:87]
	s_nop 0
	s_add_i32 m0, s100, 0x16000
	s_nop 0
	global_load_lds_dwordx4 v174, s[86:87]
	s_waitcnt vmcnt(6)
	s_barrier
; #define P8_STAGE(P,BASE,br,kt) do{const bfr* _ub=(BASE)+((long)(br)*K+(long)(kt)*BK); \
;     __builtin_amdgcn_global_load_lds((const unsigned*)(_ub+so0),(unsigned*)((char*)(P)+wid*1024),16,0,0); \
;     __builtin_amdgcn_global_load_lds((const unsigned*)(_ub+so1),(unsigned*)((char*)(P)+wid*1024+8192),16,0,0);}while(0)
; #define P8_LDA(dst,b,h) _Pragma("unroll") for(int m=0;m<4;++m) _Pragma("unroll") for(int k=0;k<2;++k) \
;     dst[m][k]=*reinterpret_cast<const bf16x8*>((char*)P8_SA(b,h)+lds_byte(wr*64+m*16+fr,k*32+fq*8))
; #define P8_LDB(dst,b,h) _Pragma("unroll") for(int n=0;n<2;++n) _Pragma("unroll") for(int k=0;k<2;++k) \
;     dst[n][k]=*reinterpret_cast<const bf16x8*>((char*)P8_SB(b,h)+lds_byte(wc*32+n*16+fr,k*32+fq*8))
; #define P8_MMA(ai,bj,At,Bt) do{__builtin_amdgcn_s_setprio(1); \
;     _Pragma("unroll") for(int m=0;m<4;++m) _Pragma("unroll") for(int n=0;n<2;++n) _Pragma("unroll") for(int k=0;k<2;++k) \
;       acc[ai][bj][m][n]=__builtin_amdgcn_mfma_f32_16x16x32_bf16(At[m][k],Bt[n][k],acc[ai][bj][m][n],0,0,0); \
;     __builtin_amdgcn_s_setprio(0);}while(0)
; #define P8_WAIT_V(n) asm volatile("s_waitcnt vmcnt(" #n ")":::"memory")
; #define P8_WAIT_L(n) asm volatile("s_waitcnt lgkmcnt(" #n ")":::"memory")
; #define P8_BAR __builtin_amdgcn_s_barrier()
; #define P8_SCHED __builtin_amdgcn_sched_barrier(0)
; template <class EPI>
; DEVI void gemm8_tile(const bfr* __restrict__ A, const bfr* __restrict__ Bt, int K, int brow, int bcol, int nbrow, int nbcol, char* shmc, EPI epi) {
;     ...
;     P8_WAIT_V(6); P8_BAR; P8_MMA(1,1,At,B1); P8_BAR;
;     P8_LDB(B0,1,0); P8_SCHED; P8_LDA(At,1,0); P8_STAGE(P8_SA(0,1),A,brow+128,t+2);
;     P8_WAIT_L(8); P8_BAR; P8_WAIT_L(0); P8_MMA(0,0,At,B0); P8_BAR; P8_SCHED;
;     P8_LDB(B1,1,1); P8_STAGE(P8_SB(1,0),Bt,bcol,t+3);
;     P8_BAR; P8_WAIT_L(0); P8_MMA(0,1,At,B1); P8_BAR;
;     P8_LDA(At,1,1); P8_STAGE(P8_SA(1,0),A,brow,t+3);
;     P8_BAR; P8_WAIT_L(0); P8_MMA(1,0,At,B0); P8_BAR; P8_SCHED;
	v_mfma_f32_16x16x32_bf16 v[28:31], v[190:193], v[220:223], v[28:31]
	v_mfma_f32_16x16x32_bf16 v[24:27], v[190:193], v[228:231], v[24:27]
	v_mfma_f32_16x16x32_bf16 v[20:23], v[200:203], v[220:223], v[20:23]
	v_mfma_f32_16x16x32_bf16 v[16:19], v[200:203], v[228:231], v[16:19]
	v_mfma_f32_16x16x32_bf16 v[12:15], v[208:211], v[220:223], v[12:15]
	v_mfma_f32_16x16x32_bf16 v[8:11], v[208:211], v[228:231], v[8:11]
	v_mfma_f32_16x16x32_bf16 v[4:7], v[216:219], v[220:223], v[4:7]
	v_mfma_f32_16x16x32_bf16 v[0:3], v[216:219], v[228:231], v[0:3]
	v_mfma_f32_16x16x32_bf16 v[28:31], v[196:199], v[224:227], v[28:31]
	v_mfma_f32_16x16x32_bf16 v[24:27], v[196:199], v[232:235], v[24:27]
	v_mfma_f32_16x16x32_bf16 v[20:23], v[204:207], v[224:227], v[20:23]
	v_mfma_f32_16x16x32_bf16 v[16:19], v[204:207], v[232:235], v[16:19]
	v_mfma_f32_16x16x32_bf16 v[12:15], v[212:215], v[224:227], v[12:15]
	v_mfma_f32_16x16x32_bf16 v[8:11], v[212:215], v[232:235], v[8:11]
	v_mfma_f32_16x16x32_bf16 v[4:7], v[236:239], v[224:227], v[4:7]
	v_mfma_f32_16x16x32_bf16 v[0:3], v[236:239], v[232:235], v[0:3]
	s_barrier
	ds_read_b128 v[174:177], v149
	ds_read_b128 v[178:181], v149 offset:1024
	ds_read_b128 v[182:185], v149 offset:2048
	ds_read_b128 v[186:189], v149 offset:3072
	s_add_i32 m0, s100, 0x3f80
	ds_read_b128 v[190:193], v147 offset:32768
	ds_read_b128 v[196:199], v147 offset:33792
	ds_read_b128 v[200:203], v146 offset:32768
	ds_read_b128 v[204:207], v146 offset:33792
	ds_read_b128 v[208:211], v145 offset:32768
	ds_read_b128 v[212:215], v145 offset:33792
	ds_read_b128 v[216:219], v144 offset:32768
	ds_read_b128 v[220:223], v144 offset:33792
	global_load_lds_dwordx4 v171, s[86:87] offset:128
	s_add_i32 m0, s100, 0x5f80
	s_nop 0
	global_load_lds_dwordx4 v172, s[86:87] offset:128
	s_waitcnt lgkmcnt(8)
	s_barrier
	s_waitcnt lgkmcnt(0)
	v_mfma_f32_16x16x32_bf16 v[124:127], v[190:193], v[174:177], v[124:127]
	v_mfma_f32_16x16x32_bf16 v[120:123], v[190:193], v[182:185], v[120:123]
	v_mfma_f32_16x16x32_bf16 v[116:119], v[200:203], v[174:177], v[116:119]
	v_mfma_f32_16x16x32_bf16 v[112:115], v[200:203], v[182:185], v[112:115]
	v_mfma_f32_16x16x32_bf16 v[108:111], v[208:211], v[174:177], v[108:111]
	v_mfma_f32_16x16x32_bf16 v[104:107], v[208:211], v[182:185], v[104:107]
	v_mfma_f32_16x16x32_bf16 v[100:103], v[216:219], v[174:177], v[100:103]
	v_mfma_f32_16x16x32_bf16 v[96:99], v[216:219], v[182:185], v[96:99]
	v_mfma_f32_16x16x32_bf16 v[124:127], v[196:199], v[178:181], v[124:127]
	v_mfma_f32_16x16x32_bf16 v[120:123], v[196:199], v[186:189], v[120:123]
	v_mfma_f32_16x16x32_bf16 v[116:119], v[204:207], v[178:181], v[116:119]
	v_mfma_f32_16x16x32_bf16 v[112:115], v[204:207], v[186:189], v[112:115]
	v_mfma_f32_16x16x32_bf16 v[108:111], v[212:215], v[178:181], v[108:111]
	v_mfma_f32_16x16x32_bf16 v[104:107], v[212:215], v[186:189], v[104:107]
	v_mfma_f32_16x16x32_bf16 v[100:103], v[220:223], v[178:181], v[100:103]
	v_mfma_f32_16x16x32_bf16 v[96:99], v[220:223], v[186:189], v[96:99]
	s_barrier
	s_add_i32 m0, s100, 0x17f80
	ds_read_b128 v[224:227], v148
	ds_read_b128 v[228:231], v148 offset:1024
	ds_read_b128 v[232:235], v148 offset:2048
	ds_read_b128 v[236:239], v148 offset:3072
	global_load_lds_dwordx4 v158, s[86:87] offset:128
	s_add_i32 m0, s100, 0x19f80
	s_nop 0
	global_load_lds_dwordx4 v159, s[86:87] offset:128
	s_barrier
	s_waitcnt lgkmcnt(0)
	v_mfma_f32_16x16x32_bf16 v[92:95], v[190:193], v[224:227], v[92:95]
	v_mfma_f32_16x16x32_bf16 v[88:91], v[190:193], v[232:235], v[88:91]
	v_mfma_f32_16x16x32_bf16 v[84:87], v[200:203], v[224:227], v[84:87]
	v_mfma_f32_16x16x32_bf16 v[80:83], v[200:203], v[232:235], v[80:83]
	v_mfma_f32_16x16x32_bf16 v[76:79], v[208:211], v[224:227], v[76:79]
	v_mfma_f32_16x16x32_bf16 v[72:75], v[208:211], v[232:235], v[72:75]
	v_mfma_f32_16x16x32_bf16 v[68:71], v[216:219], v[224:227], v[68:71]
	v_mfma_f32_16x16x32_bf16 v[64:67], v[216:219], v[232:235], v[64:67]
	v_mfma_f32_16x16x32_bf16 v[92:95], v[196:199], v[228:231], v[92:95]
	v_mfma_f32_16x16x32_bf16 v[88:91], v[196:199], v[236:239], v[88:91]
	v_mfma_f32_16x16x32_bf16 v[84:87], v[204:207], v[228:231], v[84:87]
	v_mfma_f32_16x16x32_bf16 v[80:83], v[204:207], v[236:239], v[80:83]
	v_mfma_f32_16x16x32_bf16 v[76:79], v[212:215], v[228:231], v[76:79]
	v_mfma_f32_16x16x32_bf16 v[72:75], v[212:215], v[236:239], v[72:75]
	v_mfma_f32_16x16x32_bf16 v[68:71], v[220:223], v[228:231], v[68:71]
	v_mfma_f32_16x16x32_bf16 v[64:67], v[220:223], v[236:239], v[64:67]
	s_add_i32 m0, s100, 0x7f80
	s_barrier
	ds_read_b128 v[190:193], v147 offset:49152
	ds_read_b128 v[196:199], v147 offset:50176
	ds_read_b128 v[200:203], v146 offset:49152
	ds_read_b128 v[204:207], v146 offset:50176
	ds_read_b128 v[208:211], v145 offset:49152
	ds_read_b128 v[212:215], v145 offset:50176
	ds_read_b128 v[216:219], v144 offset:49152
	ds_read_b128 v[220:223], v144 offset:50176
	global_load_lds_dwordx4 v170, s[86:87] offset:128
	s_add_i32 m0, s100, 0x9f80
	s_nop 0
	global_load_lds_dwordx4 v248, s[86:87] offset:128
	s_barrier
	s_waitcnt lgkmcnt(0)
	v_mfma_f32_16x16x32_bf16 v[60:63], v[190:193], v[174:177], v[60:63]
	v_mfma_f32_16x16x32_bf16 v[56:59], v[190:193], v[182:185], v[56:59]
	v_mfma_f32_16x16x32_bf16 v[52:55], v[200:203], v[174:177], v[52:55]
	v_mfma_f32_16x16x32_bf16 v[48:51], v[200:203], v[182:185], v[48:51]
	v_mfma_f32_16x16x32_bf16 v[44:47], v[208:211], v[174:177], v[44:47]
	v_mfma_f32_16x16x32_bf16 v[40:43], v[208:211], v[182:185], v[40:43]
	v_mfma_f32_16x16x32_bf16 v[36:39], v[216:219], v[174:177], v[36:39]
	v_mfma_f32_16x16x32_bf16 v[32:35], v[216:219], v[182:185], v[32:35]
	v_mfma_f32_16x16x32_bf16 v[60:63], v[196:199], v[178:181], v[60:63]
	v_mfma_f32_16x16x32_bf16 v[56:59], v[196:199], v[186:189], v[56:59]
	v_mfma_f32_16x16x32_bf16 v[52:55], v[204:207], v[178:181], v[52:55]
	v_mfma_f32_16x16x32_bf16 v[48:51], v[204:207], v[186:189], v[48:51]
	v_mfma_f32_16x16x32_bf16 v[44:47], v[212:215], v[178:181], v[44:47]
	v_mfma_f32_16x16x32_bf16 v[40:43], v[212:215], v[186:189], v[40:43]
	v_mfma_f32_16x16x32_bf16 v[36:39], v[220:223], v[178:181], v[36:39]
	v_mfma_f32_16x16x32_bf16 v[32:35], v[220:223], v[186:189], v[32:35]
	s_barrier
; #define P8_STAGE(P,BASE,br,kt) do{const bfr* _ub=(BASE)+((long)(br)*K+(long)(kt)*BK); \
;     __builtin_amdgcn_global_load_lds((const unsigned*)(_ub+so0),(unsigned*)((char*)(P)+wid*1024),16,0,0); \
;     __builtin_amdgcn_global_load_lds((const unsigned*)(_ub+so1),(unsigned*)((char*)(P)+wid*1024+8192),16,0,0);}while(0)
; #define P8_LDA(dst,b,h) _Pragma("unroll") for(int m=0;m<4;++m) _Pragma("unroll") for(int k=0;k<2;++k) \
;     dst[m][k]=*reinterpret_cast<const bf16x8*>((char*)P8_SA(b,h)+lds_byte(wr*64+m*16+fr,k*32+fq*8))
; #define P8_LDB(dst,b,h) _Pragma("unroll") for(int n=0;n<2;++n) _Pragma("unroll") for(int k=0;k<2;++k) \
;     dst[n][k]=*reinterpret_cast<const bf16x8*>((char*)P8_SB(b,h)+lds_byte(wc*32+n*16+fr,k*32+fq*8))
; #define P8_MMA(ai,bj,At,Bt) do{__builtin_amdgcn_s_setprio(1); \
;     _Pragma("unroll") for(int m=0;m<4;++m) _Pragma("unroll") for(int n=0;n<2;++n) _Pragma("unroll") for(int k=0;k<2;++k) \
;       acc[ai][bj][m][n]=__builtin_amdgcn_mfma_f32_16x16x32_bf16(At[m][k],Bt[n][k],acc[ai][bj][m][n],0,0,0); \
;     __builtin_amdgcn_s_setprio(0);}while(0)
; #define P8_WAIT_V(n) asm volatile("s_waitcnt vmcnt(" #n ")":::"memory")
; #define P8_WAIT_L(n) asm volatile("s_waitcnt lgkmcnt(" #n ")":::"memory")
; #define P8_BAR __builtin_amdgcn_s_barrier()
; #define P8_SCHED __builtin_amdgcn_sched_barrier(0)
; template <class EPI>
; DEVI void gemm8_tile(const bfr* __restrict__ A, const bfr* __restrict__ Bt, int K, int brow, int bcol, int nbrow, int nbcol, char* shmc, EPI epi) {
;     ...
;     P8_BAR; P8_WAIT_L(0); P8_MMA(1,0,At,B0); P8_BAR; P8_SCHED;
;     P8_STAGE(P8_SB(1,1),Bt,bcol+128,t+3);
;     P8_WAIT_V(6); P8_BAR; P8_MMA(1,1,At,B1); P8_BAR;
;   }
;   { P8_LDB(B0,0,0); P8_LDA(At,0,0); P8_STAGE(P8_SA(1,1),A,brow+128,nt-1);
;     P8_BAR; P8_WAIT_L(0); P8_MMA(0,0,At,B0); P8_BAR;
;     P8_LDB(B1,0,1); P8_BAR; P8_WAIT_L(0); P8_MMA(0,1,At,B1); P8_BAR;
	s_add_i32 m0, s100, 0x1bf80
	s_nop 0
	global_load_lds_dwordx4 v240, s[86:87] offset:128
	v_add_u32_e32 v174, s78, v134
	s_add_i32 m0, s100, 0x1e000
	s_nop 0
	global_load_lds_dwordx4 v174, s[86:87]
	s_waitcnt vmcnt(6)
	s_barrier
	v_mfma_f32_16x16x32_bf16 v[28:31], v[190:193], v[224:227], v[28:31]
	v_mfma_f32_16x16x32_bf16 v[24:27], v[190:193], v[232:235], v[24:27]
	v_mfma_f32_16x16x32_bf16 v[20:23], v[200:203], v[224:227], v[20:23]
	v_mfma_f32_16x16x32_bf16 v[16:19], v[200:203], v[232:235], v[16:19]
	v_mfma_f32_16x16x32_bf16 v[12:15], v[208:211], v[224:227], v[12:15]
	v_mfma_f32_16x16x32_bf16 v[8:11], v[208:211], v[232:235], v[8:11]
	v_mfma_f32_16x16x32_bf16 v[4:7], v[216:219], v[224:227], v[4:7]
	v_mfma_f32_16x16x32_bf16 v[0:3], v[216:219], v[232:235], v[0:3]
	v_mfma_f32_16x16x32_bf16 v[28:31], v[196:199], v[228:231], v[28:31]
	v_mfma_f32_16x16x32_bf16 v[24:27], v[196:199], v[236:239], v[24:27]
	v_mfma_f32_16x16x32_bf16 v[20:23], v[204:207], v[228:231], v[20:23]
	v_mfma_f32_16x16x32_bf16 v[16:19], v[204:207], v[236:239], v[16:19]
	v_mfma_f32_16x16x32_bf16 v[12:15], v[212:215], v[228:231], v[12:15]
	v_mfma_f32_16x16x32_bf16 v[8:11], v[212:215], v[236:239], v[8:11]
	v_mfma_f32_16x16x32_bf16 v[4:7], v[220:223], v[228:231], v[4:7]
	v_mfma_f32_16x16x32_bf16 v[0:3], v[220:223], v[236:239], v[0:3]
	s_add_i32 s0, s0, 2
	v_lshl_add_u64 v[134:135], v[134:135], 0, s[80:81]
	v_lshl_add_u64 v[136:137], v[136:137], 0, s[80:81]
	v_lshl_add_u64 v[138:139], v[138:139], 0, s[80:81]
	s_cmp_lt_u32 s0, 28
	v_lshl_add_u64 v[140:141], v[140:141], 0, s[80:81]
	s_barrier
	s_cbranch_scc1 .LBB0_286
	v_add_u32_e32 v171, 0xc000, v143
	v_add_u32_e32 v172, 0xe000, v143
	v_add_u32_e32 v158, 0x10000, v143
	v_add_u32_e32 v159, 0x12000, v143
	v_add_u32_e32 v160, 0x2000, v143
	v_add_u32_e32 v161, 0x14000, v143
	v_add_u32_e32 v162, 0x16000, v143
	v_add_u32_e32 v163, 0x4000, v143
	v_add_u32_e32 v170, 0x6000, v143
	s_or_b32 s0, s8, 0x80
	s_ashr_i32 s1, s0, 31
	s_lshl_b64 s[0:1], s[0:1], 12
	s_add_u32 s0, s29, s0
	s_addc_u32 s1, s68, s1
	ds_read_b128 v[134:137], v157
	ds_read_b128 v[138:141], v157 offset:1024
	ds_read_b128 v[150:153], v157 offset:2048
	ds_read_b128 v[174:177], v157 offset:3072
	ds_read_b128 v[178:181], v147
	ds_read_b128 v[182:185], v147 offset:1024
	ds_read_b128 v[186:189], v146
	ds_read_b128 v[190:193], v146 offset:1024
	ds_read_b128 v[196:199], v145
	ds_read_b128 v[200:203], v145 offset:1024
	ds_read_b128 v[204:207], v144
	ds_read_b128 v[208:211], v144 offset:1024
	v_lshl_add_u64 v[156:157], v[166:167], 1, s[0:1]
	s_mov_b64 s[54:55], 0xf80
	v_lshl_add_u64 v[156:157], v[156:157], 0, s[54:55]
	s_add_i32 m0, s100, 0xc000
	v_lshl_add_u64 v[132:133], v[132:133], 1, s[0:1]
	global_load_lds_dwordx4 v[156:157], off
	v_lshl_add_u64 v[132:133], v[132:133], 0, s[54:55]
	s_add_i32 m0, s100, 0xe000
	s_nop 0
	global_load_lds_dwordx4 v[132:133], off
	s_barrier
	s_waitcnt lgkmcnt(0)
	s_setprio 1
	s_waitcnt lgkmcnt(0)
	v_mfma_f32_16x16x32_bf16 v[124:127], v[178:181], v[134:137], v[124:127]
	v_mfma_f32_16x16x32_bf16 v[116:119], v[186:189], v[134:137], v[116:119]
	v_mfma_f32_16x16x32_bf16 v[112:115], v[186:189], v[150:153], v[112:115]
	v_mfma_f32_16x16x32_bf16 v[96:99], v[204:207], v[150:153], v[96:99]
	v_mfma_f32_16x16x32_bf16 v[124:127], v[182:185], v[138:141], v[124:127]
	v_mfma_f32_16x16x32_bf16 v[120:123], v[178:181], v[150:153], v[120:123]
	v_mfma_f32_16x16x32_bf16 v[116:119], v[190:193], v[138:141], v[116:119]
	v_mfma_f32_16x16x32_bf16 v[112:115], v[190:193], v[174:177], v[112:115]
	v_mfma_f32_16x16x32_bf16 v[108:111], v[196:199], v[134:137], v[108:111]
	v_mfma_f32_16x16x32_bf16 v[104:107], v[196:199], v[150:153], v[104:107]
	v_mfma_f32_16x16x32_bf16 v[100:103], v[204:207], v[134:137], v[100:103]
	v_mfma_f32_16x16x32_bf16 v[96:99], v[208:211], v[174:177], v[96:99]
	v_mfma_f32_16x16x32_bf16 v[212:215], v[182:185], v[174:177], v[120:123]
	v_mfma_f32_16x16x32_bf16 v[216:219], v[200:203], v[138:141], v[108:111]
	v_mfma_f32_16x16x32_bf16 v[220:223], v[200:203], v[174:177], v[104:107]
	v_mfma_f32_16x16x32_bf16 v[224:227], v[208:211], v[138:141], v[100:103]
	s_setprio 0
	s_barrier
	s_nop 0
	ds_read_b128 v[100:103], v155
	ds_read_b128 v[104:107], v155 offset:1024
	ds_read_b128 v[108:111], v155 offset:2048
	ds_read_b128 v[120:123], v155 offset:3072
	s_barrier
	s_waitcnt lgkmcnt(0)
	s_setprio 1
	s_waitcnt lgkmcnt(0)
	v_mfma_f32_16x16x32_bf16 v[92:95], v[178:181], v[100:103], v[92:95]
	v_mfma_f32_16x16x32_bf16 v[84:87], v[186:189], v[100:103], v[84:87]
	v_mfma_f32_16x16x32_bf16 v[80:83], v[186:189], v[108:111], v[80:83]
	v_mfma_f32_16x16x32_bf16 v[64:67], v[204:207], v[108:111], v[64:67]
	v_mfma_f32_16x16x32_bf16 v[92:95], v[182:185], v[104:107], v[92:95]
	v_mfma_f32_16x16x32_bf16 v[88:91], v[178:181], v[108:111], v[88:91]
	v_mfma_f32_16x16x32_bf16 v[84:87], v[190:193], v[104:107], v[84:87]
	v_mfma_f32_16x16x32_bf16 v[80:83], v[190:193], v[120:123], v[80:83]
	v_mfma_f32_16x16x32_bf16 v[76:79], v[196:199], v[100:103], v[76:79]
	v_mfma_f32_16x16x32_bf16 v[72:75], v[196:199], v[108:111], v[72:75]
	v_mfma_f32_16x16x32_bf16 v[68:71], v[204:207], v[100:103], v[68:71]
	v_mfma_f32_16x16x32_bf16 v[64:67], v[208:211], v[120:123], v[64:67]
	v_mfma_f32_16x16x32_bf16 v[154:157], v[182:185], v[120:123], v[88:91]
	v_mfma_f32_16x16x32_bf16 v[178:181], v[200:203], v[104:107], v[76:79]
	v_mfma_f32_16x16x32_bf16 v[182:185], v[200:203], v[120:123], v[72:75]
	v_mfma_f32_16x16x32_bf16 v[186:189], v[208:211], v[104:107], v[68:71]
	s_setprio 0
	s_barrier
; #define P8_LDA(dst,b,h) _Pragma("unroll") for(int m=0;m<4;++m) _Pragma("unroll") for(int k=0;k<2;++k) \
;     dst[m][k]=*reinterpret_cast<const bf16x8*>((char*)P8_SA(b,h)+lds_byte(wr*64+m*16+fr,k*32+fq*8))
; #define P8_LDB(dst,b,h) _Pragma("unroll") for(int n=0;n<2;++n) _Pragma("unroll") for(int k=0;k<2;++k) \
;     dst[n][k]=*reinterpret_cast<const bf16x8*>((char*)P8_SB(b,h)+lds_byte(wc*32+n*16+fr,k*32+fq*8))
; #define P8_MMA(ai,bj,At,Bt) do{__builtin_amdgcn_s_setprio(1); \
;     _Pragma("unroll") for(int m=0;m<4;++m) _Pragma("unroll") for(int n=0;n<2;++n) _Pragma("unroll") for(int k=0;k<2;++k) \
;       acc[ai][bj][m][n]=__builtin_amdgcn_mfma_f32_16x16x32_bf16(At[m][k],Bt[n][k],acc[ai][bj][m][n],0,0,0); \
;     __builtin_amdgcn_s_setprio(0);}while(0)
; #define P8_WAIT_V(n) asm volatile("s_waitcnt vmcnt(" #n ")":::"memory")
; #define P8_WAIT_L(n) asm volatile("s_waitcnt lgkmcnt(" #n ")":::"memory")
; #define P8_BAR __builtin_amdgcn_s_barrier()
; template <class EPI>
; DEVI void gemm8_tile(const bfr* __restrict__ A, const bfr* __restrict__ Bt, int K, int brow, int bcol, int nbrow, int nbcol, char* shmc, EPI epi) {
;     ...
;     P8_LDA(At,0,1); P8_WAIT_V(4); P8_BAR; P8_WAIT_L(0); P8_MMA(1,0,At,B0); P8_MMA(1,1,At,B1); P8_BAR; }
;   { P8_LDB(B0,1,0); P8_LDA(At,1,0); P8_WAIT_V(2); P8_BAR; P8_WAIT_L(0); P8_MMA(0,0,At,B0); P8_BAR;
	s_nop 0
	ds_read_b128 v[68:71], v147 offset:16384
	ds_read_b128 v[72:75], v147 offset:17408
	ds_read_b128 v[76:79], v146 offset:16384
	ds_read_b128 v[88:91], v146 offset:17408
	ds_read_b128 v[190:193], v145 offset:16384
	ds_read_b128 v[196:199], v145 offset:17408
	ds_read_b128 v[200:203], v144 offset:16384
	ds_read_b128 v[204:207], v144 offset:17408
	s_waitcnt vmcnt(4)
	s_barrier
	s_waitcnt lgkmcnt(0)
	s_setprio 1
	s_waitcnt lgkmcnt(0)
	v_mfma_f32_16x16x32_bf16 v[60:63], v[68:71], v[134:137], v[60:63]
	v_mfma_f32_16x16x32_bf16 v[52:55], v[76:79], v[134:137], v[52:55]
	v_mfma_f32_16x16x32_bf16 v[48:51], v[76:79], v[150:153], v[48:51]
	v_mfma_f32_16x16x32_bf16 v[32:35], v[200:203], v[150:153], v[32:35]
	v_mfma_f32_16x16x32_bf16 v[60:63], v[72:75], v[138:141], v[60:63]
	v_mfma_f32_16x16x32_bf16 v[56:59], v[68:71], v[150:153], v[56:59]
	v_mfma_f32_16x16x32_bf16 v[52:55], v[88:91], v[138:141], v[52:55]
	v_mfma_f32_16x16x32_bf16 v[48:51], v[88:91], v[174:177], v[48:51]
	v_mfma_f32_16x16x32_bf16 v[44:47], v[190:193], v[134:137], v[44:47]
	v_mfma_f32_16x16x32_bf16 v[40:43], v[190:193], v[150:153], v[40:43]
	v_mfma_f32_16x16x32_bf16 v[36:39], v[200:203], v[134:137], v[36:39]
	v_mfma_f32_16x16x32_bf16 v[32:35], v[204:207], v[174:177], v[32:35]
	v_mfma_f32_16x16x32_bf16 v[208:211], v[72:75], v[174:177], v[56:59]
	v_mfma_f32_16x16x32_bf16 v[228:231], v[196:199], v[138:141], v[44:47]
	v_mfma_f32_16x16x32_bf16 v[232:235], v[196:199], v[174:177], v[40:43]
	v_mfma_f32_16x16x32_bf16 v[132:135], v[204:207], v[138:141], v[36:39]
	s_setprio 0
	s_setprio 1
	v_mfma_f32_16x16x32_bf16 v[28:31], v[68:71], v[100:103], v[28:31]
	v_mfma_f32_16x16x32_bf16 v[20:23], v[76:79], v[100:103], v[20:23]
	v_mfma_f32_16x16x32_bf16 v[16:19], v[76:79], v[108:111], v[16:19]
	v_mfma_f32_16x16x32_bf16 v[0:3], v[200:203], v[108:111], v[0:3]
	v_mfma_f32_16x16x32_bf16 v[28:31], v[72:75], v[104:107], v[28:31]
	v_mfma_f32_16x16x32_bf16 v[24:27], v[68:71], v[108:111], v[24:27]
	v_mfma_f32_16x16x32_bf16 v[20:23], v[88:91], v[104:107], v[20:23]
	v_mfma_f32_16x16x32_bf16 v[16:19], v[88:91], v[120:123], v[16:19]
	v_mfma_f32_16x16x32_bf16 v[12:15], v[190:193], v[100:103], v[12:15]
	v_mfma_f32_16x16x32_bf16 v[8:11], v[190:193], v[108:111], v[8:11]
	v_mfma_f32_16x16x32_bf16 v[4:7], v[200:203], v[100:103], v[4:7]
	v_mfma_f32_16x16x32_bf16 v[0:3], v[204:207], v[120:123], v[0:3]
	v_mfma_f32_16x16x32_bf16 v[136:139], v[72:75], v[120:123], v[24:27]
	v_mfma_f32_16x16x32_bf16 v[150:153], v[196:199], v[104:107], v[12:15]
	v_mfma_f32_16x16x32_bf16 v[172:175], v[196:199], v[120:123], v[8:11]
	v_mfma_f32_16x16x32_bf16 v[190:193], v[204:207], v[104:107], v[4:7]
	s_setprio 0
	s_barrier
	s_nop 0
	ds_read_b128 v[4:7], v149
	ds_read_b128 v[8:11], v149 offset:1024
	ds_read_b128 v[12:15], v149 offset:2048
	ds_read_b128 v[24:27], v149 offset:3072
	ds_read_b128 v[36:39], v147 offset:32768
	ds_read_b128 v[40:43], v147 offset:33792
	ds_read_b128 v[44:47], v146 offset:32768
	ds_read_b128 v[56:59], v146 offset:33792
	ds_read_b128 v[68:71], v145 offset:32768
	ds_read_b128 v[196:199], v145 offset:33792
	ds_read_b128 v[200:203], v144 offset:32768
	ds_read_b128 v[204:207], v144 offset:33792
	s_waitcnt vmcnt(2)
	s_barrier
	s_waitcnt lgkmcnt(0)
	s_setprio 1
	s_waitcnt lgkmcnt(0)
	v_mfma_f32_16x16x32_bf16 v[72:75], v[36:39], v[4:7], v[124:127]
	v_mfma_f32_16x16x32_bf16 v[120:123], v[40:43], v[8:11], v[72:75]
	v_mfma_f32_16x16x32_bf16 v[72:75], v[36:39], v[12:15], v[212:215]
	v_mfma_f32_16x16x32_bf16 v[104:107], v[40:43], v[24:27], v[72:75]
	v_mfma_f32_16x16x32_bf16 v[72:75], v[44:47], v[4:7], v[116:119]
	v_mfma_f32_16x16x32_bf16 v[124:127], v[56:59], v[8:11], v[72:75]
	v_mfma_f32_16x16x32_bf16 v[72:75], v[44:47], v[12:15], v[112:115]
	v_mfma_f32_16x16x32_bf16 v[108:111], v[56:59], v[24:27], v[72:75]
	v_mfma_f32_16x16x32_bf16 v[72:75], v[68:71], v[4:7], v[216:219]
	v_mfma_f32_16x16x32_bf16 v[112:115], v[196:199], v[8:11], v[72:75]
	v_mfma_f32_16x16x32_bf16 v[72:75], v[68:71], v[12:15], v[220:223]
	v_mfma_f32_16x16x32_bf16 v[100:103], v[196:199], v[24:27], v[72:75]
	v_mfma_f32_16x16x32_bf16 v[72:75], v[200:203], v[4:7], v[224:227]
	v_mfma_f32_16x16x32_bf16 v[116:119], v[204:207], v[8:11], v[72:75]
	v_mfma_f32_16x16x32_bf16 v[72:75], v[200:203], v[12:15], v[96:99]
	v_mfma_f32_16x16x32_bf16 v[96:99], v[204:207], v[24:27], v[72:75]
	s_setprio 0
	s_barrier
; #define P8_LDA(dst,b,h) _Pragma("unroll") for(int m=0;m<4;++m) _Pragma("unroll") for(int k=0;k<2;++k) \
;     dst[m][k]=*reinterpret_cast<const bf16x8*>((char*)P8_SA(b,h)+lds_byte(wr*64+m*16+fr,k*32+fq*8))
; #define P8_LDB(dst,b,h) _Pragma("unroll") for(int n=0;n<2;++n) _Pragma("unroll") for(int k=0;k<2;++k) \
;     dst[n][k]=*reinterpret_cast<const bf16x8*>((char*)P8_SB(b,h)+lds_byte(wc*32+n*16+fr,k*32+fq*8))
; #define P8_MMA(ai,bj,At,Bt) do{__builtin_amdgcn_s_setprio(1); \
;     _Pragma("unroll") for(int m=0;m<4;++m) _Pragma("unroll") for(int n=0;n<2;++n) _Pragma("unroll") for(int k=0;k<2;++k) \
;       acc[ai][bj][m][n]=__builtin_amdgcn_mfma_f32_16x16x32_bf16(At[m][k],Bt[n][k],acc[ai][bj][m][n],0,0,0); \
;     __builtin_amdgcn_s_setprio(0);}while(0)
; #define P8_WAIT_V(n) asm volatile("s_waitcnt vmcnt(" #n ")":::"memory")
; #define P8_WAIT_L(n) asm volatile("s_waitcnt lgkmcnt(" #n ")":::"memory")
; #define P8_BAR __builtin_amdgcn_s_barrier()
; template <class EPI>
; DEVI void gemm8_tile(const bfr* __restrict__ A, const bfr* __restrict__ Bt, int K, int brow, int bcol, int nbrow, int nbcol, char* shmc, EPI epi) {
;     ...
;     P8_LDB(B1,1,1); P8_WAIT_V(0); P8_BAR; P8_WAIT_L(0); P8_MMA(0,1,At,B1); P8_BAR;
;     P8_LDA(At,1,1); P8_BAR; P8_WAIT_L(0); P8_MMA(1,0,At,B0); P8_MMA(1,1,At,B1); P8_BAR; }
;   if(wr==0)P8_BAR;
	ds_read_b128 v[212:215], v148
	ds_read_b128 v[216:219], v148 offset:1024
	ds_read_b128 v[220:223], v148 offset:2048
	ds_read_b128 v[224:227], v148 offset:3072
	s_waitcnt vmcnt(0)
	s_barrier
	s_waitcnt lgkmcnt(0)
	s_setprio 1
	s_waitcnt lgkmcnt(0)
	v_mfma_f32_16x16x32_bf16 v[72:75], v[36:39], v[212:215], v[92:95]
	v_mfma_f32_16x16x32_bf16 v[36:39], v[36:39], v[220:223], v[154:157]
	v_mfma_f32_16x16x32_bf16 v[88:91], v[40:43], v[216:219], v[72:75]
	v_mfma_f32_16x16x32_bf16 v[72:75], v[40:43], v[224:227], v[36:39]
	v_mfma_f32_16x16x32_bf16 v[36:39], v[44:47], v[212:215], v[84:87]
	v_mfma_f32_16x16x32_bf16 v[92:95], v[56:59], v[216:219], v[36:39]
	v_mfma_f32_16x16x32_bf16 v[36:39], v[44:47], v[220:223], v[80:83]
	v_mfma_f32_16x16x32_bf16 v[76:79], v[56:59], v[224:227], v[36:39]
	v_mfma_f32_16x16x32_bf16 v[36:39], v[68:71], v[212:215], v[178:181]
	v_mfma_f32_16x16x32_bf16 v[80:83], v[196:199], v[216:219], v[36:39]
	v_mfma_f32_16x16x32_bf16 v[36:39], v[68:71], v[220:223], v[182:185]
	v_mfma_f32_16x16x32_bf16 v[68:71], v[196:199], v[224:227], v[36:39]
	v_mfma_f32_16x16x32_bf16 v[36:39], v[200:203], v[212:215], v[186:189]
	v_mfma_f32_16x16x32_bf16 v[84:87], v[204:207], v[216:219], v[36:39]
	v_mfma_f32_16x16x32_bf16 v[36:39], v[200:203], v[220:223], v[64:67]
	v_mfma_f32_16x16x32_bf16 v[64:67], v[204:207], v[224:227], v[36:39]
	s_setprio 0
	s_barrier
	ds_read_b128 v[154:157], v147 offset:49152
	ds_read_b128 v[176:179], v147 offset:50176
	ds_read_b128 v[180:183], v146 offset:49152
	ds_read_b128 v[146:149], v146 offset:50176
	ds_read_b128 v[184:187], v145 offset:49152
	ds_read_b128 v[196:199], v145 offset:50176
	ds_read_b128 v[200:203], v144 offset:49152
	ds_read_b128 v[204:207], v144 offset:50176
	s_barrier
	s_waitcnt lgkmcnt(0)
	s_setprio 1
	s_waitcnt lgkmcnt(0)
	v_mfma_f32_16x16x32_bf16 v[36:39], v[154:157], v[4:7], v[60:63]
	v_mfma_f32_16x16x32_bf16 v[56:59], v[176:179], v[8:11], v[36:39]
	v_mfma_f32_16x16x32_bf16 v[36:39], v[154:157], v[12:15], v[208:211]
	v_mfma_f32_16x16x32_bf16 v[40:43], v[176:179], v[24:27], v[36:39]
	v_mfma_f32_16x16x32_bf16 v[36:39], v[180:183], v[4:7], v[52:55]
	v_mfma_f32_16x16x32_bf16 v[60:63], v[146:149], v[8:11], v[36:39]
	v_mfma_f32_16x16x32_bf16 v[36:39], v[180:183], v[12:15], v[48:51]
	v_mfma_f32_16x16x32_bf16 v[44:47], v[146:149], v[24:27], v[36:39]
	v_mfma_f32_16x16x32_bf16 v[36:39], v[184:187], v[4:7], v[228:231]
	v_mfma_f32_16x16x32_bf16 v[4:7], v[200:203], v[4:7], v[132:135]
	v_mfma_f32_16x16x32_bf16 v[48:51], v[196:199], v[8:11], v[36:39]
	v_mfma_f32_16x16x32_bf16 v[36:39], v[184:187], v[12:15], v[232:235]
	v_mfma_f32_16x16x32_bf16 v[52:55], v[204:207], v[8:11], v[4:7]
	v_mfma_f32_16x16x32_bf16 v[4:7], v[200:203], v[12:15], v[32:35]
	v_mfma_f32_16x16x32_bf16 v[36:39], v[196:199], v[24:27], v[36:39]
	v_mfma_f32_16x16x32_bf16 v[32:35], v[204:207], v[24:27], v[4:7]
	s_setprio 0
	s_setprio 1
	v_mfma_f32_16x16x32_bf16 v[4:7], v[154:157], v[212:215], v[28:31]
	v_mfma_f32_16x16x32_bf16 v[24:27], v[176:179], v[216:219], v[4:7]
	v_mfma_f32_16x16x32_bf16 v[4:7], v[154:157], v[220:223], v[136:139]
	v_mfma_f32_16x16x32_bf16 v[8:11], v[176:179], v[224:227], v[4:7]
	v_mfma_f32_16x16x32_bf16 v[4:7], v[180:183], v[212:215], v[20:23]
	v_mfma_f32_16x16x32_bf16 v[28:31], v[146:149], v[216:219], v[4:7]
	v_mfma_f32_16x16x32_bf16 v[4:7], v[180:183], v[220:223], v[16:19]
	v_mfma_f32_16x16x32_bf16 v[12:15], v[146:149], v[224:227], v[4:7]
	v_mfma_f32_16x16x32_bf16 v[4:7], v[184:187], v[212:215], v[150:153]
	v_mfma_f32_16x16x32_bf16 v[16:19], v[196:199], v[216:219], v[4:7]
	v_mfma_f32_16x16x32_bf16 v[4:7], v[184:187], v[220:223], v[172:175]
	v_mfma_f32_16x16x32_bf16 v[20:23], v[200:203], v[212:215], v[190:193]
	v_mfma_f32_16x16x32_bf16 v[0:3], v[200:203], v[220:223], v[0:3]
	v_mfma_f32_16x16x32_bf16 v[4:7], v[196:199], v[224:227], v[4:7]
	v_mfma_f32_16x16x32_bf16 v[20:23], v[204:207], v[216:219], v[20:23]
	v_mfma_f32_16x16x32_bf16 v[0:3], v[204:207], v[224:227], v[0:3]
	s_setprio 0
	v_cmp_gt_u32_e32 vcc, s57, v142
	s_barrier
	s_and_saveexec_b64 s[0:1], vcc
	s_cbranch_execz .LBB0_289
	s_barrier

; #define P8_STAGE(P,BASE,br,kt) do{const bfr* _ub=(BASE)+((long)(br)*K+(long)(kt)*BK); \
;     __builtin_amdgcn_global_load_lds((const unsigned*)(_ub+so0),(unsigned*)((char*)(P)+wid*1024),16,0,0); \
;     __builtin_amdgcn_global_load_lds((const unsigned*)(_ub+so1),(unsigned*)((char*)(P)+wid*1024+8192),16,0,0);}while(0)
; #define P8_LDA(dst,b,h) _Pragma("unroll") for(int m=0;m<4;++m) _Pragma("unroll") for(int k=0;k<2;++k) \
;     dst[m][k]=*reinterpret_cast<const bf16x8*>((char*)P8_SA(b,h)+lds_byte(wr*64+m*16+fr,k*32+fq*8))
; #define P8_LDB(dst,b,h) _Pragma("unroll") for(int n=0;n<2;++n) _Pragma("unroll") for(int k=0;k<2;++k) \
;     dst[n][k]=*reinterpret_cast<const bf16x8*>((char*)P8_SB(b,h)+lds_byte(wc*32+n*16+fr,k*32+fq*8))
; #define P8_MMA(ai,bj,At,Bt) do{__builtin_amdgcn_s_setprio(1); \
;     _Pragma("unroll") for(int m=0;m<4;++m) _Pragma("unroll") for(int n=0;n<2;++n) _Pragma("unroll") for(int k=0;k<2;++k) \
;       acc[ai][bj][m][n]=__builtin_amdgcn_mfma_f32_16x16x32_bf16(At[m][k],Bt[n][k],acc[ai][bj][m][n],0,0,0); \
;     __builtin_amdgcn_s_setprio(0);}while(0)
; #define P8_WAIT_V(n) asm volatile("s_waitcnt vmcnt(" #n ")":::"memory")
; #define P8_WAIT_L(n) asm volatile("s_waitcnt lgkmcnt(" #n ")":::"memory")
; #define P8_BAR __builtin_amdgcn_s_barrier()
; #define P8_SCHED __builtin_amdgcn_sched_barrier(0)
; template <class EPI>
; DEVI void gemm8_tile(const bfr* __restrict__ A, const bfr* __restrict__ Bt, int K, int brow, int bcol, int nbrow, int nbcol, char* shmc, EPI epi) {
;     ...
;     P8_LDB(B0,0,0); P8_SCHED; P8_LDA(At,0,0); P8_STAGE(P8_SA(1,1),A,brow+128,t+1);
;     P8_WAIT_L(8); P8_BAR; P8_WAIT_L(0); P8_MMA(0,0,At,B0); P8_BAR; P8_SCHED;
;     P8_LDB(B1,0,1); P8_STAGE(P8_SB(0,0),Bt,bcol,t+2);
;     P8_BAR; P8_WAIT_L(0); P8_MMA(0,1,At,B1); P8_BAR;
;     P8_LDA(At,0,1); P8_STAGE(P8_SA(0,0),A,brow,t+2);
;     P8_BAR; P8_WAIT_L(0); P8_MMA(1,0,At,B0); P8_BAR; P8_SCHED;
;     P8_STAGE(P8_SB(0,1),Bt,bcol+128,t+2);
;     P8_WAIT_V(6); P8_BAR; P8_MMA(1,1,At,B1); P8_BAR;
.LBB0_382:
	ds_read_b128 v[174:177], v157
	ds_read_b128 v[178:181], v157 offset:1024
	ds_read_b128 v[182:185], v157 offset:2048
	ds_read_b128 v[186:189], v157 offset:3072
	v_add_u32_e32 v171, s54, v140
	s_add_i32 m0, s100, 0xc000
	ds_read_b128 v[160:163], v147
	ds_read_b128 v[190:193], v147 offset:1024
	ds_read_b128 v[196:199], v146
	ds_read_b128 v[208:211], v146 offset:1024
	ds_read_b128 v[212:215], v145
	ds_read_b128 v[216:219], v145 offset:1024
	ds_read_b128 v[220:223], v144
	ds_read_b128 v[224:227], v144 offset:1024
	global_load_lds_dwordx4 v171, s[86:87]
	v_add_u32_e32 v172, s54, v138
	s_add_i32 m0, s100, 0xe000
	s_nop 0
	global_load_lds_dwordx4 v172, s[86:87]
	s_waitcnt lgkmcnt(8)
	s_barrier
	s_waitcnt lgkmcnt(0)
	v_mfma_f32_16x16x32_bf16 v[124:127], v[160:163], v[174:177], v[124:127]
	v_mfma_f32_16x16x32_bf16 v[120:123], v[160:163], v[182:185], v[120:123]
	v_mfma_f32_16x16x32_bf16 v[116:119], v[196:199], v[174:177], v[116:119]
	v_mfma_f32_16x16x32_bf16 v[112:115], v[196:199], v[182:185], v[112:115]
	v_mfma_f32_16x16x32_bf16 v[108:111], v[212:215], v[174:177], v[108:111]
	v_mfma_f32_16x16x32_bf16 v[104:107], v[212:215], v[182:185], v[104:107]
	v_mfma_f32_16x16x32_bf16 v[100:103], v[220:223], v[174:177], v[100:103]
	v_mfma_f32_16x16x32_bf16 v[96:99], v[220:223], v[182:185], v[96:99]
	v_mfma_f32_16x16x32_bf16 v[124:127], v[190:193], v[178:181], v[124:127]
	v_mfma_f32_16x16x32_bf16 v[120:123], v[190:193], v[186:189], v[120:123]
	v_mfma_f32_16x16x32_bf16 v[116:119], v[208:211], v[178:181], v[116:119]
	v_mfma_f32_16x16x32_bf16 v[112:115], v[208:211], v[186:189], v[112:115]
	v_mfma_f32_16x16x32_bf16 v[108:111], v[216:219], v[178:181], v[108:111]
	v_mfma_f32_16x16x32_bf16 v[104:107], v[216:219], v[186:189], v[104:107]
	v_mfma_f32_16x16x32_bf16 v[100:103], v[224:227], v[178:181], v[100:103]
	v_mfma_f32_16x16x32_bf16 v[96:99], v[224:227], v[186:189], v[96:99]
	s_barrier
	v_add_u32_e32 v158, s60, v136
	s_add_i32 m0, s100, 0x10000
	ds_read_b128 v[228:231], v154
	ds_read_b128 v[232:235], v154 offset:1024
	ds_read_b128 v[236:239], v154 offset:2048
	ds_read_b128 v[240:243], v154 offset:3072
	global_load_lds_dwordx4 v158, s[86:87]
	v_add_u32_e32 v159, s60, v134
	s_add_i32 m0, s100, 0x12000
	s_nop 0
	global_load_lds_dwordx4 v159, s[86:87]
	s_barrier
	s_waitcnt lgkmcnt(0)
	v_mfma_f32_16x16x32_bf16 v[92:95], v[160:163], v[228:231], v[92:95]
	v_mfma_f32_16x16x32_bf16 v[88:91], v[160:163], v[236:239], v[88:91]
	v_mfma_f32_16x16x32_bf16 v[84:87], v[196:199], v[228:231], v[84:87]
	v_mfma_f32_16x16x32_bf16 v[80:83], v[196:199], v[236:239], v[80:83]
	v_mfma_f32_16x16x32_bf16 v[76:79], v[212:215], v[228:231], v[76:79]
	v_mfma_f32_16x16x32_bf16 v[72:75], v[212:215], v[236:239], v[72:75]
	v_mfma_f32_16x16x32_bf16 v[68:71], v[220:223], v[228:231], v[68:71]
	v_mfma_f32_16x16x32_bf16 v[64:67], v[220:223], v[236:239], v[64:67]
	v_mfma_f32_16x16x32_bf16 v[92:95], v[190:193], v[232:235], v[92:95]
	v_mfma_f32_16x16x32_bf16 v[88:91], v[190:193], v[240:243], v[88:91]
	v_mfma_f32_16x16x32_bf16 v[84:87], v[208:211], v[232:235], v[84:87]
	v_mfma_f32_16x16x32_bf16 v[80:83], v[208:211], v[240:243], v[80:83]
	v_mfma_f32_16x16x32_bf16 v[76:79], v[216:219], v[232:235], v[76:79]
	v_mfma_f32_16x16x32_bf16 v[72:75], v[216:219], v[240:243], v[72:75]
	v_mfma_f32_16x16x32_bf16 v[68:71], v[224:227], v[232:235], v[68:71]
	v_mfma_f32_16x16x32_bf16 v[64:67], v[224:227], v[240:243], v[64:67]
	v_add_u32_e32 v170, s82, v140
	s_mov_b32 m0, s100
	s_barrier
	ds_read_b128 v[190:193], v147 offset:16384
	ds_read_b128 v[196:199], v147 offset:17408
	ds_read_b128 v[208:211], v146 offset:16384
	ds_read_b128 v[212:215], v146 offset:17408
	ds_read_b128 v[216:219], v145 offset:16384
	ds_read_b128 v[220:223], v145 offset:17408
	ds_read_b128 v[224:227], v144 offset:16384
	ds_read_b128 v[244:247], v144 offset:17408
	global_load_lds_dwordx4 v170, s[86:87]
	v_add_u32_e32 v206, s82, v138
	s_add_i32 m0, s100, 0x2000
	s_nop 0
	global_load_lds_dwordx4 v206, s[86:87]
	s_barrier
	s_waitcnt lgkmcnt(0)
	v_mfma_f32_16x16x32_bf16 v[60:63], v[190:193], v[174:177], v[60:63]
	v_mfma_f32_16x16x32_bf16 v[56:59], v[190:193], v[182:185], v[56:59]
	v_mfma_f32_16x16x32_bf16 v[52:55], v[208:211], v[174:177], v[52:55]
	v_mfma_f32_16x16x32_bf16 v[48:51], v[208:211], v[182:185], v[48:51]
	v_mfma_f32_16x16x32_bf16 v[44:47], v[216:219], v[174:177], v[44:47]
	v_mfma_f32_16x16x32_bf16 v[40:43], v[216:219], v[182:185], v[40:43]
	v_mfma_f32_16x16x32_bf16 v[36:39], v[224:227], v[174:177], v[36:39]
	v_mfma_f32_16x16x32_bf16 v[32:35], v[224:227], v[182:185], v[32:35]
	v_mfma_f32_16x16x32_bf16 v[60:63], v[196:199], v[178:181], v[60:63]
	v_mfma_f32_16x16x32_bf16 v[56:59], v[196:199], v[186:189], v[56:59]
	v_mfma_f32_16x16x32_bf16 v[52:55], v[212:215], v[178:181], v[52:55]
	v_mfma_f32_16x16x32_bf16 v[48:51], v[212:215], v[186:189], v[48:51]
	v_mfma_f32_16x16x32_bf16 v[44:47], v[220:223], v[178:181], v[44:47]
	v_mfma_f32_16x16x32_bf16 v[40:43], v[220:223], v[186:189], v[40:43]
	v_mfma_f32_16x16x32_bf16 v[36:39], v[244:247], v[178:181], v[36:39]
	v_mfma_f32_16x16x32_bf16 v[32:35], v[244:247], v[186:189], v[32:35]
	s_barrier
	v_add_u32_e32 v248, s92, v136
	s_add_i32 m0, s100, 0x14000
	v_add_u32_e32 v200, s92, v134
	global_load_lds_dwordx4 v248, s[86:87]
	s_nop 0
	s_add_i32 m0, s100, 0x16000
	s_nop 0
	global_load_lds_dwordx4 v200, s[86:87]
	s_waitcnt vmcnt(6)
	s_barrier
; #define P8_STAGE(P,BASE,br,kt) do{const bfr* _ub=(BASE)+((long)(br)*K+(long)(kt)*BK); \
;     __builtin_amdgcn_global_load_lds((const unsigned*)(_ub+so0),(unsigned*)((char*)(P)+wid*1024),16,0,0); \
;     __builtin_amdgcn_global_load_lds((const unsigned*)(_ub+so1),(unsigned*)((char*)(P)+wid*1024+8192),16,0,0);}while(0)
; #define P8_LDA(dst,b,h) _Pragma("unroll") for(int m=0;m<4;++m) _Pragma("unroll") for(int k=0;k<2;++k) \
;     dst[m][k]=*reinterpret_cast<const bf16x8*>((char*)P8_SA(b,h)+lds_byte(wr*64+m*16+fr,k*32+fq*8))
; #define P8_LDB(dst,b,h) _Pragma("unroll") for(int n=0;n<2;++n) _Pragma("unroll") for(int k=0;k<2;++k) \
;     dst[n][k]=*reinterpret_cast<const bf16x8*>((char*)P8_SB(b,h)+lds_byte(wc*32+n*16+fr,k*32+fq*8))
; #define P8_MMA(ai,bj,At,Bt) do{__builtin_amdgcn_s_setprio(1); \
;     _Pragma("unroll") for(int m=0;m<4;++m) _Pragma("unroll") for(int n=0;n<2;++n) _Pragma("unroll") for(int k=0;k<2;++k) \
;       acc[ai][bj][m][n]=__builtin_amdgcn_mfma_f32_16x16x32_bf16(At[m][k],Bt[n][k],acc[ai][bj][m][n],0,0,0); \
;     __builtin_amdgcn_s_setprio(0);}while(0)
; #define P8_WAIT_V(n) asm volatile("s_waitcnt vmcnt(" #n ")":::"memory")
; #define P8_WAIT_L(n) asm volatile("s_waitcnt lgkmcnt(" #n ")":::"memory")
; #define P8_BAR __builtin_amdgcn_s_barrier()
; #define P8_SCHED __builtin_amdgcn_sched_barrier(0)
; template <class EPI>
; DEVI void gemm8_tile(const bfr* __restrict__ A, const bfr* __restrict__ Bt, int K, int brow, int bcol, int nbrow, int nbcol, char* shmc, EPI epi) {
;     ...
;     P8_WAIT_V(6); P8_BAR; P8_MMA(1,1,At,B1); P8_BAR;
;     P8_LDB(B0,1,0); P8_SCHED; P8_LDA(At,1,0); P8_STAGE(P8_SA(0,1),A,brow+128,t+2);
;     P8_WAIT_L(8); P8_BAR; P8_WAIT_L(0); P8_MMA(0,0,At,B0); P8_BAR; P8_SCHED;
;     P8_LDB(B1,1,1); P8_STAGE(P8_SB(1,0),Bt,bcol,t+3);
;     P8_BAR; P8_WAIT_L(0); P8_MMA(0,1,At,B1); P8_BAR;
;     P8_LDA(At,1,1); P8_STAGE(P8_SA(1,0),A,brow,t+3);
;     P8_BAR; P8_WAIT_L(0); P8_MMA(1,0,At,B0); P8_BAR; P8_SCHED;
	v_mfma_f32_16x16x32_bf16 v[28:31], v[190:193], v[228:231], v[28:31]
	v_mfma_f32_16x16x32_bf16 v[24:27], v[190:193], v[236:239], v[24:27]
	v_mfma_f32_16x16x32_bf16 v[20:23], v[208:211], v[228:231], v[20:23]
	v_mfma_f32_16x16x32_bf16 v[16:19], v[208:211], v[236:239], v[16:19]
	v_mfma_f32_16x16x32_bf16 v[12:15], v[216:219], v[228:231], v[12:15]
	v_mfma_f32_16x16x32_bf16 v[8:11], v[216:219], v[236:239], v[8:11]
	v_mfma_f32_16x16x32_bf16 v[4:7], v[224:227], v[228:231], v[4:7]
	v_mfma_f32_16x16x32_bf16 v[0:3], v[224:227], v[236:239], v[0:3]
	v_mfma_f32_16x16x32_bf16 v[28:31], v[196:199], v[232:235], v[28:31]
	v_mfma_f32_16x16x32_bf16 v[24:27], v[196:199], v[240:243], v[24:27]
	v_mfma_f32_16x16x32_bf16 v[20:23], v[212:215], v[232:235], v[20:23]
	v_mfma_f32_16x16x32_bf16 v[16:19], v[212:215], v[240:243], v[16:19]
	v_mfma_f32_16x16x32_bf16 v[12:15], v[220:223], v[232:235], v[12:15]
	v_mfma_f32_16x16x32_bf16 v[8:11], v[220:223], v[240:243], v[8:11]
	v_mfma_f32_16x16x32_bf16 v[4:7], v[244:247], v[232:235], v[4:7]
	v_mfma_f32_16x16x32_bf16 v[0:3], v[244:247], v[240:243], v[0:3]
	s_barrier
	ds_read_b128 v[174:177], v149
	ds_read_b128 v[178:181], v149 offset:1024
	ds_read_b128 v[182:185], v149 offset:2048
	ds_read_b128 v[186:189], v149 offset:3072
	s_add_i32 m0, s100, 0x3f80
	ds_read_b128 v[190:193], v147 offset:32768
	ds_read_b128 v[196:199], v147 offset:33792
	ds_read_b128 v[208:211], v146 offset:32768
	ds_read_b128 v[212:215], v146 offset:33792
	ds_read_b128 v[216:219], v145 offset:32768
	ds_read_b128 v[220:223], v145 offset:33792
	ds_read_b128 v[224:227], v144 offset:32768
	ds_read_b128 v[228:231], v144 offset:33792
	global_load_lds_dwordx4 v171, s[86:87] offset:128
	s_add_i32 m0, s100, 0x5f80
	s_nop 0
	global_load_lds_dwordx4 v172, s[86:87] offset:128
	s_waitcnt lgkmcnt(8)
	s_barrier
	s_waitcnt lgkmcnt(0)
	v_mfma_f32_16x16x32_bf16 v[124:127], v[190:193], v[174:177], v[124:127]
	v_mfma_f32_16x16x32_bf16 v[120:123], v[190:193], v[182:185], v[120:123]
	v_mfma_f32_16x16x32_bf16 v[116:119], v[208:211], v[174:177], v[116:119]
	v_mfma_f32_16x16x32_bf16 v[112:115], v[208:211], v[182:185], v[112:115]
	v_mfma_f32_16x16x32_bf16 v[108:111], v[216:219], v[174:177], v[108:111]
	v_mfma_f32_16x16x32_bf16 v[104:107], v[216:219], v[182:185], v[104:107]
	v_mfma_f32_16x16x32_bf16 v[100:103], v[224:227], v[174:177], v[100:103]
	v_mfma_f32_16x16x32_bf16 v[96:99], v[224:227], v[182:185], v[96:99]
	v_mfma_f32_16x16x32_bf16 v[124:127], v[196:199], v[178:181], v[124:127]
	v_mfma_f32_16x16x32_bf16 v[120:123], v[196:199], v[186:189], v[120:123]
	v_mfma_f32_16x16x32_bf16 v[116:119], v[212:215], v[178:181], v[116:119]
	v_mfma_f32_16x16x32_bf16 v[112:115], v[212:215], v[186:189], v[112:115]
	v_mfma_f32_16x16x32_bf16 v[108:111], v[220:223], v[178:181], v[108:111]
	v_mfma_f32_16x16x32_bf16 v[104:107], v[220:223], v[186:189], v[104:107]
	v_mfma_f32_16x16x32_bf16 v[100:103], v[228:231], v[178:181], v[100:103]
	v_mfma_f32_16x16x32_bf16 v[96:99], v[228:231], v[186:189], v[96:99]
	s_barrier
	s_add_i32 m0, s100, 0x17f80
	ds_read_b128 v[232:235], v148
	ds_read_b128 v[236:239], v148 offset:1024
	ds_read_b128 v[240:243], v148 offset:2048
	ds_read_b128 v[244:247], v148 offset:3072
	global_load_lds_dwordx4 v158, s[86:87] offset:128
	s_add_i32 m0, s100, 0x19f80
	s_nop 0
	global_load_lds_dwordx4 v159, s[86:87] offset:128
	s_barrier
	s_waitcnt lgkmcnt(0)
	v_mfma_f32_16x16x32_bf16 v[92:95], v[190:193], v[232:235], v[92:95]
	v_mfma_f32_16x16x32_bf16 v[88:91], v[190:193], v[240:243], v[88:91]
	v_mfma_f32_16x16x32_bf16 v[84:87], v[208:211], v[232:235], v[84:87]
	v_mfma_f32_16x16x32_bf16 v[80:83], v[208:211], v[240:243], v[80:83]
	v_mfma_f32_16x16x32_bf16 v[76:79], v[216:219], v[232:235], v[76:79]
	v_mfma_f32_16x16x32_bf16 v[72:75], v[216:219], v[240:243], v[72:75]
	v_mfma_f32_16x16x32_bf16 v[68:71], v[224:227], v[232:235], v[68:71]
	v_mfma_f32_16x16x32_bf16 v[64:67], v[224:227], v[240:243], v[64:67]
	v_mfma_f32_16x16x32_bf16 v[92:95], v[196:199], v[236:239], v[92:95]
	v_mfma_f32_16x16x32_bf16 v[88:91], v[196:199], v[244:247], v[88:91]
	v_mfma_f32_16x16x32_bf16 v[84:87], v[212:215], v[236:239], v[84:87]
	v_mfma_f32_16x16x32_bf16 v[80:83], v[212:215], v[244:247], v[80:83]
	v_mfma_f32_16x16x32_bf16 v[76:79], v[220:223], v[236:239], v[76:79]
	v_mfma_f32_16x16x32_bf16 v[72:75], v[220:223], v[244:247], v[72:75]
	v_mfma_f32_16x16x32_bf16 v[68:71], v[228:231], v[236:239], v[68:71]
	v_mfma_f32_16x16x32_bf16 v[64:67], v[228:231], v[244:247], v[64:67]
	s_add_i32 m0, s100, 0x7f80
	s_barrier
	ds_read_b128 v[190:193], v147 offset:49152
	ds_read_b128 v[196:199], v147 offset:50176
	ds_read_b128 v[208:211], v146 offset:49152
	ds_read_b128 v[212:215], v146 offset:50176
	ds_read_b128 v[216:219], v145 offset:49152
	ds_read_b128 v[220:223], v145 offset:50176
	ds_read_b128 v[224:227], v144 offset:49152
	ds_read_b128 v[228:231], v144 offset:50176
	global_load_lds_dwordx4 v170, s[86:87] offset:128
	s_add_i32 m0, s100, 0x9f80
	s_nop 0
	global_load_lds_dwordx4 v206, s[86:87] offset:128
	s_barrier
	s_waitcnt lgkmcnt(0)
	v_mfma_f32_16x16x32_bf16 v[60:63], v[190:193], v[174:177], v[60:63]
	v_mfma_f32_16x16x32_bf16 v[56:59], v[190:193], v[182:185], v[56:59]
	v_mfma_f32_16x16x32_bf16 v[52:55], v[208:211], v[174:177], v[52:55]
	v_mfma_f32_16x16x32_bf16 v[48:51], v[208:211], v[182:185], v[48:51]
	v_mfma_f32_16x16x32_bf16 v[44:47], v[216:219], v[174:177], v[44:47]
	v_mfma_f32_16x16x32_bf16 v[40:43], v[216:219], v[182:185], v[40:43]
	v_mfma_f32_16x16x32_bf16 v[36:39], v[224:227], v[174:177], v[36:39]
	v_mfma_f32_16x16x32_bf16 v[32:35], v[224:227], v[182:185], v[32:35]
	v_mfma_f32_16x16x32_bf16 v[60:63], v[196:199], v[178:181], v[60:63]
	v_mfma_f32_16x16x32_bf16 v[56:59], v[196:199], v[186:189], v[56:59]
	v_mfma_f32_16x16x32_bf16 v[52:55], v[212:215], v[178:181], v[52:55]
	v_mfma_f32_16x16x32_bf16 v[48:51], v[212:215], v[186:189], v[48:51]
	v_mfma_f32_16x16x32_bf16 v[44:47], v[220:223], v[178:181], v[44:47]
	v_mfma_f32_16x16x32_bf16 v[40:43], v[220:223], v[186:189], v[40:43]
	v_mfma_f32_16x16x32_bf16 v[36:39], v[228:231], v[178:181], v[36:39]
	v_mfma_f32_16x16x32_bf16 v[32:35], v[228:231], v[186:189], v[32:35]
	s_barrier
; #define P8_STAGE(P,BASE,br,kt) do{const bfr* _ub=(BASE)+((long)(br)*K+(long)(kt)*BK); \
;     __builtin_amdgcn_global_load_lds((const unsigned*)(_ub+so0),(unsigned*)((char*)(P)+wid*1024),16,0,0); \
;     __builtin_amdgcn_global_load_lds((const unsigned*)(_ub+so1),(unsigned*)((char*)(P)+wid*1024+8192),16,0,0);}while(0)
; #define P8_LDA(dst,b,h) _Pragma("unroll") for(int m=0;m<4;++m) _Pragma("unroll") for(int k=0;k<2;++k) \
;     dst[m][k]=*reinterpret_cast<const bf16x8*>((char*)P8_SA(b,h)+lds_byte(wr*64+m*16+fr,k*32+fq*8))
; #define P8_LDB(dst,b,h) _Pragma("unroll") for(int n=0;n<2;++n) _Pragma("unroll") for(int k=0;k<2;++k) \
;     dst[n][k]=*reinterpret_cast<const bf16x8*>((char*)P8_SB(b,h)+lds_byte(wc*32+n*16+fr,k*32+fq*8))
; #define P8_MMA(ai,bj,At,Bt) do{__builtin_amdgcn_s_setprio(1); \
;     _Pragma("unroll") for(int m=0;m<4;++m) _Pragma("unroll") for(int n=0;n<2;++n) _Pragma("unroll") for(int k=0;k<2;++k) \
;       acc[ai][bj][m][n]=__builtin_amdgcn_mfma_f32_16x16x32_bf16(At[m][k],Bt[n][k],acc[ai][bj][m][n],0,0,0); \
;     __builtin_amdgcn_s_setprio(0);}while(0)
; #define P8_WAIT_V(n) asm volatile("s_waitcnt vmcnt(" #n ")":::"memory")
; #define P8_WAIT_L(n) asm volatile("s_waitcnt lgkmcnt(" #n ")":::"memory")
; #define P8_BAR __builtin_amdgcn_s_barrier()
; #define P8_SCHED __builtin_amdgcn_sched_barrier(0)
; template <class EPI>
; DEVI void gemm8_tile(const bfr* __restrict__ A, const bfr* __restrict__ Bt, int K, int brow, int bcol, int nbrow, int nbcol, char* shmc, EPI epi) {
;     ...
;     P8_BAR; P8_WAIT_L(0); P8_MMA(1,0,At,B0); P8_BAR; P8_SCHED;
;     P8_STAGE(P8_SB(1,1),Bt,bcol+128,t+3);
;     P8_WAIT_V(6); P8_BAR; P8_MMA(1,1,At,B1); P8_BAR;
;   }
;   { P8_LDB(B0,0,0); P8_LDA(At,0,0); P8_STAGE(P8_SA(1,1),A,brow+128,nt-1);
;     P8_BAR; P8_WAIT_L(0); P8_MMA(0,0,At,B0); P8_BAR;
;     P8_LDB(B1,0,1); P8_BAR; P8_WAIT_L(0); P8_MMA(0,1,At,B1); P8_BAR;
;     P8_LDA(At,0,1); P8_WAIT_V(4); P8_BAR; P8_WAIT_L(0); P8_MMA(1,0,At,B0); P8_MMA(1,1,At,B1); P8_BAR; }
	s_add_i32 m0, s100, 0x1bf80
	s_nop 0
	global_load_lds_dwordx4 v248, s[86:87] offset:128
	s_add_i32 m0, s100, 0x1df80
	s_nop 0
	global_load_lds_dwordx4 v200, s[86:87] offset:128
	s_waitcnt vmcnt(6)
	s_barrier
	v_mfma_f32_16x16x32_bf16 v[28:31], v[190:193], v[232:235], v[28:31]
	v_mfma_f32_16x16x32_bf16 v[24:27], v[190:193], v[240:243], v[24:27]
	v_mfma_f32_16x16x32_bf16 v[20:23], v[208:211], v[232:235], v[20:23]
	v_mfma_f32_16x16x32_bf16 v[16:19], v[208:211], v[240:243], v[16:19]
	v_mfma_f32_16x16x32_bf16 v[12:15], v[216:219], v[232:235], v[12:15]
	v_mfma_f32_16x16x32_bf16 v[8:11], v[216:219], v[240:243], v[8:11]
	v_mfma_f32_16x16x32_bf16 v[4:7], v[224:227], v[232:235], v[4:7]
	v_mfma_f32_16x16x32_bf16 v[0:3], v[224:227], v[240:243], v[0:3]
	v_mfma_f32_16x16x32_bf16 v[28:31], v[196:199], v[236:239], v[28:31]
	v_mfma_f32_16x16x32_bf16 v[24:27], v[196:199], v[244:247], v[24:27]
	v_mfma_f32_16x16x32_bf16 v[20:23], v[212:215], v[236:239], v[20:23]
	v_mfma_f32_16x16x32_bf16 v[16:19], v[212:215], v[244:247], v[16:19]
	v_mfma_f32_16x16x32_bf16 v[12:15], v[220:223], v[236:239], v[12:15]
	v_mfma_f32_16x16x32_bf16 v[8:11], v[220:223], v[244:247], v[8:11]
	v_mfma_f32_16x16x32_bf16 v[4:7], v[228:231], v[236:239], v[4:7]
	v_mfma_f32_16x16x32_bf16 v[0:3], v[228:231], v[244:247], v[0:3]
	s_add_i32 s0, s0, 2
	v_lshl_add_u64 v[134:135], v[134:135], 0, s[80:81]
	v_lshl_add_u64 v[136:137], v[136:137], 0, s[80:81]
	v_lshl_add_u64 v[138:139], v[138:139], 0, s[80:81]
	s_cmpk_lt_u32 s0, 0x7c
	v_lshl_add_u64 v[140:141], v[140:141], 0, s[80:81]
	s_barrier
	s_cbranch_scc1 .LBB0_382
	v_add_u32_e32 v171, 0xc000, v143
	v_add_u32_e32 v172, 0xe000, v143
	v_add_u32_e32 v158, 0x10000, v143
	v_add_u32_e32 v159, 0x12000, v143
	v_add_u32_e32 v160, 0x2000, v143
	v_add_u32_e32 v161, 0x14000, v143
	v_add_u32_e32 v162, 0x16000, v143
	v_add_u32_e32 v163, 0x4000, v143
	v_add_u32_e32 v170, 0x6000, v143
	s_or_b32 s0, s10, 0x80
	s_ashr_i32 s1, s0, 31
	s_lshl_b64 s[0:1], s[0:1], 14
	s_add_u32 s0, s31, s0
	s_addc_u32 s1, s64, s1
	s_add_u32 s0, s0, 0x3f80
	s_addc_u32 s1, s1, 0
	ds_read_b128 v[134:137], v157
	ds_read_b128 v[138:141], v157 offset:1024
	ds_read_b128 v[150:153], v157 offset:2048
	ds_read_b128 v[174:177], v157 offset:3072
	ds_read_b128 v[178:181], v147
	ds_read_b128 v[182:185], v147 offset:1024
	ds_read_b128 v[186:189], v146
	ds_read_b128 v[190:193], v146 offset:1024
	ds_read_b128 v[196:199], v145
	ds_read_b128 v[208:211], v145 offset:1024
	ds_read_b128 v[212:215], v144
	ds_read_b128 v[216:219], v144 offset:1024
	v_lshl_add_u64 v[156:157], v[166:167], 1, s[0:1]
	s_add_i32 m0, s100, 0xc000
	v_lshl_add_u64 v[132:133], v[132:133], 1, s[0:1]
	global_load_lds_dwordx4 v[156:157], off
	s_add_i32 m0, s100, 0xe000
	s_nop 0
	global_load_lds_dwordx4 v[132:133], off
	s_barrier
	s_waitcnt lgkmcnt(0)
	s_setprio 1
	s_waitcnt lgkmcnt(0)
	v_mfma_f32_16x16x32_bf16 v[124:127], v[178:181], v[134:137], v[124:127]
	v_mfma_f32_16x16x32_bf16 v[116:119], v[186:189], v[134:137], v[116:119]
	v_mfma_f32_16x16x32_bf16 v[112:115], v[186:189], v[150:153], v[112:115]
	v_mfma_f32_16x16x32_bf16 v[96:99], v[212:215], v[150:153], v[96:99]
	v_mfma_f32_16x16x32_bf16 v[124:127], v[182:185], v[138:141], v[124:127]
	v_mfma_f32_16x16x32_bf16 v[120:123], v[178:181], v[150:153], v[120:123]
	v_mfma_f32_16x16x32_bf16 v[116:119], v[190:193], v[138:141], v[116:119]
	v_mfma_f32_16x16x32_bf16 v[112:115], v[190:193], v[174:177], v[112:115]
	v_mfma_f32_16x16x32_bf16 v[108:111], v[196:199], v[134:137], v[108:111]
	v_mfma_f32_16x16x32_bf16 v[104:107], v[196:199], v[150:153], v[104:107]
	v_mfma_f32_16x16x32_bf16 v[100:103], v[212:215], v[134:137], v[100:103]
	v_mfma_f32_16x16x32_bf16 v[96:99], v[216:219], v[174:177], v[96:99]
	v_mfma_f32_16x16x32_bf16 v[220:223], v[182:185], v[174:177], v[120:123]
	v_mfma_f32_16x16x32_bf16 v[224:227], v[208:211], v[138:141], v[108:111]
	v_mfma_f32_16x16x32_bf16 v[228:231], v[208:211], v[174:177], v[104:107]
	v_mfma_f32_16x16x32_bf16 v[232:235], v[216:219], v[138:141], v[100:103]
	s_setprio 0
	s_barrier
	s_nop 0
	ds_read_b128 v[100:103], v154
	ds_read_b128 v[104:107], v154 offset:1024
	ds_read_b128 v[108:111], v154 offset:2048
	ds_read_b128 v[120:123], v154 offset:3072
	s_barrier
	s_waitcnt lgkmcnt(0)
	s_setprio 1
	s_waitcnt lgkmcnt(0)
	v_mfma_f32_16x16x32_bf16 v[92:95], v[178:181], v[100:103], v[92:95]
	v_mfma_f32_16x16x32_bf16 v[84:87], v[186:189], v[100:103], v[84:87]
	v_mfma_f32_16x16x32_bf16 v[80:83], v[186:189], v[108:111], v[80:83]
	v_mfma_f32_16x16x32_bf16 v[64:67], v[212:215], v[108:111], v[64:67]
	v_mfma_f32_16x16x32_bf16 v[92:95], v[182:185], v[104:107], v[92:95]
	v_mfma_f32_16x16x32_bf16 v[88:91], v[178:181], v[108:111], v[88:91]
	v_mfma_f32_16x16x32_bf16 v[84:87], v[190:193], v[104:107], v[84:87]
	v_mfma_f32_16x16x32_bf16 v[80:83], v[190:193], v[120:123], v[80:83]
	v_mfma_f32_16x16x32_bf16 v[76:79], v[196:199], v[100:103], v[76:79]
	v_mfma_f32_16x16x32_bf16 v[72:75], v[196:199], v[108:111], v[72:75]
	v_mfma_f32_16x16x32_bf16 v[68:71], v[212:215], v[100:103], v[68:71]
	v_mfma_f32_16x16x32_bf16 v[64:67], v[216:219], v[120:123], v[64:67]
	v_mfma_f32_16x16x32_bf16 v[154:157], v[182:185], v[120:123], v[88:91]
	v_mfma_f32_16x16x32_bf16 v[178:181], v[208:211], v[104:107], v[76:79]
	v_mfma_f32_16x16x32_bf16 v[182:185], v[208:211], v[120:123], v[72:75]
	v_mfma_f32_16x16x32_bf16 v[186:189], v[216:219], v[104:107], v[68:71]
	s_setprio 0
	s_barrier
	s_nop 0
	ds_read_b128 v[68:71], v147 offset:16384
	ds_read_b128 v[72:75], v147 offset:17408
	ds_read_b128 v[76:79], v146 offset:16384
	ds_read_b128 v[88:91], v146 offset:17408
	ds_read_b128 v[190:193], v145 offset:16384
	ds_read_b128 v[196:199], v145 offset:17408
	ds_read_b128 v[208:211], v144 offset:16384
	ds_read_b128 v[212:215], v144 offset:17408
	s_waitcnt vmcnt(4)
	s_barrier
; #define P8_LDA(dst,b,h) _Pragma("unroll") for(int m=0;m<4;++m) _Pragma("unroll") for(int k=0;k<2;++k) \
;     dst[m][k]=*reinterpret_cast<const bf16x8*>((char*)P8_SA(b,h)+lds_byte(wr*64+m*16+fr,k*32+fq*8))
; #define P8_LDB(dst,b,h) _Pragma("unroll") for(int n=0;n<2;++n) _Pragma("unroll") for(int k=0;k<2;++k) \
;     dst[n][k]=*reinterpret_cast<const bf16x8*>((char*)P8_SB(b,h)+lds_byte(wc*32+n*16+fr,k*32+fq*8))
; #define P8_MMA(ai,bj,At,Bt) do{__builtin_amdgcn_s_setprio(1); \
;     _Pragma("unroll") for(int m=0;m<4;++m) _Pragma("unroll") for(int n=0;n<2;++n) _Pragma("unroll") for(int k=0;k<2;++k) \
;       acc[ai][bj][m][n]=__builtin_amdgcn_mfma_f32_16x16x32_bf16(At[m][k],Bt[n][k],acc[ai][bj][m][n],0,0,0); \
;     __builtin_amdgcn_s_setprio(0);}while(0)
; #define P8_WAIT_V(n) asm volatile("s_waitcnt vmcnt(" #n ")":::"memory")
; #define P8_WAIT_L(n) asm volatile("s_waitcnt lgkmcnt(" #n ")":::"memory")
; #define P8_BAR __builtin_amdgcn_s_barrier()
; template <class EPI>
; DEVI void gemm8_tile(const bfr* __restrict__ A, const bfr* __restrict__ Bt, int K, int brow, int bcol, int nbrow, int nbcol, char* shmc, EPI epi) {
;     ...
;     P8_LDA(At,0,1); P8_WAIT_V(4); P8_BAR; P8_WAIT_L(0); P8_MMA(1,0,At,B0); P8_MMA(1,1,At,B1); P8_BAR; }
;   { P8_LDB(B0,1,0); P8_LDA(At,1,0); P8_WAIT_V(2); P8_BAR; P8_WAIT_L(0); P8_MMA(0,0,At,B0); P8_BAR;
	s_waitcnt lgkmcnt(0)
	s_setprio 1
	s_waitcnt lgkmcnt(0)
	v_mfma_f32_16x16x32_bf16 v[60:63], v[68:71], v[134:137], v[60:63]
	v_mfma_f32_16x16x32_bf16 v[52:55], v[76:79], v[134:137], v[52:55]
	v_mfma_f32_16x16x32_bf16 v[48:51], v[76:79], v[150:153], v[48:51]
	v_mfma_f32_16x16x32_bf16 v[32:35], v[208:211], v[150:153], v[32:35]
	v_mfma_f32_16x16x32_bf16 v[60:63], v[72:75], v[138:141], v[60:63]
	v_mfma_f32_16x16x32_bf16 v[56:59], v[68:71], v[150:153], v[56:59]
	v_mfma_f32_16x16x32_bf16 v[52:55], v[88:91], v[138:141], v[52:55]
	v_mfma_f32_16x16x32_bf16 v[48:51], v[88:91], v[174:177], v[48:51]
	v_mfma_f32_16x16x32_bf16 v[44:47], v[190:193], v[134:137], v[44:47]
	v_mfma_f32_16x16x32_bf16 v[40:43], v[190:193], v[150:153], v[40:43]
	v_mfma_f32_16x16x32_bf16 v[36:39], v[208:211], v[134:137], v[36:39]
	v_mfma_f32_16x16x32_bf16 v[32:35], v[212:215], v[174:177], v[32:35]
	v_mfma_f32_16x16x32_bf16 v[216:219], v[72:75], v[174:177], v[56:59]
	v_mfma_f32_16x16x32_bf16 v[236:239], v[196:199], v[138:141], v[44:47]
	v_mfma_f32_16x16x32_bf16 v[240:243], v[196:199], v[174:177], v[40:43]
	v_mfma_f32_16x16x32_bf16 v[132:135], v[212:215], v[138:141], v[36:39]
	s_setprio 0
	s_setprio 1
	v_mfma_f32_16x16x32_bf16 v[28:31], v[68:71], v[100:103], v[28:31]
	v_mfma_f32_16x16x32_bf16 v[20:23], v[76:79], v[100:103], v[20:23]
	v_mfma_f32_16x16x32_bf16 v[16:19], v[76:79], v[108:111], v[16:19]
	v_mfma_f32_16x16x32_bf16 v[0:3], v[208:211], v[108:111], v[0:3]
	v_mfma_f32_16x16x32_bf16 v[28:31], v[72:75], v[104:107], v[28:31]
	v_mfma_f32_16x16x32_bf16 v[24:27], v[68:71], v[108:111], v[24:27]
	v_mfma_f32_16x16x32_bf16 v[20:23], v[88:91], v[104:107], v[20:23]
	v_mfma_f32_16x16x32_bf16 v[16:19], v[88:91], v[120:123], v[16:19]
	v_mfma_f32_16x16x32_bf16 v[12:15], v[190:193], v[100:103], v[12:15]
	v_mfma_f32_16x16x32_bf16 v[8:11], v[190:193], v[108:111], v[8:11]
	v_mfma_f32_16x16x32_bf16 v[4:7], v[208:211], v[100:103], v[4:7]
	v_mfma_f32_16x16x32_bf16 v[0:3], v[212:215], v[120:123], v[0:3]
	v_mfma_f32_16x16x32_bf16 v[136:139], v[72:75], v[120:123], v[24:27]
	v_mfma_f32_16x16x32_bf16 v[150:153], v[196:199], v[104:107], v[12:15]
	v_mfma_f32_16x16x32_bf16 v[172:175], v[196:199], v[120:123], v[8:11]
	v_mfma_f32_16x16x32_bf16 v[190:193], v[212:215], v[104:107], v[4:7]
	s_setprio 0
	s_barrier
	s_nop 0
	ds_read_b128 v[4:7], v149
	ds_read_b128 v[8:11], v149 offset:1024
	ds_read_b128 v[12:15], v149 offset:2048
	ds_read_b128 v[24:27], v149 offset:3072
	ds_read_b128 v[36:39], v147 offset:32768
	ds_read_b128 v[40:43], v147 offset:33792
	ds_read_b128 v[44:47], v146 offset:32768
	ds_read_b128 v[56:59], v146 offset:33792
	ds_read_b128 v[68:71], v145 offset:32768
	ds_read_b128 v[196:199], v145 offset:33792
	ds_read_b128 v[208:211], v144 offset:32768
	ds_read_b128 v[212:215], v144 offset:33792
	s_waitcnt vmcnt(2)
	s_barrier
	s_waitcnt lgkmcnt(0)
	s_setprio 1
	s_waitcnt lgkmcnt(0)
	v_mfma_f32_16x16x32_bf16 v[72:75], v[36:39], v[4:7], v[124:127]
	v_mfma_f32_16x16x32_bf16 v[120:123], v[40:43], v[8:11], v[72:75]
	v_mfma_f32_16x16x32_bf16 v[72:75], v[36:39], v[12:15], v[220:223]
	v_mfma_f32_16x16x32_bf16 v[104:107], v[40:43], v[24:27], v[72:75]
	v_mfma_f32_16x16x32_bf16 v[72:75], v[44:47], v[4:7], v[116:119]
	v_mfma_f32_16x16x32_bf16 v[124:127], v[56:59], v[8:11], v[72:75]
	v_mfma_f32_16x16x32_bf16 v[72:75], v[44:47], v[12:15], v[112:115]
	v_mfma_f32_16x16x32_bf16 v[108:111], v[56:59], v[24:27], v[72:75]
	v_mfma_f32_16x16x32_bf16 v[72:75], v[68:71], v[4:7], v[224:227]
	v_mfma_f32_16x16x32_bf16 v[112:115], v[196:199], v[8:11], v[72:75]
	v_mfma_f32_16x16x32_bf16 v[72:75], v[68:71], v[12:15], v[228:231]
	v_mfma_f32_16x16x32_bf16 v[100:103], v[196:199], v[24:27], v[72:75]
	v_mfma_f32_16x16x32_bf16 v[72:75], v[208:211], v[4:7], v[232:235]
	v_mfma_f32_16x16x32_bf16 v[116:119], v[212:215], v[8:11], v[72:75]
	v_mfma_f32_16x16x32_bf16 v[72:75], v[208:211], v[12:15], v[96:99]
	v_mfma_f32_16x16x32_bf16 v[96:99], v[212:215], v[24:27], v[72:75]
	s_setprio 0
	s_barrier
; #define P8_LDA(dst,b,h) _Pragma("unroll") for(int m=0;m<4;++m) _Pragma("unroll") for(int k=0;k<2;++k) \
;     dst[m][k]=*reinterpret_cast<const bf16x8*>((char*)P8_SA(b,h)+lds_byte(wr*64+m*16+fr,k*32+fq*8))
; #define P8_LDB(dst,b,h) _Pragma("unroll") for(int n=0;n<2;++n) _Pragma("unroll") for(int k=0;k<2;++k) \
;     dst[n][k]=*reinterpret_cast<const bf16x8*>((char*)P8_SB(b,h)+lds_byte(wc*32+n*16+fr,k*32+fq*8))
; #define P8_MMA(ai,bj,At,Bt) do{__builtin_amdgcn_s_setprio(1); \
;     _Pragma("unroll") for(int m=0;m<4;++m) _Pragma("unroll") for(int n=0;n<2;++n) _Pragma("unroll") for(int k=0;k<2;++k) \
;       acc[ai][bj][m][n]=__builtin_amdgcn_mfma_f32_16x16x32_bf16(At[m][k],Bt[n][k],acc[ai][bj][m][n],0,0,0); \
;     __builtin_amdgcn_s_setprio(0);}while(0)
; #define P8_WAIT_V(n) asm volatile("s_waitcnt vmcnt(" #n ")":::"memory")
; #define P8_WAIT_L(n) asm volatile("s_waitcnt lgkmcnt(" #n ")":::"memory")
; #define P8_BAR __builtin_amdgcn_s_barrier()
; template <class EPI>
; DEVI void gemm8_tile(const bfr* __restrict__ A, const bfr* __restrict__ Bt, int K, int brow, int bcol, int nbrow, int nbcol, char* shmc, EPI epi) {
;     ...
;     P8_LDB(B1,1,1); P8_WAIT_V(0); P8_BAR; P8_WAIT_L(0); P8_MMA(0,1,At,B1); P8_BAR;
;     P8_LDA(At,1,1); P8_BAR; P8_WAIT_L(0); P8_MMA(1,0,At,B0); P8_MMA(1,1,At,B1); P8_BAR; }
;   if(wr==0)P8_BAR;
	ds_read_b128 v[220:223], v148
	ds_read_b128 v[224:227], v148 offset:1024
	ds_read_b128 v[228:231], v148 offset:2048
	ds_read_b128 v[232:235], v148 offset:3072
	s_waitcnt vmcnt(0)
	s_barrier
	s_waitcnt lgkmcnt(0)
	s_setprio 1
	s_waitcnt lgkmcnt(0)
	v_mfma_f32_16x16x32_bf16 v[72:75], v[36:39], v[220:223], v[92:95]
	v_mfma_f32_16x16x32_bf16 v[36:39], v[36:39], v[228:231], v[154:157]
	v_mfma_f32_16x16x32_bf16 v[88:91], v[40:43], v[224:227], v[72:75]
	v_mfma_f32_16x16x32_bf16 v[72:75], v[40:43], v[232:235], v[36:39]
	v_mfma_f32_16x16x32_bf16 v[36:39], v[44:47], v[220:223], v[84:87]
	v_mfma_f32_16x16x32_bf16 v[92:95], v[56:59], v[224:227], v[36:39]
	v_mfma_f32_16x16x32_bf16 v[36:39], v[44:47], v[228:231], v[80:83]
	v_mfma_f32_16x16x32_bf16 v[76:79], v[56:59], v[232:235], v[36:39]
	v_mfma_f32_16x16x32_bf16 v[36:39], v[68:71], v[220:223], v[178:181]
	v_mfma_f32_16x16x32_bf16 v[80:83], v[196:199], v[224:227], v[36:39]
	v_mfma_f32_16x16x32_bf16 v[36:39], v[68:71], v[228:231], v[182:185]
	v_mfma_f32_16x16x32_bf16 v[68:71], v[196:199], v[232:235], v[36:39]
	v_mfma_f32_16x16x32_bf16 v[36:39], v[208:211], v[220:223], v[186:189]
	v_mfma_f32_16x16x32_bf16 v[84:87], v[212:215], v[224:227], v[36:39]
	v_mfma_f32_16x16x32_bf16 v[36:39], v[208:211], v[228:231], v[64:67]
	v_mfma_f32_16x16x32_bf16 v[64:67], v[212:215], v[232:235], v[36:39]
	s_setprio 0
	s_barrier
	ds_read_b128 v[154:157], v147 offset:49152
	ds_read_b128 v[176:179], v147 offset:50176
	ds_read_b128 v[180:183], v146 offset:49152
	ds_read_b128 v[146:149], v146 offset:50176
	ds_read_b128 v[184:187], v145 offset:49152
	ds_read_b128 v[196:199], v145 offset:50176
	ds_read_b128 v[208:211], v144 offset:49152
	ds_read_b128 v[212:215], v144 offset:50176
	s_barrier
	s_waitcnt lgkmcnt(0)
	s_setprio 1
	s_waitcnt lgkmcnt(0)
	v_mfma_f32_16x16x32_bf16 v[36:39], v[154:157], v[4:7], v[60:63]
	v_mfma_f32_16x16x32_bf16 v[56:59], v[176:179], v[8:11], v[36:39]
	v_mfma_f32_16x16x32_bf16 v[36:39], v[154:157], v[12:15], v[216:219]
	v_mfma_f32_16x16x32_bf16 v[40:43], v[176:179], v[24:27], v[36:39]
	v_mfma_f32_16x16x32_bf16 v[36:39], v[180:183], v[4:7], v[52:55]
	v_mfma_f32_16x16x32_bf16 v[60:63], v[146:149], v[8:11], v[36:39]
	v_mfma_f32_16x16x32_bf16 v[36:39], v[180:183], v[12:15], v[48:51]
	v_mfma_f32_16x16x32_bf16 v[44:47], v[146:149], v[24:27], v[36:39]
	v_mfma_f32_16x16x32_bf16 v[36:39], v[184:187], v[4:7], v[236:239]
	v_mfma_f32_16x16x32_bf16 v[4:7], v[208:211], v[4:7], v[132:135]
	v_mfma_f32_16x16x32_bf16 v[48:51], v[196:199], v[8:11], v[36:39]
	v_mfma_f32_16x16x32_bf16 v[36:39], v[184:187], v[12:15], v[240:243]
	v_mfma_f32_16x16x32_bf16 v[52:55], v[212:215], v[8:11], v[4:7]
	v_mfma_f32_16x16x32_bf16 v[4:7], v[208:211], v[12:15], v[32:35]
	v_mfma_f32_16x16x32_bf16 v[36:39], v[196:199], v[24:27], v[36:39]
	v_mfma_f32_16x16x32_bf16 v[32:35], v[212:215], v[24:27], v[4:7]
	s_setprio 0
	s_setprio 1
	v_mfma_f32_16x16x32_bf16 v[4:7], v[154:157], v[220:223], v[28:31]
	v_mfma_f32_16x16x32_bf16 v[24:27], v[176:179], v[224:227], v[4:7]
	v_mfma_f32_16x16x32_bf16 v[4:7], v[154:157], v[228:231], v[136:139]
	v_mfma_f32_16x16x32_bf16 v[8:11], v[176:179], v[232:235], v[4:7]
	v_mfma_f32_16x16x32_bf16 v[4:7], v[180:183], v[220:223], v[20:23]
	v_mfma_f32_16x16x32_bf16 v[28:31], v[146:149], v[224:227], v[4:7]
	v_mfma_f32_16x16x32_bf16 v[4:7], v[180:183], v[228:231], v[16:19]
	v_mfma_f32_16x16x32_bf16 v[12:15], v[146:149], v[232:235], v[4:7]
	v_mfma_f32_16x16x32_bf16 v[4:7], v[184:187], v[220:223], v[150:153]
	v_mfma_f32_16x16x32_bf16 v[16:19], v[196:199], v[224:227], v[4:7]
	v_mfma_f32_16x16x32_bf16 v[4:7], v[184:187], v[228:231], v[172:175]
	v_mfma_f32_16x16x32_bf16 v[20:23], v[208:211], v[220:223], v[190:193]
	v_mfma_f32_16x16x32_bf16 v[0:3], v[208:211], v[228:231], v[0:3]
	v_mfma_f32_16x16x32_bf16 v[4:7], v[196:199], v[232:235], v[4:7]
	v_mfma_f32_16x16x32_bf16 v[20:23], v[212:215], v[224:227], v[20:23]
	v_mfma_f32_16x16x32_bf16 v[0:3], v[212:215], v[232:235], v[0:3]
	s_setprio 0
	v_cmp_gt_u32_e32 vcc, s57, v142
	s_barrier
	s_and_saveexec_b64 s[0:1], vcc
	s_cbranch_execz .LBB0_385
	s_barrier

; #define P8_STAGE(P,BASE,br,kt) do{const bfr* _ub=(BASE)+((long)(br)*K+(long)(kt)*BK); \
;     __builtin_amdgcn_global_load_lds((const unsigned*)(_ub+so0),(unsigned*)((char*)(P)+wid*1024),16,0,0); \
;     __builtin_amdgcn_global_load_lds((const unsigned*)(_ub+so1),(unsigned*)((char*)(P)+wid*1024+8192),16,0,0);}while(0)
; #define P8_LDA(dst,b,h) _Pragma("unroll") for(int m=0;m<4;++m) _Pragma("unroll") for(int k=0;k<2;++k) \
;     dst[m][k]=*reinterpret_cast<const bf16x8*>((char*)P8_SA(b,h)+lds_byte(wr*64+m*16+fr,k*32+fq*8))
; #define P8_LDB(dst,b,h) _Pragma("unroll") for(int n=0;n<2;++n) _Pragma("unroll") for(int k=0;k<2;++k) \
;     dst[n][k]=*reinterpret_cast<const bf16x8*>((char*)P8_SB(b,h)+lds_byte(wc*32+n*16+fr,k*32+fq*8))
; #define P8_MMA(ai,bj,At,Bt) do{__builtin_amdgcn_s_setprio(1); \
;     _Pragma("unroll") for(int m=0;m<4;++m) _Pragma("unroll") for(int n=0;n<2;++n) _Pragma("unroll") for(int k=0;k<2;++k) \
;       acc[ai][bj][m][n]=__builtin_amdgcn_mfma_f32_16x16x32_bf16(At[m][k],Bt[n][k],acc[ai][bj][m][n],0,0,0); \
;     __builtin_amdgcn_s_setprio(0);}while(0)
; #define P8_WAIT_V(n) asm volatile("s_waitcnt vmcnt(" #n ")":::"memory")
; #define P8_WAIT_L(n) asm volatile("s_waitcnt lgkmcnt(" #n ")":::"memory")
; #define P8_BAR __builtin_amdgcn_s_barrier()
; #define P8_SCHED __builtin_amdgcn_sched_barrier(0)
; template <class EPI>
; DEVI void gemm8_tile(const bfr* __restrict__ A, const bfr* __restrict__ Bt, int K, int brow, int bcol, int nbrow, int nbcol, char* shmc, EPI epi) {
;     ...
;     P8_LDB(B0,0,0); P8_SCHED; P8_LDA(At,0,0); P8_STAGE(P8_SA(1,1),A,brow+128,t+1);
;     P8_WAIT_L(8); P8_BAR; P8_WAIT_L(0); P8_MMA(0,0,At,B0); P8_BAR; P8_SCHED;
;     P8_LDB(B1,0,1); P8_STAGE(P8_SB(0,0),Bt,bcol,t+2);
;     P8_BAR; P8_WAIT_L(0); P8_MMA(0,1,At,B1); P8_BAR;
;     P8_LDA(At,0,1); P8_STAGE(P8_SA(0,0),A,brow,t+2);
;     P8_BAR; P8_WAIT_L(0); P8_MMA(1,0,At,B0); P8_BAR; P8_SCHED;
;     P8_STAGE(P8_SB(0,1),Bt,bcol+128,t+2);
;     P8_WAIT_V(6); P8_BAR; P8_MMA(1,1,At,B1); P8_BAR;
.LBB0_401:
	ds_read_b128 v[174:177], v157
	ds_read_b128 v[178:181], v157 offset:1024
	ds_read_b128 v[182:185], v157 offset:2048
	ds_read_b128 v[186:189], v157 offset:3072
	v_add_u32_e32 v171, s54, v136
	s_add_i32 m0, s100, 0xc000
	ds_read_b128 v[160:163], v147
	ds_read_b128 v[190:193], v147 offset:1024
	ds_read_b128 v[196:199], v146
	ds_read_b128 v[208:211], v146 offset:1024
	ds_read_b128 v[212:215], v145
	ds_read_b128 v[216:219], v145 offset:1024
	ds_read_b128 v[220:223], v144
	ds_read_b128 v[224:227], v144 offset:1024
	global_load_lds_dwordx4 v171, s[86:87]
	v_add_u32_e32 v172, s54, v134
	s_add_i32 m0, s100, 0xe000
	s_nop 0
	global_load_lds_dwordx4 v172, s[86:87]
	s_waitcnt lgkmcnt(8)
	s_barrier
	s_waitcnt lgkmcnt(0)
	v_mfma_f32_16x16x32_bf16 v[124:127], v[160:163], v[174:177], v[124:127]
	v_mfma_f32_16x16x32_bf16 v[120:123], v[160:163], v[182:185], v[120:123]
	v_mfma_f32_16x16x32_bf16 v[116:119], v[196:199], v[174:177], v[116:119]
	v_mfma_f32_16x16x32_bf16 v[112:115], v[196:199], v[182:185], v[112:115]
	v_mfma_f32_16x16x32_bf16 v[108:111], v[212:215], v[174:177], v[108:111]
	v_mfma_f32_16x16x32_bf16 v[104:107], v[212:215], v[182:185], v[104:107]
	v_mfma_f32_16x16x32_bf16 v[100:103], v[220:223], v[174:177], v[100:103]
	v_mfma_f32_16x16x32_bf16 v[96:99], v[220:223], v[182:185], v[96:99]
	v_mfma_f32_16x16x32_bf16 v[124:127], v[190:193], v[178:181], v[124:127]
	v_mfma_f32_16x16x32_bf16 v[120:123], v[190:193], v[186:189], v[120:123]
	v_mfma_f32_16x16x32_bf16 v[116:119], v[208:211], v[178:181], v[116:119]
	v_mfma_f32_16x16x32_bf16 v[112:115], v[208:211], v[186:189], v[112:115]
	v_mfma_f32_16x16x32_bf16 v[108:111], v[216:219], v[178:181], v[108:111]
	v_mfma_f32_16x16x32_bf16 v[104:107], v[216:219], v[186:189], v[104:107]
	v_mfma_f32_16x16x32_bf16 v[100:103], v[224:227], v[178:181], v[100:103]
	v_mfma_f32_16x16x32_bf16 v[96:99], v[224:227], v[186:189], v[96:99]
	s_barrier
	v_add_u32_e32 v158, s66, v140
	s_add_i32 m0, s100, 0x10000
	ds_read_b128 v[228:231], v155
	ds_read_b128 v[232:235], v155 offset:1024
	ds_read_b128 v[236:239], v155 offset:2048
	ds_read_b128 v[240:243], v155 offset:3072
	global_load_lds_dwordx4 v158, s[86:87]
	v_add_u32_e32 v159, s66, v138
	s_add_i32 m0, s100, 0x12000
	s_nop 0
	global_load_lds_dwordx4 v159, s[86:87]
	s_barrier
	s_waitcnt lgkmcnt(0)
	v_mfma_f32_16x16x32_bf16 v[92:95], v[160:163], v[228:231], v[92:95]
	v_mfma_f32_16x16x32_bf16 v[88:91], v[160:163], v[236:239], v[88:91]
	v_mfma_f32_16x16x32_bf16 v[84:87], v[196:199], v[228:231], v[84:87]
	v_mfma_f32_16x16x32_bf16 v[80:83], v[196:199], v[236:239], v[80:83]
	v_mfma_f32_16x16x32_bf16 v[76:79], v[212:215], v[228:231], v[76:79]
	v_mfma_f32_16x16x32_bf16 v[72:75], v[212:215], v[236:239], v[72:75]
	v_mfma_f32_16x16x32_bf16 v[68:71], v[220:223], v[228:231], v[68:71]
	v_mfma_f32_16x16x32_bf16 v[64:67], v[220:223], v[236:239], v[64:67]
	v_mfma_f32_16x16x32_bf16 v[92:95], v[190:193], v[232:235], v[92:95]
	v_mfma_f32_16x16x32_bf16 v[88:91], v[190:193], v[240:243], v[88:91]
	v_mfma_f32_16x16x32_bf16 v[84:87], v[208:211], v[232:235], v[84:87]
	v_mfma_f32_16x16x32_bf16 v[80:83], v[208:211], v[240:243], v[80:83]
	v_mfma_f32_16x16x32_bf16 v[76:79], v[216:219], v[232:235], v[76:79]
	v_mfma_f32_16x16x32_bf16 v[72:75], v[216:219], v[240:243], v[72:75]
	v_mfma_f32_16x16x32_bf16 v[68:71], v[224:227], v[232:235], v[68:71]
	v_mfma_f32_16x16x32_bf16 v[64:67], v[224:227], v[240:243], v[64:67]
	v_add_u32_e32 v170, s60, v136
	s_mov_b32 m0, s100
	s_barrier
	ds_read_b128 v[190:193], v147 offset:16384
	ds_read_b128 v[196:199], v147 offset:17408
	ds_read_b128 v[208:211], v146 offset:16384
	ds_read_b128 v[212:215], v146 offset:17408
	ds_read_b128 v[216:219], v145 offset:16384
	ds_read_b128 v[220:223], v145 offset:17408
	ds_read_b128 v[224:227], v144 offset:16384
	ds_read_b128 v[244:247], v144 offset:17408
	global_load_lds_dwordx4 v170, s[86:87]
	v_add_u32_e32 v206, s60, v134
	s_add_i32 m0, s100, 0x2000
	s_nop 0
	global_load_lds_dwordx4 v206, s[86:87]
	s_barrier
	s_waitcnt lgkmcnt(0)
	v_mfma_f32_16x16x32_bf16 v[60:63], v[190:193], v[174:177], v[60:63]
	v_mfma_f32_16x16x32_bf16 v[56:59], v[190:193], v[182:185], v[56:59]
	v_mfma_f32_16x16x32_bf16 v[52:55], v[208:211], v[174:177], v[52:55]
	v_mfma_f32_16x16x32_bf16 v[48:51], v[208:211], v[182:185], v[48:51]
	v_mfma_f32_16x16x32_bf16 v[44:47], v[216:219], v[174:177], v[44:47]
	v_mfma_f32_16x16x32_bf16 v[40:43], v[216:219], v[182:185], v[40:43]
	v_mfma_f32_16x16x32_bf16 v[36:39], v[224:227], v[174:177], v[36:39]
	v_mfma_f32_16x16x32_bf16 v[32:35], v[224:227], v[182:185], v[32:35]
	v_mfma_f32_16x16x32_bf16 v[60:63], v[196:199], v[178:181], v[60:63]
	v_mfma_f32_16x16x32_bf16 v[56:59], v[196:199], v[186:189], v[56:59]
	v_mfma_f32_16x16x32_bf16 v[52:55], v[212:215], v[178:181], v[52:55]
	v_mfma_f32_16x16x32_bf16 v[48:51], v[212:215], v[186:189], v[48:51]
	v_mfma_f32_16x16x32_bf16 v[44:47], v[220:223], v[178:181], v[44:47]
	v_mfma_f32_16x16x32_bf16 v[40:43], v[220:223], v[186:189], v[40:43]
	v_mfma_f32_16x16x32_bf16 v[36:39], v[244:247], v[178:181], v[36:39]
	v_mfma_f32_16x16x32_bf16 v[32:35], v[244:247], v[186:189], v[32:35]
	s_barrier
	v_add_u32_e32 v248, s70, v140
	s_add_i32 m0, s100, 0x14000
	v_add_u32_e32 v200, s70, v138
	global_load_lds_dwordx4 v248, s[86:87]
	s_nop 0
	s_add_i32 m0, s100, 0x16000
	s_nop 0
	global_load_lds_dwordx4 v200, s[86:87]
	s_waitcnt vmcnt(6)
	s_barrier
; #define P8_STAGE(P,BASE,br,kt) do{const bfr* _ub=(BASE)+((long)(br)*K+(long)(kt)*BK); \
;     __builtin_amdgcn_global_load_lds((const unsigned*)(_ub+so0),(unsigned*)((char*)(P)+wid*1024),16,0,0); \
;     __builtin_amdgcn_global_load_lds((const unsigned*)(_ub+so1),(unsigned*)((char*)(P)+wid*1024+8192),16,0,0);}while(0)
; #define P8_LDA(dst,b,h) _Pragma("unroll") for(int m=0;m<4;++m) _Pragma("unroll") for(int k=0;k<2;++k) \
;     dst[m][k]=*reinterpret_cast<const bf16x8*>((char*)P8_SA(b,h)+lds_byte(wr*64+m*16+fr,k*32+fq*8))
; #define P8_LDB(dst,b,h) _Pragma("unroll") for(int n=0;n<2;++n) _Pragma("unroll") for(int k=0;k<2;++k) \
;     dst[n][k]=*reinterpret_cast<const bf16x8*>((char*)P8_SB(b,h)+lds_byte(wc*32+n*16+fr,k*32+fq*8))
; #define P8_MMA(ai,bj,At,Bt) do{__builtin_amdgcn_s_setprio(1); \
;     _Pragma("unroll") for(int m=0;m<4;++m) _Pragma("unroll") for(int n=0;n<2;++n) _Pragma("unroll") for(int k=0;k<2;++k) \
;       acc[ai][bj][m][n]=__builtin_amdgcn_mfma_f32_16x16x32_bf16(At[m][k],Bt[n][k],acc[ai][bj][m][n],0,0,0); \
;     __builtin_amdgcn_s_setprio(0);}while(0)
; #define P8_WAIT_V(n) asm volatile("s_waitcnt vmcnt(" #n ")":::"memory")
; #define P8_WAIT_L(n) asm volatile("s_waitcnt lgkmcnt(" #n ")":::"memory")
; #define P8_BAR __builtin_amdgcn_s_barrier()
; #define P8_SCHED __builtin_amdgcn_sched_barrier(0)
; template <class EPI>
; DEVI void gemm8_tile(const bfr* __restrict__ A, const bfr* __restrict__ Bt, int K, int brow, int bcol, int nbrow, int nbcol, char* shmc, EPI epi) {
;     ...
;     P8_WAIT_V(6); P8_BAR; P8_MMA(1,1,At,B1); P8_BAR;
;     P8_LDB(B0,1,0); P8_SCHED; P8_LDA(At,1,0); P8_STAGE(P8_SA(0,1),A,brow+128,t+2);
;     P8_WAIT_L(8); P8_BAR; P8_WAIT_L(0); P8_MMA(0,0,At,B0); P8_BAR; P8_SCHED;
;     P8_LDB(B1,1,1); P8_STAGE(P8_SB(1,0),Bt,bcol,t+3);
;     P8_BAR; P8_WAIT_L(0); P8_MMA(0,1,At,B1); P8_BAR;
;     P8_LDA(At,1,1); P8_STAGE(P8_SA(1,0),A,brow,t+3);
;     P8_BAR; P8_WAIT_L(0); P8_MMA(1,0,At,B0); P8_BAR; P8_SCHED;
	v_mfma_f32_16x16x32_bf16 v[28:31], v[190:193], v[228:231], v[28:31]
	v_mfma_f32_16x16x32_bf16 v[24:27], v[190:193], v[236:239], v[24:27]
	v_mfma_f32_16x16x32_bf16 v[20:23], v[208:211], v[228:231], v[20:23]
	v_mfma_f32_16x16x32_bf16 v[16:19], v[208:211], v[236:239], v[16:19]
	v_mfma_f32_16x16x32_bf16 v[12:15], v[216:219], v[228:231], v[12:15]
	v_mfma_f32_16x16x32_bf16 v[8:11], v[216:219], v[236:239], v[8:11]
	v_mfma_f32_16x16x32_bf16 v[4:7], v[224:227], v[228:231], v[4:7]
	v_mfma_f32_16x16x32_bf16 v[0:3], v[224:227], v[236:239], v[0:3]
	v_mfma_f32_16x16x32_bf16 v[28:31], v[196:199], v[232:235], v[28:31]
	v_mfma_f32_16x16x32_bf16 v[24:27], v[196:199], v[240:243], v[24:27]
	v_mfma_f32_16x16x32_bf16 v[20:23], v[212:215], v[232:235], v[20:23]
	v_mfma_f32_16x16x32_bf16 v[16:19], v[212:215], v[240:243], v[16:19]
	v_mfma_f32_16x16x32_bf16 v[12:15], v[220:223], v[232:235], v[12:15]
	v_mfma_f32_16x16x32_bf16 v[8:11], v[220:223], v[240:243], v[8:11]
	v_mfma_f32_16x16x32_bf16 v[4:7], v[244:247], v[232:235], v[4:7]
	v_mfma_f32_16x16x32_bf16 v[0:3], v[244:247], v[240:243], v[0:3]
	s_barrier
	ds_read_b128 v[174:177], v149
	ds_read_b128 v[178:181], v149 offset:1024
	ds_read_b128 v[182:185], v149 offset:2048
	ds_read_b128 v[186:189], v149 offset:3072
	s_add_i32 m0, s100, 0x3f80
	ds_read_b128 v[190:193], v147 offset:32768
	ds_read_b128 v[196:199], v147 offset:33792
	ds_read_b128 v[208:211], v146 offset:32768
	ds_read_b128 v[212:215], v146 offset:33792
	ds_read_b128 v[216:219], v145 offset:32768
	ds_read_b128 v[220:223], v145 offset:33792
	ds_read_b128 v[224:227], v144 offset:32768
	ds_read_b128 v[228:231], v144 offset:33792
	global_load_lds_dwordx4 v171, s[86:87] offset:128
	s_add_i32 m0, s100, 0x5f80
	s_nop 0
	global_load_lds_dwordx4 v172, s[86:87] offset:128
	s_waitcnt lgkmcnt(8)
	s_barrier
	s_waitcnt lgkmcnt(0)
	v_mfma_f32_16x16x32_bf16 v[124:127], v[190:193], v[174:177], v[124:127]
	v_mfma_f32_16x16x32_bf16 v[120:123], v[190:193], v[182:185], v[120:123]
	v_mfma_f32_16x16x32_bf16 v[116:119], v[208:211], v[174:177], v[116:119]
	v_mfma_f32_16x16x32_bf16 v[112:115], v[208:211], v[182:185], v[112:115]
	v_mfma_f32_16x16x32_bf16 v[108:111], v[216:219], v[174:177], v[108:111]
	v_mfma_f32_16x16x32_bf16 v[104:107], v[216:219], v[182:185], v[104:107]
	v_mfma_f32_16x16x32_bf16 v[100:103], v[224:227], v[174:177], v[100:103]
	v_mfma_f32_16x16x32_bf16 v[96:99], v[224:227], v[182:185], v[96:99]
	v_mfma_f32_16x16x32_bf16 v[124:127], v[196:199], v[178:181], v[124:127]
	v_mfma_f32_16x16x32_bf16 v[120:123], v[196:199], v[186:189], v[120:123]
	v_mfma_f32_16x16x32_bf16 v[116:119], v[212:215], v[178:181], v[116:119]
	v_mfma_f32_16x16x32_bf16 v[112:115], v[212:215], v[186:189], v[112:115]
	v_mfma_f32_16x16x32_bf16 v[108:111], v[220:223], v[178:181], v[108:111]
	v_mfma_f32_16x16x32_bf16 v[104:107], v[220:223], v[186:189], v[104:107]
	v_mfma_f32_16x16x32_bf16 v[100:103], v[228:231], v[178:181], v[100:103]
	v_mfma_f32_16x16x32_bf16 v[96:99], v[228:231], v[186:189], v[96:99]
	s_barrier
	s_add_i32 m0, s100, 0x17f80
	ds_read_b128 v[232:235], v148
	ds_read_b128 v[236:239], v148 offset:1024
	ds_read_b128 v[240:243], v148 offset:2048
	ds_read_b128 v[244:247], v148 offset:3072
	global_load_lds_dwordx4 v158, s[86:87] offset:128
	s_add_i32 m0, s100, 0x19f80
	s_nop 0
	global_load_lds_dwordx4 v159, s[86:87] offset:128
	s_barrier
	s_waitcnt lgkmcnt(0)
	v_mfma_f32_16x16x32_bf16 v[92:95], v[190:193], v[232:235], v[92:95]
	v_mfma_f32_16x16x32_bf16 v[88:91], v[190:193], v[240:243], v[88:91]
	v_mfma_f32_16x16x32_bf16 v[84:87], v[208:211], v[232:235], v[84:87]
	v_mfma_f32_16x16x32_bf16 v[80:83], v[208:211], v[240:243], v[80:83]
	v_mfma_f32_16x16x32_bf16 v[76:79], v[216:219], v[232:235], v[76:79]
	v_mfma_f32_16x16x32_bf16 v[72:75], v[216:219], v[240:243], v[72:75]
	v_mfma_f32_16x16x32_bf16 v[68:71], v[224:227], v[232:235], v[68:71]
	v_mfma_f32_16x16x32_bf16 v[64:67], v[224:227], v[240:243], v[64:67]
	v_mfma_f32_16x16x32_bf16 v[92:95], v[196:199], v[236:239], v[92:95]
	v_mfma_f32_16x16x32_bf16 v[88:91], v[196:199], v[244:247], v[88:91]
	v_mfma_f32_16x16x32_bf16 v[84:87], v[212:215], v[236:239], v[84:87]
	v_mfma_f32_16x16x32_bf16 v[80:83], v[212:215], v[244:247], v[80:83]
	v_mfma_f32_16x16x32_bf16 v[76:79], v[220:223], v[236:239], v[76:79]
	v_mfma_f32_16x16x32_bf16 v[72:75], v[220:223], v[244:247], v[72:75]
	v_mfma_f32_16x16x32_bf16 v[68:71], v[228:231], v[236:239], v[68:71]
	v_mfma_f32_16x16x32_bf16 v[64:67], v[228:231], v[244:247], v[64:67]
	s_add_i32 m0, s100, 0x7f80
	s_barrier
	ds_read_b128 v[190:193], v147 offset:49152
	ds_read_b128 v[196:199], v147 offset:50176
	ds_read_b128 v[208:211], v146 offset:49152
	ds_read_b128 v[212:215], v146 offset:50176
	ds_read_b128 v[216:219], v145 offset:49152
	ds_read_b128 v[220:223], v145 offset:50176
	ds_read_b128 v[224:227], v144 offset:49152
	ds_read_b128 v[228:231], v144 offset:50176
	global_load_lds_dwordx4 v170, s[86:87] offset:128
	s_add_i32 m0, s100, 0x9f80
	s_nop 0
	global_load_lds_dwordx4 v206, s[86:87] offset:128
	s_barrier
	s_waitcnt lgkmcnt(0)
	v_mfma_f32_16x16x32_bf16 v[60:63], v[190:193], v[174:177], v[60:63]
	v_mfma_f32_16x16x32_bf16 v[56:59], v[190:193], v[182:185], v[56:59]
	v_mfma_f32_16x16x32_bf16 v[52:55], v[208:211], v[174:177], v[52:55]
	v_mfma_f32_16x16x32_bf16 v[48:51], v[208:211], v[182:185], v[48:51]
	v_mfma_f32_16x16x32_bf16 v[44:47], v[216:219], v[174:177], v[44:47]
	v_mfma_f32_16x16x32_bf16 v[40:43], v[216:219], v[182:185], v[40:43]
	v_mfma_f32_16x16x32_bf16 v[36:39], v[224:227], v[174:177], v[36:39]
	v_mfma_f32_16x16x32_bf16 v[32:35], v[224:227], v[182:185], v[32:35]
	v_mfma_f32_16x16x32_bf16 v[60:63], v[196:199], v[178:181], v[60:63]
	v_mfma_f32_16x16x32_bf16 v[56:59], v[196:199], v[186:189], v[56:59]
	v_mfma_f32_16x16x32_bf16 v[52:55], v[212:215], v[178:181], v[52:55]
	v_mfma_f32_16x16x32_bf16 v[48:51], v[212:215], v[186:189], v[48:51]
	v_mfma_f32_16x16x32_bf16 v[44:47], v[220:223], v[178:181], v[44:47]
	v_mfma_f32_16x16x32_bf16 v[40:43], v[220:223], v[186:189], v[40:43]
	v_mfma_f32_16x16x32_bf16 v[36:39], v[228:231], v[178:181], v[36:39]
	v_mfma_f32_16x16x32_bf16 v[32:35], v[228:231], v[186:189], v[32:35]
	s_barrier
; #define P8_STAGE(P,BASE,br,kt) do{const bfr* _ub=(BASE)+((long)(br)*K+(long)(kt)*BK); \
;     __builtin_amdgcn_global_load_lds((const unsigned*)(_ub+so0),(unsigned*)((char*)(P)+wid*1024),16,0,0); \
;     __builtin_amdgcn_global_load_lds((const unsigned*)(_ub+so1),(unsigned*)((char*)(P)+wid*1024+8192),16,0,0);}while(0)
; #define P8_LDA(dst,b,h) _Pragma("unroll") for(int m=0;m<4;++m) _Pragma("unroll") for(int k=0;k<2;++k) \
;     dst[m][k]=*reinterpret_cast<const bf16x8*>((char*)P8_SA(b,h)+lds_byte(wr*64+m*16+fr,k*32+fq*8))
; #define P8_LDB(dst,b,h) _Pragma("unroll") for(int n=0;n<2;++n) _Pragma("unroll") for(int k=0;k<2;++k) \
;     dst[n][k]=*reinterpret_cast<const bf16x8*>((char*)P8_SB(b,h)+lds_byte(wc*32+n*16+fr,k*32+fq*8))
; #define P8_MMA(ai,bj,At,Bt) do{__builtin_amdgcn_s_setprio(1); \
;     _Pragma("unroll") for(int m=0;m<4;++m) _Pragma("unroll") for(int n=0;n<2;++n) _Pragma("unroll") for(int k=0;k<2;++k) \
;       acc[ai][bj][m][n]=__builtin_amdgcn_mfma_f32_16x16x32_bf16(At[m][k],Bt[n][k],acc[ai][bj][m][n],0,0,0); \
;     __builtin_amdgcn_s_setprio(0);}while(0)
; #define P8_WAIT_V(n) asm volatile("s_waitcnt vmcnt(" #n ")":::"memory")
; #define P8_WAIT_L(n) asm volatile("s_waitcnt lgkmcnt(" #n ")":::"memory")
; #define P8_BAR __builtin_amdgcn_s_barrier()
; #define P8_SCHED __builtin_amdgcn_sched_barrier(0)
; template <class EPI>
; DEVI void gemm8_tile(const bfr* __restrict__ A, const bfr* __restrict__ Bt, int K, int brow, int bcol, int nbrow, int nbcol, char* shmc, EPI epi) {
;     ...
;     P8_BAR; P8_WAIT_L(0); P8_MMA(1,0,At,B0); P8_BAR; P8_SCHED;
;     P8_STAGE(P8_SB(1,1),Bt,bcol+128,t+3);
;     P8_WAIT_V(6); P8_BAR; P8_MMA(1,1,At,B1); P8_BAR;
;   }
;   { P8_LDB(B0,0,0); P8_LDA(At,0,0); P8_STAGE(P8_SA(1,1),A,brow+128,nt-1);
;     P8_BAR; P8_WAIT_L(0); P8_MMA(0,0,At,B0); P8_BAR;
;     P8_LDB(B1,0,1); P8_BAR; P8_WAIT_L(0); P8_MMA(0,1,At,B1); P8_BAR;
	s_add_i32 m0, s100, 0x1bf80
	s_nop 0
	global_load_lds_dwordx4 v248, s[86:87] offset:128
	s_add_i32 m0, s100, 0x1df80
	s_nop 0
	global_load_lds_dwordx4 v200, s[86:87] offset:128
	s_waitcnt vmcnt(6)
	s_barrier
	v_mfma_f32_16x16x32_bf16 v[28:31], v[190:193], v[232:235], v[28:31]
	v_mfma_f32_16x16x32_bf16 v[24:27], v[190:193], v[240:243], v[24:27]
	v_mfma_f32_16x16x32_bf16 v[20:23], v[208:211], v[232:235], v[20:23]
	v_mfma_f32_16x16x32_bf16 v[16:19], v[208:211], v[240:243], v[16:19]
	v_mfma_f32_16x16x32_bf16 v[12:15], v[216:219], v[232:235], v[12:15]
	v_mfma_f32_16x16x32_bf16 v[8:11], v[216:219], v[240:243], v[8:11]
	v_mfma_f32_16x16x32_bf16 v[4:7], v[224:227], v[232:235], v[4:7]
	v_mfma_f32_16x16x32_bf16 v[0:3], v[224:227], v[240:243], v[0:3]
	v_mfma_f32_16x16x32_bf16 v[28:31], v[196:199], v[236:239], v[28:31]
	v_mfma_f32_16x16x32_bf16 v[24:27], v[196:199], v[244:247], v[24:27]
	v_mfma_f32_16x16x32_bf16 v[20:23], v[212:215], v[236:239], v[20:23]
	v_mfma_f32_16x16x32_bf16 v[16:19], v[212:215], v[244:247], v[16:19]
	v_mfma_f32_16x16x32_bf16 v[12:15], v[220:223], v[236:239], v[12:15]
	v_mfma_f32_16x16x32_bf16 v[8:11], v[220:223], v[244:247], v[8:11]
	v_mfma_f32_16x16x32_bf16 v[4:7], v[228:231], v[236:239], v[4:7]
	v_mfma_f32_16x16x32_bf16 v[0:3], v[228:231], v[244:247], v[0:3]
	s_add_i32 s0, s0, 2
	v_lshl_add_u64 v[134:135], v[134:135], 0, s[80:81]
	v_lshl_add_u64 v[136:137], v[136:137], 0, s[80:81]
	v_lshl_add_u64 v[138:139], v[138:139], 0, s[80:81]
	s_cmp_lt_u32 s0, 28
	v_lshl_add_u64 v[140:141], v[140:141], 0, s[80:81]
	s_barrier
	s_cbranch_scc1 .LBB0_401
	v_add_u32_e32 v171, 0xc000, v143
	v_add_u32_e32 v172, 0xe000, v143
	v_add_u32_e32 v158, 0x10000, v143
	v_add_u32_e32 v159, 0x12000, v143
	v_add_u32_e32 v160, 0x2000, v143
	v_add_u32_e32 v161, 0x14000, v143
	v_add_u32_e32 v162, 0x16000, v143
	v_add_u32_e32 v163, 0x4000, v143
	v_add_u32_e32 v170, 0x6000, v143
	s_or_b32 s0, s34, 0x80
	s_ashr_i32 s1, s0, 31
	s_lshl_b64 s[0:1], s[0:1], 12
	s_add_u32 s0, s31, s0
	s_addc_u32 s1, s64, s1
	ds_read_b128 v[134:137], v157
	ds_read_b128 v[138:141], v157 offset:1024
	ds_read_b128 v[150:153], v157 offset:2048
	ds_read_b128 v[174:177], v157 offset:3072
	ds_read_b128 v[178:181], v147
	ds_read_b128 v[182:185], v147 offset:1024
	ds_read_b128 v[186:189], v146
	ds_read_b128 v[190:193], v146 offset:1024
	ds_read_b128 v[196:199], v145
	ds_read_b128 v[208:211], v145 offset:1024
	ds_read_b128 v[212:215], v144
	ds_read_b128 v[216:219], v144 offset:1024
	v_lshl_add_u64 v[156:157], v[166:167], 1, s[0:1]
	s_mov_b64 s[54:55], 0xf80
	v_lshl_add_u64 v[156:157], v[156:157], 0, s[54:55]
	s_add_i32 m0, s100, 0xc000
	v_lshl_add_u64 v[132:133], v[132:133], 1, s[0:1]
	global_load_lds_dwordx4 v[156:157], off
	v_lshl_add_u64 v[132:133], v[132:133], 0, s[54:55]
	s_add_i32 m0, s100, 0xe000
	s_nop 0
	global_load_lds_dwordx4 v[132:133], off
	s_barrier
	s_waitcnt lgkmcnt(0)
	s_setprio 1
	s_waitcnt lgkmcnt(0)
	v_mfma_f32_16x16x32_bf16 v[124:127], v[178:181], v[134:137], v[124:127]
	v_mfma_f32_16x16x32_bf16 v[116:119], v[186:189], v[134:137], v[116:119]
	v_mfma_f32_16x16x32_bf16 v[112:115], v[186:189], v[150:153], v[112:115]
	v_mfma_f32_16x16x32_bf16 v[100:103], v[212:215], v[134:137], v[100:103]
	v_mfma_f32_16x16x32_bf16 v[124:127], v[182:185], v[138:141], v[124:127]
	v_mfma_f32_16x16x32_bf16 v[120:123], v[178:181], v[150:153], v[120:123]
	v_mfma_f32_16x16x32_bf16 v[116:119], v[190:193], v[138:141], v[116:119]
	v_mfma_f32_16x16x32_bf16 v[112:115], v[190:193], v[174:177], v[112:115]
	v_mfma_f32_16x16x32_bf16 v[108:111], v[196:199], v[134:137], v[108:111]
	v_mfma_f32_16x16x32_bf16 v[104:107], v[196:199], v[150:153], v[104:107]
	v_mfma_f32_16x16x32_bf16 v[100:103], v[216:219], v[138:141], v[100:103]
	v_mfma_f32_16x16x32_bf16 v[96:99], v[212:215], v[150:153], v[96:99]
	v_mfma_f32_16x16x32_bf16 v[220:223], v[182:185], v[174:177], v[120:123]
	v_mfma_f32_16x16x32_bf16 v[224:227], v[208:211], v[138:141], v[108:111]
	v_mfma_f32_16x16x32_bf16 v[228:231], v[208:211], v[174:177], v[104:107]
	v_mfma_f32_16x16x32_bf16 v[232:235], v[216:219], v[174:177], v[96:99]
	s_setprio 0
	s_barrier
	s_nop 1
	ds_read_b128 v[96:99], v155
	ds_read_b128 v[104:107], v155 offset:1024
	ds_read_b128 v[108:111], v155 offset:2048
	ds_read_b128 v[120:123], v155 offset:3072
	s_barrier
	s_waitcnt lgkmcnt(0)
	s_setprio 1
	s_waitcnt lgkmcnt(0)
	v_mfma_f32_16x16x32_bf16 v[92:95], v[178:181], v[96:99], v[92:95]
	v_mfma_f32_16x16x32_bf16 v[84:87], v[186:189], v[96:99], v[84:87]
	v_mfma_f32_16x16x32_bf16 v[80:83], v[186:189], v[108:111], v[80:83]
	v_mfma_f32_16x16x32_bf16 v[68:71], v[212:215], v[96:99], v[68:71]
	v_mfma_f32_16x16x32_bf16 v[92:95], v[182:185], v[104:107], v[92:95]
	v_mfma_f32_16x16x32_bf16 v[88:91], v[178:181], v[108:111], v[88:91]
	v_mfma_f32_16x16x32_bf16 v[84:87], v[190:193], v[104:107], v[84:87]
	v_mfma_f32_16x16x32_bf16 v[80:83], v[190:193], v[120:123], v[80:83]
	v_mfma_f32_16x16x32_bf16 v[76:79], v[196:199], v[96:99], v[76:79]
	v_mfma_f32_16x16x32_bf16 v[72:75], v[196:199], v[108:111], v[72:75]
	v_mfma_f32_16x16x32_bf16 v[68:71], v[216:219], v[104:107], v[68:71]
	v_mfma_f32_16x16x32_bf16 v[64:67], v[212:215], v[108:111], v[64:67]
	v_mfma_f32_16x16x32_bf16 v[154:157], v[182:185], v[120:123], v[88:91]
	v_mfma_f32_16x16x32_bf16 v[178:181], v[208:211], v[104:107], v[76:79]
	v_mfma_f32_16x16x32_bf16 v[182:185], v[208:211], v[120:123], v[72:75]
	v_mfma_f32_16x16x32_bf16 v[186:189], v[216:219], v[120:123], v[64:67]
	s_setprio 0
	s_barrier
; #define P8_LDA(dst,b,h) _Pragma("unroll") for(int m=0;m<4;++m) _Pragma("unroll") for(int k=0;k<2;++k) \
;     dst[m][k]=*reinterpret_cast<const bf16x8*>((char*)P8_SA(b,h)+lds_byte(wr*64+m*16+fr,k*32+fq*8))
; #define P8_LDB(dst,b,h) _Pragma("unroll") for(int n=0;n<2;++n) _Pragma("unroll") for(int k=0;k<2;++k) \
;     dst[n][k]=*reinterpret_cast<const bf16x8*>((char*)P8_SB(b,h)+lds_byte(wc*32+n*16+fr,k*32+fq*8))
; #define P8_MMA(ai,bj,At,Bt) do{__builtin_amdgcn_s_setprio(1); \
;     _Pragma("unroll") for(int m=0;m<4;++m) _Pragma("unroll") for(int n=0;n<2;++n) _Pragma("unroll") for(int k=0;k<2;++k) \
;       acc[ai][bj][m][n]=__builtin_amdgcn_mfma_f32_16x16x32_bf16(At[m][k],Bt[n][k],acc[ai][bj][m][n],0,0,0); \
;     __builtin_amdgcn_s_setprio(0);}while(0)
; #define P8_WAIT_V(n) asm volatile("s_waitcnt vmcnt(" #n ")":::"memory")
; #define P8_WAIT_L(n) asm volatile("s_waitcnt lgkmcnt(" #n ")":::"memory")
; #define P8_BAR __builtin_amdgcn_s_barrier()
; template <class EPI>
; DEVI void gemm8_tile(const bfr* __restrict__ A, const bfr* __restrict__ Bt, int K, int brow, int bcol, int nbrow, int nbcol, char* shmc, EPI epi) {
;     ...
;     P8_LDA(At,0,1); P8_WAIT_V(4); P8_BAR; P8_WAIT_L(0); P8_MMA(1,0,At,B0); P8_MMA(1,1,At,B1); P8_BAR; }
;   { P8_LDB(B0,1,0); P8_LDA(At,1,0); P8_WAIT_V(2); P8_BAR; P8_WAIT_L(0); P8_MMA(0,0,At,B0); P8_BAR;
	s_nop 1
	ds_read_b128 v[64:67], v147 offset:16384
	ds_read_b128 v[72:75], v147 offset:17408
	ds_read_b128 v[76:79], v146 offset:16384
	ds_read_b128 v[88:91], v146 offset:17408
	ds_read_b128 v[190:193], v145 offset:16384
	ds_read_b128 v[196:199], v145 offset:17408
	ds_read_b128 v[208:211], v144 offset:16384
	ds_read_b128 v[212:215], v144 offset:17408
	s_waitcnt vmcnt(4)
	s_barrier
	s_waitcnt lgkmcnt(0)
	s_setprio 1
	s_waitcnt lgkmcnt(0)
	v_mfma_f32_16x16x32_bf16 v[60:63], v[64:67], v[134:137], v[60:63]
	v_mfma_f32_16x16x32_bf16 v[52:55], v[76:79], v[134:137], v[52:55]
	v_mfma_f32_16x16x32_bf16 v[48:51], v[76:79], v[150:153], v[48:51]
	v_mfma_f32_16x16x32_bf16 v[36:39], v[208:211], v[134:137], v[36:39]
	v_mfma_f32_16x16x32_bf16 v[60:63], v[72:75], v[138:141], v[60:63]
	v_mfma_f32_16x16x32_bf16 v[56:59], v[64:67], v[150:153], v[56:59]
	v_mfma_f32_16x16x32_bf16 v[52:55], v[88:91], v[138:141], v[52:55]
	v_mfma_f32_16x16x32_bf16 v[48:51], v[88:91], v[174:177], v[48:51]
	v_mfma_f32_16x16x32_bf16 v[44:47], v[190:193], v[134:137], v[44:47]
	v_mfma_f32_16x16x32_bf16 v[40:43], v[190:193], v[150:153], v[40:43]
	v_mfma_f32_16x16x32_bf16 v[36:39], v[212:215], v[138:141], v[36:39]
	v_mfma_f32_16x16x32_bf16 v[32:35], v[208:211], v[150:153], v[32:35]
	v_mfma_f32_16x16x32_bf16 v[216:219], v[72:75], v[174:177], v[56:59]
	v_mfma_f32_16x16x32_bf16 v[236:239], v[196:199], v[138:141], v[44:47]
	v_mfma_f32_16x16x32_bf16 v[240:243], v[196:199], v[174:177], v[40:43]
	v_mfma_f32_16x16x32_bf16 v[132:135], v[212:215], v[174:177], v[32:35]
	s_setprio 0
	s_setprio 1
	v_mfma_f32_16x16x32_bf16 v[28:31], v[64:67], v[96:99], v[28:31]
	v_mfma_f32_16x16x32_bf16 v[20:23], v[76:79], v[96:99], v[20:23]
	v_mfma_f32_16x16x32_bf16 v[16:19], v[76:79], v[108:111], v[16:19]
	v_mfma_f32_16x16x32_bf16 v[4:7], v[208:211], v[96:99], v[4:7]
	v_mfma_f32_16x16x32_bf16 v[28:31], v[72:75], v[104:107], v[28:31]
	v_mfma_f32_16x16x32_bf16 v[24:27], v[64:67], v[108:111], v[24:27]
	v_mfma_f32_16x16x32_bf16 v[20:23], v[88:91], v[104:107], v[20:23]
	v_mfma_f32_16x16x32_bf16 v[16:19], v[88:91], v[120:123], v[16:19]
	v_mfma_f32_16x16x32_bf16 v[12:15], v[190:193], v[96:99], v[12:15]
	v_mfma_f32_16x16x32_bf16 v[8:11], v[190:193], v[108:111], v[8:11]
	v_mfma_f32_16x16x32_bf16 v[4:7], v[212:215], v[104:107], v[4:7]
	v_mfma_f32_16x16x32_bf16 v[0:3], v[208:211], v[108:111], v[0:3]
	v_mfma_f32_16x16x32_bf16 v[136:139], v[72:75], v[120:123], v[24:27]
	v_mfma_f32_16x16x32_bf16 v[150:153], v[196:199], v[104:107], v[12:15]
	v_mfma_f32_16x16x32_bf16 v[172:175], v[196:199], v[120:123], v[8:11]
	v_mfma_f32_16x16x32_bf16 v[190:193], v[212:215], v[120:123], v[0:3]
	s_setprio 0
	s_barrier
	s_nop 1
	ds_read_b128 v[0:3], v149
	ds_read_b128 v[8:11], v149 offset:1024
	ds_read_b128 v[12:15], v149 offset:2048
	ds_read_b128 v[24:27], v149 offset:3072
	ds_read_b128 v[32:35], v147 offset:32768
	ds_read_b128 v[40:43], v147 offset:33792
	ds_read_b128 v[44:47], v146 offset:32768
	ds_read_b128 v[56:59], v146 offset:33792
	ds_read_b128 v[64:67], v145 offset:32768
	ds_read_b128 v[196:199], v145 offset:33792
	ds_read_b128 v[208:211], v144 offset:32768
	ds_read_b128 v[212:215], v144 offset:33792
	s_waitcnt vmcnt(2)
	s_barrier
	s_waitcnt lgkmcnt(0)
	s_setprio 1
	s_waitcnt lgkmcnt(0)
	v_mfma_f32_16x16x32_bf16 v[72:75], v[32:35], v[0:3], v[124:127]
	v_mfma_f32_16x16x32_bf16 v[120:123], v[40:43], v[8:11], v[72:75]
	v_mfma_f32_16x16x32_bf16 v[72:75], v[32:35], v[12:15], v[220:223]
	v_mfma_f32_16x16x32_bf16 v[104:107], v[40:43], v[24:27], v[72:75]
	v_mfma_f32_16x16x32_bf16 v[72:75], v[44:47], v[0:3], v[116:119]
	v_mfma_f32_16x16x32_bf16 v[124:127], v[56:59], v[8:11], v[72:75]
	v_mfma_f32_16x16x32_bf16 v[72:75], v[44:47], v[12:15], v[112:115]
	v_mfma_f32_16x16x32_bf16 v[108:111], v[56:59], v[24:27], v[72:75]
	v_mfma_f32_16x16x32_bf16 v[72:75], v[64:67], v[0:3], v[224:227]
	v_mfma_f32_16x16x32_bf16 v[112:115], v[196:199], v[8:11], v[72:75]
	v_mfma_f32_16x16x32_bf16 v[72:75], v[64:67], v[12:15], v[228:231]
	v_mfma_f32_16x16x32_bf16 v[96:99], v[196:199], v[24:27], v[72:75]
	v_mfma_f32_16x16x32_bf16 v[72:75], v[208:211], v[0:3], v[100:103]
	v_mfma_f32_16x16x32_bf16 v[116:119], v[212:215], v[8:11], v[72:75]
	v_mfma_f32_16x16x32_bf16 v[72:75], v[208:211], v[12:15], v[232:235]
	v_mfma_f32_16x16x32_bf16 v[100:103], v[212:215], v[24:27], v[72:75]
	s_setprio 0
	s_barrier
; #define P8_LDA(dst,b,h) _Pragma("unroll") for(int m=0;m<4;++m) _Pragma("unroll") for(int k=0;k<2;++k) \
;     dst[m][k]=*reinterpret_cast<const bf16x8*>((char*)P8_SA(b,h)+lds_byte(wr*64+m*16+fr,k*32+fq*8))
; #define P8_LDB(dst,b,h) _Pragma("unroll") for(int n=0;n<2;++n) _Pragma("unroll") for(int k=0;k<2;++k) \
;     dst[n][k]=*reinterpret_cast<const bf16x8*>((char*)P8_SB(b,h)+lds_byte(wc*32+n*16+fr,k*32+fq*8))
; #define P8_MMA(ai,bj,At,Bt) do{__builtin_amdgcn_s_setprio(1); \
;     _Pragma("unroll") for(int m=0;m<4;++m) _Pragma("unroll") for(int n=0;n<2;++n) _Pragma("unroll") for(int k=0;k<2;++k) \
;       acc[ai][bj][m][n]=__builtin_amdgcn_mfma_f32_16x16x32_bf16(At[m][k],Bt[n][k],acc[ai][bj][m][n],0,0,0); \
;     __builtin_amdgcn_s_setprio(0);}while(0)
; #define P8_WAIT_V(n) asm volatile("s_waitcnt vmcnt(" #n ")":::"memory")
; #define P8_WAIT_L(n) asm volatile("s_waitcnt lgkmcnt(" #n ")":::"memory")
; #define P8_BAR __builtin_amdgcn_s_barrier()
; template <class EPI>
; DEVI void gemm8_tile(const bfr* __restrict__ A, const bfr* __restrict__ Bt, int K, int brow, int bcol, int nbrow, int nbcol, char* shmc, EPI epi) {
;     ...
;     P8_LDB(B1,1,1); P8_WAIT_V(0); P8_BAR; P8_WAIT_L(0); P8_MMA(0,1,At,B1); P8_BAR;
;     P8_LDA(At,1,1); P8_BAR; P8_WAIT_L(0); P8_MMA(1,0,At,B0); P8_MMA(1,1,At,B1); P8_BAR; }
;   if(wr==0)P8_BAR;
	ds_read_b128 v[220:223], v148
	ds_read_b128 v[224:227], v148 offset:1024
	ds_read_b128 v[228:231], v148 offset:2048
	ds_read_b128 v[232:235], v148 offset:3072
	s_waitcnt vmcnt(0)
	s_barrier
	s_waitcnt lgkmcnt(0)
	s_setprio 1
	s_waitcnt lgkmcnt(0)
	v_mfma_f32_16x16x32_bf16 v[72:75], v[32:35], v[220:223], v[92:95]
	v_mfma_f32_16x16x32_bf16 v[32:35], v[32:35], v[228:231], v[154:157]
	v_mfma_f32_16x16x32_bf16 v[88:91], v[40:43], v[224:227], v[72:75]
	v_mfma_f32_16x16x32_bf16 v[72:75], v[40:43], v[232:235], v[32:35]
	v_mfma_f32_16x16x32_bf16 v[32:35], v[44:47], v[220:223], v[84:87]
	v_mfma_f32_16x16x32_bf16 v[92:95], v[56:59], v[224:227], v[32:35]
	v_mfma_f32_16x16x32_bf16 v[32:35], v[44:47], v[228:231], v[80:83]
	v_mfma_f32_16x16x32_bf16 v[76:79], v[56:59], v[232:235], v[32:35]
	v_mfma_f32_16x16x32_bf16 v[32:35], v[64:67], v[220:223], v[178:181]
	v_mfma_f32_16x16x32_bf16 v[80:83], v[196:199], v[224:227], v[32:35]
	v_mfma_f32_16x16x32_bf16 v[32:35], v[64:67], v[228:231], v[182:185]
	v_mfma_f32_16x16x32_bf16 v[64:67], v[196:199], v[232:235], v[32:35]
	v_mfma_f32_16x16x32_bf16 v[32:35], v[208:211], v[220:223], v[68:71]
	v_mfma_f32_16x16x32_bf16 v[84:87], v[212:215], v[224:227], v[32:35]
	v_mfma_f32_16x16x32_bf16 v[32:35], v[208:211], v[228:231], v[186:189]
	v_mfma_f32_16x16x32_bf16 v[68:71], v[212:215], v[232:235], v[32:35]
	s_setprio 0
	s_barrier
	ds_read_b128 v[154:157], v147 offset:49152
	ds_read_b128 v[176:179], v147 offset:50176
	ds_read_b128 v[180:183], v146 offset:49152
	ds_read_b128 v[146:149], v146 offset:50176
	ds_read_b128 v[184:187], v145 offset:49152
	ds_read_b128 v[196:199], v145 offset:50176
	ds_read_b128 v[208:211], v144 offset:49152
	ds_read_b128 v[212:215], v144 offset:50176
	s_barrier
	s_waitcnt lgkmcnt(0)
	s_setprio 1
	s_waitcnt lgkmcnt(0)
	v_mfma_f32_16x16x32_bf16 v[32:35], v[154:157], v[0:3], v[60:63]
	v_mfma_f32_16x16x32_bf16 v[56:59], v[176:179], v[8:11], v[32:35]
	v_mfma_f32_16x16x32_bf16 v[32:35], v[154:157], v[12:15], v[216:219]
	v_mfma_f32_16x16x32_bf16 v[40:43], v[176:179], v[24:27], v[32:35]
	v_mfma_f32_16x16x32_bf16 v[32:35], v[180:183], v[0:3], v[52:55]
	v_mfma_f32_16x16x32_bf16 v[60:63], v[146:149], v[8:11], v[32:35]
	v_mfma_f32_16x16x32_bf16 v[32:35], v[180:183], v[12:15], v[48:51]
	v_mfma_f32_16x16x32_bf16 v[44:47], v[146:149], v[24:27], v[32:35]
	v_mfma_f32_16x16x32_bf16 v[32:35], v[184:187], v[0:3], v[236:239]
	v_mfma_f32_16x16x32_bf16 v[0:3], v[208:211], v[0:3], v[36:39]
	v_mfma_f32_16x16x32_bf16 v[48:51], v[196:199], v[8:11], v[32:35]
	v_mfma_f32_16x16x32_bf16 v[32:35], v[184:187], v[12:15], v[240:243]
	v_mfma_f32_16x16x32_bf16 v[52:55], v[212:215], v[8:11], v[0:3]
	v_mfma_f32_16x16x32_bf16 v[0:3], v[208:211], v[12:15], v[132:135]
	v_mfma_f32_16x16x32_bf16 v[32:35], v[196:199], v[24:27], v[32:35]
	v_mfma_f32_16x16x32_bf16 v[36:39], v[212:215], v[24:27], v[0:3]
	s_setprio 0
	s_setprio 1
	v_mfma_f32_16x16x32_bf16 v[0:3], v[154:157], v[220:223], v[28:31]
	v_mfma_f32_16x16x32_bf16 v[24:27], v[176:179], v[224:227], v[0:3]
	v_mfma_f32_16x16x32_bf16 v[0:3], v[154:157], v[228:231], v[136:139]
	v_mfma_f32_16x16x32_bf16 v[8:11], v[176:179], v[232:235], v[0:3]
	v_mfma_f32_16x16x32_bf16 v[0:3], v[180:183], v[220:223], v[20:23]
	v_mfma_f32_16x16x32_bf16 v[28:31], v[146:149], v[224:227], v[0:3]
	v_mfma_f32_16x16x32_bf16 v[0:3], v[180:183], v[228:231], v[16:19]
	v_mfma_f32_16x16x32_bf16 v[12:15], v[146:149], v[232:235], v[0:3]
	v_mfma_f32_16x16x32_bf16 v[0:3], v[184:187], v[220:223], v[150:153]
	v_mfma_f32_16x16x32_bf16 v[4:7], v[208:211], v[220:223], v[4:7]
	v_mfma_f32_16x16x32_bf16 v[16:19], v[196:199], v[224:227], v[0:3]
	v_mfma_f32_16x16x32_bf16 v[0:3], v[184:187], v[228:231], v[172:175]
	v_mfma_f32_16x16x32_bf16 v[20:23], v[212:215], v[224:227], v[4:7]
	v_mfma_f32_16x16x32_bf16 v[4:7], v[208:211], v[228:231], v[190:193]
	v_mfma_f32_16x16x32_bf16 v[0:3], v[196:199], v[232:235], v[0:3]
	v_mfma_f32_16x16x32_bf16 v[4:7], v[212:215], v[232:235], v[4:7]
	s_setprio 0
	v_cmp_gt_u32_e32 vcc, s57, v142
	s_barrier
	s_and_saveexec_b64 s[0:1], vcc
	s_cbranch_execz .LBB0_404
	s_barrier
